# strategy 7.4 step (a) only, other half: K-loop flips kept; waves 4-7 get s_setprio 1 at entry and after every K-loop
# baseline (speedup 1.0000x reference)
; #define PG8_STAGE(bufoff, gbase, voff) do { _Pragma("unroll") for (int _i = 0; _i < 2; ++_i) \
;         __builtin_amdgcn_global_load_lds((const unsigned*)((const char*)(gbase) + (voff)[_i]), (PG8_LAS unsigned*)(lds + (bufoff) + ldsw + _i * 8192), 16, 0, 0); } while (0)
; #define PG8_LDA(dst, b, h) do { _Pragma("unroll") for (int m = 0; m < 4; ++m) _Pragma("unroll") for (int k = 0; k < 2; ++k) dst[m][k] = *(const PG8_LAS bf16x8*)(lds + PG8_SA(b, h) + aoff + m * 2048 + k * 1024); } while (0)
; #define PG8_LDB(dst, b, h) do { _Pragma("unroll") for (int n = 0; n < 2; ++n) _Pragma("unroll") for (int k = 0; k < 2; ++k) dst[n][k] = *(const PG8_LAS bf16x8*)(lds + PG8_SB(b, h) + boff + n * 2048 + k * 1024); } while (0)
; #define PG8_MMA(ai, bj, At, Bt) do { __builtin_amdgcn_s_setprio(1); _Pragma("unroll") for (int m = 0; m < 4; ++m) _Pragma("unroll") for (int n = 0; n < 2; ++n) _Pragma("unroll") for (int k = 0; k < 2; ++k) \
;         acc[ai][bj][m][n] = __builtin_amdgcn_mfma_f32_16x16x32_bf16(Bt[n][k], At[m][k], acc[ai][bj][m][n], 0, 0, 0); __builtin_amdgcn_s_setprio(0); } while (0)
; #define PG8_WAIT_V(n) asm volatile("s_waitcnt vmcnt(" #n ")" ::: "memory")
; #define PG8_WAIT_L(n) asm volatile("s_waitcnt lgkmcnt(" #n ")" ::: "memory")
; template <class Epi, class Sched, bool ALIGN_EPI = false, bool SP2 = false>
; __device__ __forceinline__ void gemm_phase(PG8_LAS unsigned char* lds, const Gemm g, const Sched& S, const Epi& E) {
;     ...
;             const bool last = (t == nt - 2);
;             const char* a1 = cA + (size_t)(t + 1) * kstep;
;             const char* a2 = last ? nA : cA + (size_t)(t + 2) * kstep; const char* b2 = last ? nB : cB + (size_t)(t + 2) * kstep;
;             const char* a3 = a2 + kstep; const char* b3 = b2 + kstep;
;             if (last && has_next) S.a_ready(nxt);
;             if constexpr (SP2) {
;             PG8_LDB(B0, 0, 0); PG8_LDB(B1, 0, 1); PG8_SCHED; PG8_LDA(At, 0, 0); PG8_STAGE(PG8_SA(1, 1), a1 + hstep, voffA);
;             PG8_WAIT_V(8); PG8_WAIT_L(0); PG8_BAR; PG8_MMA(0, 0, At, B0); PG8_MMA(0, 1, At, B1); PG8_BAR; PG8_SCHED;
;             PG8_LDA(At, 0, 1); PG8_STAGE(PG8_SB(0, 0), b2, voffB); PG8_STAGE(PG8_SB(0, 1), b2 + hstep, voffB); PG8_STAGE(PG8_SA(0, 0), a2, voffA);
;             PG8_WAIT_V(8); PG8_WAIT_L(0); PG8_BAR; PG8_MMA(1, 0, At, B0); PG8_MMA(1, 1, At, B1); PG8_BAR; PG8_SCHED;
.LBB0_289:
	ds_read_b128 v[146:149], v156
	ds_read_b128 v[160:163], v156 offset:1024
	ds_read_b128 v[164:167], v156 offset:2048
	ds_read_b128 v[168:171], v156 offset:3072
	ds_read_b128 v[180:183], v157
	ds_read_b128 v[184:187], v157 offset:1024
	ds_read_b128 v[188:191], v157 offset:2048
	ds_read_b128 v[192:195], v157 offset:3072
	s_add_u32 s24, s22, 0xfff80080
	s_addc_u32 s25, s23, -1
	s_cmp_eq_u32 s50, 28
	s_cselect_b32 s27, s15, s25
	s_cselect_b32 s26, s46, s24
	s_cselect_b32 s25, s13, s49
	s_cselect_b32 s24, s47, s48
	v_lshl_add_u64 v[150:151], s[22:23], 0, v[138:139]
	s_add_i32 m0, s21, 0xc000
	ds_read_b128 v[196:199], v158
	ds_read_b128 v[200:203], v158 offset:1024
	ds_read_b128 v[204:207], v158 offset:2048
	ds_read_b128 v[208:211], v158 offset:3072
	ds_read_b128 v[212:215], v158 offset:4096
	ds_read_b128 v[216:219], v158 offset:5120
	ds_read_b128 v[220:223], v158 offset:6144
	ds_read_b128 v[224:227], v158 offset:7168
	global_load_lds_dwordx4 v[150:151], off
	v_lshl_add_u64 v[150:151], s[22:23], 0, v[140:141]
	s_add_i32 m0, s21, 0xe000
	s_nop 0
	global_load_lds_dwordx4 v[150:151], off
	s_waitcnt vmcnt(8)
	s_waitcnt lgkmcnt(0)
	s_barrier
	s_setprio 1
	s_waitcnt lgkmcnt(0)
	v_mfma_f32_16x16x32_bf16 v[124:127], v[146:149], v[196:199], v[124:127]
	v_mfma_f32_16x16x32_bf16 v[120:123], v[164:167], v[196:199], v[120:123]
	v_mfma_f32_16x16x32_bf16 v[116:119], v[146:149], v[204:207], v[116:119]
	v_mfma_f32_16x16x32_bf16 v[108:111], v[164:167], v[204:207], v[108:111]
	v_mfma_f32_16x16x32_bf16 v[100:103], v[146:149], v[212:215], v[100:103]
	v_mfma_f32_16x16x32_bf16 v[92:95], v[164:167], v[212:215], v[92:95]
	v_mfma_f32_16x16x32_bf16 v[84:87], v[146:149], v[220:223], v[84:87]
	v_mfma_f32_16x16x32_bf16 v[76:79], v[164:167], v[220:223], v[76:79]
	v_mfma_f32_16x16x32_bf16 v[124:127], v[160:163], v[200:203], v[124:127]
	v_mfma_f32_16x16x32_bf16 v[120:123], v[168:171], v[200:203], v[120:123]
	v_mfma_f32_16x16x32_bf16 v[116:119], v[160:163], v[208:211], v[116:119]
	v_mfma_f32_16x16x32_bf16 v[108:111], v[168:171], v[208:211], v[108:111]
	v_mfma_f32_16x16x32_bf16 v[100:103], v[160:163], v[216:219], v[100:103]
	v_mfma_f32_16x16x32_bf16 v[92:95], v[168:171], v[216:219], v[92:95]
	v_mfma_f32_16x16x32_bf16 v[84:87], v[160:163], v[224:227], v[84:87]
	v_mfma_f32_16x16x32_bf16 v[76:79], v[168:171], v[224:227], v[76:79]
	s_setprio 0
	s_setprio 1
	v_mfma_f32_16x16x32_bf16 v[112:115], v[180:183], v[196:199], v[112:115]
	v_mfma_f32_16x16x32_bf16 v[104:107], v[188:191], v[196:199], v[104:107]
	v_mfma_f32_16x16x32_bf16 v[96:99], v[180:183], v[204:207], v[96:99]
	v_mfma_f32_16x16x32_bf16 v[88:91], v[188:191], v[204:207], v[88:91]
	v_mfma_f32_16x16x32_bf16 v[80:83], v[180:183], v[212:215], v[80:83]
	v_mfma_f32_16x16x32_bf16 v[72:75], v[188:191], v[212:215], v[72:75]
	v_mfma_f32_16x16x32_bf16 v[68:71], v[180:183], v[220:223], v[68:71]
	v_mfma_f32_16x16x32_bf16 v[64:67], v[188:191], v[220:223], v[64:67]
	v_mfma_f32_16x16x32_bf16 v[112:115], v[184:187], v[200:203], v[112:115]
	v_mfma_f32_16x16x32_bf16 v[104:107], v[192:195], v[200:203], v[104:107]
	v_mfma_f32_16x16x32_bf16 v[96:99], v[184:187], v[208:211], v[96:99]
	v_mfma_f32_16x16x32_bf16 v[88:91], v[192:195], v[208:211], v[88:91]
	v_mfma_f32_16x16x32_bf16 v[80:83], v[184:187], v[216:219], v[80:83]
	v_mfma_f32_16x16x32_bf16 v[72:75], v[192:195], v[216:219], v[72:75]
	v_mfma_f32_16x16x32_bf16 v[68:71], v[184:187], v[224:227], v[68:71]
	v_mfma_f32_16x16x32_bf16 v[64:67], v[192:195], v[224:227], v[64:67]
	s_setprio 0
	s_barrier
	s_add_i32 s51, s40, s30
	v_lshl_add_u64 v[150:151], s[24:25], 0, v[134:135]
	s_mov_b32 m0, s51
	ds_read_b128 v[196:199], v158 offset:16384
	ds_read_b128 v[200:203], v158 offset:17408
	ds_read_b128 v[204:207], v158 offset:18432
	ds_read_b128 v[208:211], v158 offset:19456
	ds_read_b128 v[212:215], v158 offset:20480
	ds_read_b128 v[216:219], v158 offset:21504
	ds_read_b128 v[220:223], v158 offset:22528
	ds_read_b128 v[224:227], v158 offset:23552
	global_load_lds_dwordx4 v[150:151], off
	s_add_i32 m0, s51, 0x2000
	s_add_u32 s52, s24, 0x80000
	v_lshl_add_u64 v[228:229], s[24:25], 0, v[130:131]
	s_addc_u32 s53, s25, 0
	s_add_i32 s51, s41, s30
	global_load_lds_dwordx4 v[228:229], off
	v_lshl_add_u64 v[230:231], s[52:53], 0, v[134:135]
	s_mov_b32 m0, s51
	v_lshl_add_u64 v[232:233], s[26:27], 0, v[132:133]
	global_load_lds_dwordx4 v[230:231], off
	v_lshl_add_u64 v[230:231], s[52:53], 0, v[130:131]
	s_add_i32 m0, s51, 0x2000
	s_nop 0
	global_load_lds_dwordx4 v[230:231], off
	v_lshl_add_u64 v[230:231], s[26:27], 0, v[136:137]
	s_mov_b32 m0, s21
	s_nop 0
	global_load_lds_dwordx4 v[230:231], off
	s_mov_b32 m0, s33
	s_nop 0
	global_load_lds_dwordx4 v[232:233], off
	s_waitcnt vmcnt(8)
	s_waitcnt lgkmcnt(0)
	s_barrier
; #define PG8_STAGE(bufoff, gbase, voff) do { _Pragma("unroll") for (int _i = 0; _i < 2; ++_i) \
;         __builtin_amdgcn_global_load_lds((const unsigned*)((const char*)(gbase) + (voff)[_i]), (PG8_LAS unsigned*)(lds + (bufoff) + ldsw + _i * 8192), 16, 0, 0); } while (0)
; #define PG8_LDA(dst, b, h) do { _Pragma("unroll") for (int m = 0; m < 4; ++m) _Pragma("unroll") for (int k = 0; k < 2; ++k) dst[m][k] = *(const PG8_LAS bf16x8*)(lds + PG8_SA(b, h) + aoff + m * 2048 + k * 1024); } while (0)
; #define PG8_LDB(dst, b, h) do { _Pragma("unroll") for (int n = 0; n < 2; ++n) _Pragma("unroll") for (int k = 0; k < 2; ++k) dst[n][k] = *(const PG8_LAS bf16x8*)(lds + PG8_SB(b, h) + boff + n * 2048 + k * 1024); } while (0)
; #define PG8_MMA(ai, bj, At, Bt) do { __builtin_amdgcn_s_setprio(1); _Pragma("unroll") for (int m = 0; m < 4; ++m) _Pragma("unroll") for (int n = 0; n < 2; ++n) _Pragma("unroll") for (int k = 0; k < 2; ++k) \
;         acc[ai][bj][m][n] = __builtin_amdgcn_mfma_f32_16x16x32_bf16(Bt[n][k], At[m][k], acc[ai][bj][m][n], 0, 0, 0); __builtin_amdgcn_s_setprio(0); } while (0)
; #define PG8_WAIT_V(n) asm volatile("s_waitcnt vmcnt(" #n ")" ::: "memory")
; #define PG8_WAIT_L(n) asm volatile("s_waitcnt lgkmcnt(" #n ")" ::: "memory")
; #define PG8_BAR __builtin_amdgcn_s_barrier()
; #define PG8_SCHED __builtin_amdgcn_sched_barrier(0)
; template <class Epi, class Sched, bool ALIGN_EPI = false, bool SP2 = false>
; __device__ __forceinline__ void gemm_phase(PG8_LAS unsigned char* lds, const Gemm g, const Sched& S, const Epi& E) {
;     ...
;             PG8_WAIT_V(8); PG8_WAIT_L(0); PG8_BAR; PG8_MMA(1, 0, At, B0); PG8_MMA(1, 1, At, B1); PG8_BAR; PG8_SCHED;
;             PG8_LDB(B0, 1, 0); PG8_LDB(B1, 1, 1); PG8_SCHED; PG8_LDA(At, 1, 0); PG8_STAGE(PG8_SA(0, 1), a2 + hstep, voffA);
;             PG8_WAIT_V(8); PG8_WAIT_L(0); PG8_BAR; PG8_MMA(0, 0, At, B0); PG8_MMA(0, 1, At, B1); PG8_BAR; PG8_SCHED;
	s_setprio 1
	s_waitcnt lgkmcnt(0)
	v_mfma_f32_16x16x32_bf16 v[60:63], v[146:149], v[196:199], v[60:63]
	v_mfma_f32_16x16x32_bf16 v[56:59], v[164:167], v[196:199], v[56:59]
	v_mfma_f32_16x16x32_bf16 v[52:55], v[146:149], v[204:207], v[52:55]
	v_mfma_f32_16x16x32_bf16 v[44:47], v[164:167], v[204:207], v[44:47]
	v_mfma_f32_16x16x32_bf16 v[36:39], v[146:149], v[212:215], v[36:39]
	v_mfma_f32_16x16x32_bf16 v[28:31], v[164:167], v[212:215], v[28:31]
	v_mfma_f32_16x16x32_bf16 v[20:23], v[146:149], v[220:223], v[20:23]
	v_mfma_f32_16x16x32_bf16 v[12:15], v[164:167], v[220:223], v[12:15]
	v_mfma_f32_16x16x32_bf16 v[60:63], v[160:163], v[200:203], v[60:63]
	v_mfma_f32_16x16x32_bf16 v[56:59], v[168:171], v[200:203], v[56:59]
	v_mfma_f32_16x16x32_bf16 v[52:55], v[160:163], v[208:211], v[52:55]
	v_mfma_f32_16x16x32_bf16 v[44:47], v[168:171], v[208:211], v[44:47]
	v_mfma_f32_16x16x32_bf16 v[36:39], v[160:163], v[216:219], v[36:39]
	v_mfma_f32_16x16x32_bf16 v[28:31], v[168:171], v[216:219], v[28:31]
	v_mfma_f32_16x16x32_bf16 v[20:23], v[160:163], v[224:227], v[20:23]
	v_mfma_f32_16x16x32_bf16 v[12:15], v[168:171], v[224:227], v[12:15]
	s_setprio 0
	s_setprio 1
	v_mfma_f32_16x16x32_bf16 v[48:51], v[180:183], v[196:199], v[48:51]
	v_mfma_f32_16x16x32_bf16 v[40:43], v[188:191], v[196:199], v[40:43]
	v_mfma_f32_16x16x32_bf16 v[32:35], v[180:183], v[204:207], v[32:35]
	v_mfma_f32_16x16x32_bf16 v[24:27], v[188:191], v[204:207], v[24:27]
	v_mfma_f32_16x16x32_bf16 v[16:19], v[180:183], v[212:215], v[16:19]
	v_mfma_f32_16x16x32_bf16 v[8:11], v[188:191], v[212:215], v[8:11]
	v_mfma_f32_16x16x32_bf16 v[4:7], v[180:183], v[220:223], v[4:7]
	v_mfma_f32_16x16x32_bf16 v[0:3], v[188:191], v[220:223], v[0:3]
	v_mfma_f32_16x16x32_bf16 v[48:51], v[184:187], v[200:203], v[48:51]
	v_mfma_f32_16x16x32_bf16 v[40:43], v[192:195], v[200:203], v[40:43]
	v_mfma_f32_16x16x32_bf16 v[32:35], v[184:187], v[208:211], v[32:35]
	v_mfma_f32_16x16x32_bf16 v[24:27], v[192:195], v[208:211], v[24:27]
	v_mfma_f32_16x16x32_bf16 v[16:19], v[184:187], v[216:219], v[16:19]
	v_mfma_f32_16x16x32_bf16 v[8:11], v[192:195], v[216:219], v[8:11]
	v_mfma_f32_16x16x32_bf16 v[4:7], v[184:187], v[224:227], v[4:7]
	v_mfma_f32_16x16x32_bf16 v[0:3], v[192:195], v[224:227], v[0:3]
	s_setprio 0
	s_barrier
	s_add_i32 s51, 0, 0x18000
	v_add_u32_e32 v159, s51, v153
	s_add_i32 s52, 0, 0x1c000
	ds_read_b128 v[146:149], v159
	ds_read_b128 v[160:163], v159 offset:1024
	ds_read_b128 v[164:167], v159 offset:2048
	ds_read_b128 v[168:171], v159 offset:3072
	v_add_u32_e32 v159, s52, v153
	ds_read_b128 v[180:183], v159
	ds_read_b128 v[184:187], v159 offset:1024
	ds_read_b128 v[188:191], v159 offset:2048
	ds_read_b128 v[192:195], v159 offset:3072
	s_add_u32 s26, s26, 0x80000
	s_addc_u32 s27, s27, 0
	s_mov_b32 m0, s34
	v_lshl_add_u64 v[234:235], s[26:27], 0, v[136:137]
	ds_read_b128 v[196:199], v158 offset:32768
	ds_read_b128 v[200:203], v158 offset:33792
	ds_read_b128 v[204:207], v158 offset:34816
	ds_read_b128 v[208:211], v158 offset:35840
	ds_read_b128 v[212:215], v158 offset:36864
	ds_read_b128 v[216:219], v158 offset:37888
	ds_read_b128 v[220:223], v158 offset:38912
	ds_read_b128 v[224:227], v158 offset:39936
	global_load_lds_dwordx4 v[234:235], off
	v_lshl_add_u64 v[234:235], s[26:27], 0, v[132:133]
	s_mov_b32 m0, s35
	s_nop 0
	global_load_lds_dwordx4 v[234:235], off
	s_waitcnt vmcnt(8)
	s_waitcnt lgkmcnt(0)
	s_barrier
	s_setprio 1
	s_waitcnt lgkmcnt(0)
	v_mfma_f32_16x16x32_bf16 v[124:127], v[146:149], v[196:199], v[124:127]
	v_mfma_f32_16x16x32_bf16 v[120:123], v[164:167], v[196:199], v[120:123]
	v_mfma_f32_16x16x32_bf16 v[116:119], v[146:149], v[204:207], v[116:119]
	v_mfma_f32_16x16x32_bf16 v[108:111], v[164:167], v[204:207], v[108:111]
	v_mfma_f32_16x16x32_bf16 v[100:103], v[146:149], v[212:215], v[100:103]
	v_mfma_f32_16x16x32_bf16 v[92:95], v[164:167], v[212:215], v[92:95]
	v_mfma_f32_16x16x32_bf16 v[84:87], v[146:149], v[220:223], v[84:87]
	v_mfma_f32_16x16x32_bf16 v[76:79], v[164:167], v[220:223], v[76:79]
	v_mfma_f32_16x16x32_bf16 v[124:127], v[160:163], v[200:203], v[124:127]
	v_mfma_f32_16x16x32_bf16 v[120:123], v[168:171], v[200:203], v[120:123]
	v_mfma_f32_16x16x32_bf16 v[116:119], v[160:163], v[208:211], v[116:119]
	v_mfma_f32_16x16x32_bf16 v[108:111], v[168:171], v[208:211], v[108:111]
	v_mfma_f32_16x16x32_bf16 v[100:103], v[160:163], v[216:219], v[100:103]
	v_mfma_f32_16x16x32_bf16 v[92:95], v[168:171], v[216:219], v[92:95]
	v_mfma_f32_16x16x32_bf16 v[84:87], v[160:163], v[224:227], v[84:87]
	v_mfma_f32_16x16x32_bf16 v[76:79], v[168:171], v[224:227], v[76:79]
	s_setprio 0
	s_setprio 1
	v_mfma_f32_16x16x32_bf16 v[112:115], v[180:183], v[196:199], v[112:115]
	v_mfma_f32_16x16x32_bf16 v[104:107], v[188:191], v[196:199], v[104:107]
	v_mfma_f32_16x16x32_bf16 v[96:99], v[180:183], v[204:207], v[96:99]
	v_mfma_f32_16x16x32_bf16 v[88:91], v[188:191], v[204:207], v[88:91]
	v_mfma_f32_16x16x32_bf16 v[80:83], v[180:183], v[212:215], v[80:83]
	v_mfma_f32_16x16x32_bf16 v[72:75], v[188:191], v[212:215], v[72:75]
	v_mfma_f32_16x16x32_bf16 v[68:71], v[180:183], v[220:223], v[68:71]
	v_mfma_f32_16x16x32_bf16 v[64:67], v[188:191], v[220:223], v[64:67]
	v_mfma_f32_16x16x32_bf16 v[112:115], v[184:187], v[200:203], v[112:115]
	v_mfma_f32_16x16x32_bf16 v[104:107], v[192:195], v[200:203], v[104:107]
	v_mfma_f32_16x16x32_bf16 v[96:99], v[184:187], v[208:211], v[96:99]
	v_mfma_f32_16x16x32_bf16 v[88:91], v[192:195], v[208:211], v[88:91]
	v_mfma_f32_16x16x32_bf16 v[80:83], v[184:187], v[216:219], v[80:83]
	v_mfma_f32_16x16x32_bf16 v[72:75], v[192:195], v[216:219], v[72:75]
	v_mfma_f32_16x16x32_bf16 v[68:71], v[184:187], v[224:227], v[68:71]
	v_mfma_f32_16x16x32_bf16 v[64:67], v[192:195], v[224:227], v[64:67]
	s_setprio 0
	s_barrier
; #define PG8_STAGE(bufoff, gbase, voff) do { _Pragma("unroll") for (int _i = 0; _i < 2; ++_i) \
;         __builtin_amdgcn_global_load_lds((const unsigned*)((const char*)(gbase) + (voff)[_i]), (PG8_LAS unsigned*)(lds + (bufoff) + ldsw + _i * 8192), 16, 0, 0); } while (0)
; #define PG8_LDA(dst, b, h) do { _Pragma("unroll") for (int m = 0; m < 4; ++m) _Pragma("unroll") for (int k = 0; k < 2; ++k) dst[m][k] = *(const PG8_LAS bf16x8*)(lds + PG8_SA(b, h) + aoff + m * 2048 + k * 1024); } while (0)
; #define PG8_LDB(dst, b, h) do { _Pragma("unroll") for (int n = 0; n < 2; ++n) _Pragma("unroll") for (int k = 0; k < 2; ++k) dst[n][k] = *(const PG8_LAS bf16x8*)(lds + PG8_SB(b, h) + boff + n * 2048 + k * 1024); } while (0)
; template <class Epi, class Sched, bool ALIGN_EPI = false, bool SP2 = false>
; __device__ __forceinline__ void gemm_phase(PG8_LAS unsigned char* lds, const Gemm g, const Sched& S, const Epi& E) {
;     ...
;         for (int t = 0; t < nt; t += 2) {
;             const bool last = (t == nt - 2);
;             const char* a1 = cA + (size_t)(t + 1) * kstep;
;             const char* a2 = last ? nA : cA + (size_t)(t + 2) * kstep; const char* b2 = last ? nB : cB + (size_t)(t + 2) * kstep;
;             const char* a3 = a2 + kstep; const char* b3 = b2 + kstep;
;             if (last && has_next) S.a_ready(nxt);
;             if constexpr (SP2) {
;             PG8_LDB(B0, 0, 0); PG8_LDB(B1, 0, 1); PG8_SCHED; PG8_LDA(At, 0, 0); PG8_STAGE(PG8_SA(1, 1), a1 + hstep, voffA);
;             PG8_WAIT_V(8); PG8_WAIT_L(0); PG8_BAR; PG8_MMA(0, 0, At, B0); PG8_MMA(0, 1, At, B1); PG8_BAR; PG8_SCHED;
;             PG8_LDA(At, 0, 1); PG8_STAGE(PG8_SB(0, 0), b2, voffB); PG8_STAGE(PG8_SB(0, 1), b2 + hstep, voffB); PG8_STAGE(PG8_SA(0, 0), a2, voffA);
;             PG8_WAIT_V(8); PG8_WAIT_L(0); PG8_BAR; PG8_MMA(1, 0, At, B0); PG8_MMA(1, 1, At, B1); PG8_BAR; PG8_SCHED;
;             PG8_LDB(B0, 1, 0); PG8_LDB(B1, 1, 1); PG8_SCHED; PG8_LDA(At, 1, 0); PG8_STAGE(PG8_SA(0, 1), a2 + hstep, voffA);
;             PG8_WAIT_V(8); PG8_WAIT_L(0); PG8_BAR; PG8_MMA(0, 0, At, B0); PG8_MMA(0, 1, At, B1); PG8_BAR; PG8_SCHED;
;             PG8_LDA(At, 1, 1); PG8_STAGE(PG8_SB(1, 0), b3, voffB); PG8_STAGE(PG8_SB(1, 1), b3 + hstep, voffB); PG8_STAGE(PG8_SA(1, 0), a3, voffA);
;             PG8_WAIT_V(8); PG8_WAIT_L(0); PG8_BAR; PG8_MMA(1, 0, At, B0); PG8_MMA(1, 1, At, B1); PG8_BAR; PG8_SCHED;
	s_add_i32 s26, s51, s30
	v_lshl_add_u64 v[150:151], v[150:151], 0, s[2:3]
	s_mov_b32 m0, s26
	ds_read_b128 v[196:199], v158 offset:49152
	ds_read_b128 v[200:203], v158 offset:50176
	ds_read_b128 v[204:207], v158 offset:51200
	ds_read_b128 v[208:211], v158 offset:52224
	ds_read_b128 v[212:215], v158 offset:53248
	ds_read_b128 v[216:219], v158 offset:54272
	ds_read_b128 v[220:223], v158 offset:55296
	ds_read_b128 v[224:227], v158 offset:56320
	global_load_lds_dwordx4 v[150:151], off
	s_add_i32 m0, s26, 0x2000
	s_add_u32 s24, s24, 0x80080
	v_lshl_add_u64 v[150:151], v[228:229], 0, s[2:3]
	s_addc_u32 s25, s25, 0
	s_add_i32 s26, s52, s30
	global_load_lds_dwordx4 v[150:151], off
	v_lshl_add_u64 v[150:151], s[24:25], 0, v[134:135]
	s_mov_b32 m0, s26
	s_nop 0
	global_load_lds_dwordx4 v[150:151], off
	v_lshl_add_u64 v[150:151], s[24:25], 0, v[130:131]
	s_add_i32 m0, s26, 0x2000
	s_nop 0
	global_load_lds_dwordx4 v[150:151], off
	v_lshl_add_u64 v[150:151], v[230:231], 0, s[2:3]
	s_mov_b32 m0, s36
	s_nop 0
	global_load_lds_dwordx4 v[150:151], off
	v_lshl_add_u64 v[150:151], v[232:233], 0, s[2:3]
	s_mov_b32 m0, s37
	s_nop 0
	global_load_lds_dwordx4 v[150:151], off
	s_waitcnt vmcnt(8)
	s_waitcnt lgkmcnt(0)
	s_barrier
	s_setprio 1
	s_waitcnt lgkmcnt(0)
	v_mfma_f32_16x16x32_bf16 v[60:63], v[146:149], v[196:199], v[60:63]
	v_mfma_f32_16x16x32_bf16 v[56:59], v[164:167], v[196:199], v[56:59]
	v_mfma_f32_16x16x32_bf16 v[52:55], v[146:149], v[204:207], v[52:55]
	v_mfma_f32_16x16x32_bf16 v[44:47], v[164:167], v[204:207], v[44:47]
	v_mfma_f32_16x16x32_bf16 v[36:39], v[146:149], v[212:215], v[36:39]
	v_mfma_f32_16x16x32_bf16 v[28:31], v[164:167], v[212:215], v[28:31]
	v_mfma_f32_16x16x32_bf16 v[20:23], v[146:149], v[220:223], v[20:23]
	v_mfma_f32_16x16x32_bf16 v[12:15], v[164:167], v[220:223], v[12:15]
	v_mfma_f32_16x16x32_bf16 v[60:63], v[160:163], v[200:203], v[60:63]
	v_mfma_f32_16x16x32_bf16 v[56:59], v[168:171], v[200:203], v[56:59]
	v_mfma_f32_16x16x32_bf16 v[52:55], v[160:163], v[208:211], v[52:55]
	v_mfma_f32_16x16x32_bf16 v[44:47], v[168:171], v[208:211], v[44:47]
	v_mfma_f32_16x16x32_bf16 v[36:39], v[160:163], v[216:219], v[36:39]
	v_mfma_f32_16x16x32_bf16 v[28:31], v[168:171], v[216:219], v[28:31]
	v_mfma_f32_16x16x32_bf16 v[20:23], v[160:163], v[224:227], v[20:23]
	v_mfma_f32_16x16x32_bf16 v[12:15], v[168:171], v[224:227], v[12:15]
	s_setprio 0
	s_setprio 1
	v_mfma_f32_16x16x32_bf16 v[48:51], v[180:183], v[196:199], v[48:51]
	v_mfma_f32_16x16x32_bf16 v[40:43], v[188:191], v[196:199], v[40:43]
	v_mfma_f32_16x16x32_bf16 v[32:35], v[180:183], v[204:207], v[32:35]
	v_mfma_f32_16x16x32_bf16 v[24:27], v[188:191], v[204:207], v[24:27]
	v_mfma_f32_16x16x32_bf16 v[16:19], v[180:183], v[212:215], v[16:19]
	v_mfma_f32_16x16x32_bf16 v[8:11], v[188:191], v[212:215], v[8:11]
	v_mfma_f32_16x16x32_bf16 v[4:7], v[180:183], v[220:223], v[4:7]
	v_mfma_f32_16x16x32_bf16 v[0:3], v[188:191], v[220:223], v[0:3]
	v_mfma_f32_16x16x32_bf16 v[48:51], v[184:187], v[200:203], v[48:51]
	v_mfma_f32_16x16x32_bf16 v[40:43], v[192:195], v[200:203], v[40:43]
	v_mfma_f32_16x16x32_bf16 v[32:35], v[184:187], v[208:211], v[32:35]
	v_mfma_f32_16x16x32_bf16 v[24:27], v[192:195], v[208:211], v[24:27]
	v_mfma_f32_16x16x32_bf16 v[16:19], v[184:187], v[216:219], v[16:19]
	v_mfma_f32_16x16x32_bf16 v[8:11], v[192:195], v[216:219], v[8:11]
	v_mfma_f32_16x16x32_bf16 v[4:7], v[184:187], v[224:227], v[4:7]
	v_mfma_f32_16x16x32_bf16 v[0:3], v[192:195], v[224:227], v[0:3]
	s_setprio 0
	s_barrier
	s_add_i32 s50, s50, 2
	s_add_u32 s22, s22, 0x100
	s_addc_u32 s23, s23, 0
	s_add_u32 s48, s48, 0x100
	s_addc_u32 s49, s49, 0
	s_cmp_gt_u32 s50, 29
	s_cbranch_scc0 .LBB0_289
	s_nop 0
	v_readfirstlane_b32 s15, v172
	s_nop 3
	s_lshr_b32 s15, s15, 6
	s_cmp_ge_u32 s15, 4
	s_cbranch_scc0 .Lprio_k0
	s_setprio 1

; #define PG8_STAGE(bufoff, gbase, voff) do { _Pragma("unroll") for (int _i = 0; _i < 2; ++_i) \
;         __builtin_amdgcn_global_load_lds((const unsigned*)((const char*)(gbase) + (voff)[_i]), (PG8_LAS unsigned*)(lds + (bufoff) + ldsw + _i * 8192), 16, 0, 0); } while (0)
; #define PG8_LDA(dst, b, h) do { _Pragma("unroll") for (int m = 0; m < 4; ++m) _Pragma("unroll") for (int k = 0; k < 2; ++k) dst[m][k] = *(const PG8_LAS bf16x8*)(lds + PG8_SA(b, h) + aoff + m * 2048 + k * 1024); } while (0)
; #define PG8_LDB(dst, b, h) do { _Pragma("unroll") for (int n = 0; n < 2; ++n) _Pragma("unroll") for (int k = 0; k < 2; ++k) dst[n][k] = *(const PG8_LAS bf16x8*)(lds + PG8_SB(b, h) + boff + n * 2048 + k * 1024); } while (0)
; #define PG8_MMA(ai, bj, At, Bt) do { __builtin_amdgcn_s_setprio(1); _Pragma("unroll") for (int m = 0; m < 4; ++m) _Pragma("unroll") for (int n = 0; n < 2; ++n) _Pragma("unroll") for (int k = 0; k < 2; ++k) \
;         acc[ai][bj][m][n] = __builtin_amdgcn_mfma_f32_16x16x32_bf16(Bt[n][k], At[m][k], acc[ai][bj][m][n], 0, 0, 0); __builtin_amdgcn_s_setprio(0); } while (0)
; #define PG8_WAIT_V(n) asm volatile("s_waitcnt vmcnt(" #n ")" ::: "memory")
; #define PG8_WAIT_L(n) asm volatile("s_waitcnt lgkmcnt(" #n ")" ::: "memory")
; template <class Epi, class Sched, bool ALIGN_EPI = false, bool SP2 = false>
; __device__ __forceinline__ void gemm_phase(PG8_LAS unsigned char* lds, const Gemm g, const Sched& S, const Epi& E) {
;     ...
;             const bool last = (t == nt - 2);
;             const char* a1 = cA + (size_t)(t + 1) * kstep;
;             const char* a2 = last ? nA : cA + (size_t)(t + 2) * kstep; const char* b2 = last ? nB : cB + (size_t)(t + 2) * kstep;
;             const char* a3 = a2 + kstep; const char* b3 = b2 + kstep;
;             if (last && has_next) S.a_ready(nxt);
;             if constexpr (SP2) {
;             PG8_LDB(B0, 0, 0); PG8_LDB(B1, 0, 1); PG8_SCHED; PG8_LDA(At, 0, 0); PG8_STAGE(PG8_SA(1, 1), a1 + hstep, voffA);
;             PG8_WAIT_V(8); PG8_WAIT_L(0); PG8_BAR; PG8_MMA(0, 0, At, B0); PG8_MMA(0, 1, At, B1); PG8_BAR; PG8_SCHED;
;             PG8_LDA(At, 0, 1); PG8_STAGE(PG8_SB(0, 0), b2, voffB); PG8_STAGE(PG8_SB(0, 1), b2 + hstep, voffB); PG8_STAGE(PG8_SA(0, 0), a2, voffA);
;             PG8_WAIT_V(8); PG8_WAIT_L(0); PG8_BAR; PG8_MMA(1, 0, At, B0); PG8_MMA(1, 1, At, B1); PG8_BAR; PG8_SCHED;
.LBB0_585:
	ds_read_b128 v[142:145], v149
	ds_read_b128 v[152:155], v149 offset:1024
	ds_read_b128 v[156:159], v149 offset:2048
	ds_read_b128 v[160:163], v149 offset:3072
	ds_read_b128 v[164:167], v150
	ds_read_b128 v[168:171], v150 offset:1024
	ds_read_b128 v[180:183], v150 offset:2048
	ds_read_b128 v[184:187], v150 offset:3072
	s_add_u32 s26, s24, 0xfff80080
	s_addc_u32 s27, s25, -1
	s_cmp_eq_u32 s51, 28
	s_cselect_b32 s29, s17, s27
	s_cselect_b32 s28, s23, s26
	s_cselect_b32 s27, s13, s50
	s_cselect_b32 s26, s48, s49
	v_lshl_add_u64 v[220:221], s[24:25], 0, v[134:135]
	s_add_i32 m0, s34, 0xc000
	ds_read_b128 v[188:191], v151
	ds_read_b128 v[192:195], v151 offset:1024
	ds_read_b128 v[196:199], v151 offset:2048
	ds_read_b128 v[200:203], v151 offset:3072
	ds_read_b128 v[204:207], v151 offset:4096
	ds_read_b128 v[208:211], v151 offset:5120
	ds_read_b128 v[212:215], v151 offset:6144
	ds_read_b128 v[216:219], v151 offset:7168
	global_load_lds_dwordx4 v[220:221], off
	v_lshl_add_u64 v[220:221], s[24:25], 0, v[136:137]
	s_add_i32 m0, s34, 0xe000
	s_nop 0
	global_load_lds_dwordx4 v[220:221], off
	s_waitcnt vmcnt(8)
	s_waitcnt lgkmcnt(0)
	s_barrier
	s_setprio 1
	s_waitcnt lgkmcnt(0)
	v_mfma_f32_16x16x32_bf16 v[124:127], v[142:145], v[188:191], v[124:127]
	v_mfma_f32_16x16x32_bf16 v[120:123], v[156:159], v[188:191], v[120:123]
	v_mfma_f32_16x16x32_bf16 v[108:111], v[142:145], v[196:199], v[108:111]
	v_mfma_f32_16x16x32_bf16 v[104:107], v[156:159], v[196:199], v[104:107]
	v_mfma_f32_16x16x32_bf16 v[92:95], v[142:145], v[204:207], v[92:95]
	v_mfma_f32_16x16x32_bf16 v[88:91], v[156:159], v[204:207], v[88:91]
	v_mfma_f32_16x16x32_bf16 v[76:79], v[142:145], v[212:215], v[76:79]
	v_mfma_f32_16x16x32_bf16 v[72:75], v[156:159], v[212:215], v[72:75]
	v_mfma_f32_16x16x32_bf16 v[124:127], v[152:155], v[192:195], v[124:127]
	v_mfma_f32_16x16x32_bf16 v[120:123], v[160:163], v[192:195], v[120:123]
	v_mfma_f32_16x16x32_bf16 v[108:111], v[152:155], v[200:203], v[108:111]
	v_mfma_f32_16x16x32_bf16 v[104:107], v[160:163], v[200:203], v[104:107]
	v_mfma_f32_16x16x32_bf16 v[92:95], v[152:155], v[208:211], v[92:95]
	v_mfma_f32_16x16x32_bf16 v[88:91], v[160:163], v[208:211], v[88:91]
	v_mfma_f32_16x16x32_bf16 v[76:79], v[152:155], v[216:219], v[76:79]
	v_mfma_f32_16x16x32_bf16 v[72:75], v[160:163], v[216:219], v[72:75]
	s_setprio 0
	s_setprio 1
	v_mfma_f32_16x16x32_bf16 v[116:119], v[164:167], v[188:191], v[116:119]
	v_mfma_f32_16x16x32_bf16 v[112:115], v[180:183], v[188:191], v[112:115]
	v_mfma_f32_16x16x32_bf16 v[100:103], v[164:167], v[196:199], v[100:103]
	v_mfma_f32_16x16x32_bf16 v[96:99], v[180:183], v[196:199], v[96:99]
	v_mfma_f32_16x16x32_bf16 v[84:87], v[164:167], v[204:207], v[84:87]
	v_mfma_f32_16x16x32_bf16 v[80:83], v[180:183], v[204:207], v[80:83]
	v_mfma_f32_16x16x32_bf16 v[68:71], v[164:167], v[212:215], v[68:71]
	v_mfma_f32_16x16x32_bf16 v[64:67], v[180:183], v[212:215], v[64:67]
	v_mfma_f32_16x16x32_bf16 v[116:119], v[168:171], v[192:195], v[116:119]
	v_mfma_f32_16x16x32_bf16 v[112:115], v[184:187], v[192:195], v[112:115]
	v_mfma_f32_16x16x32_bf16 v[100:103], v[168:171], v[200:203], v[100:103]
	v_mfma_f32_16x16x32_bf16 v[96:99], v[184:187], v[200:203], v[96:99]
	v_mfma_f32_16x16x32_bf16 v[84:87], v[168:171], v[208:211], v[84:87]
	v_mfma_f32_16x16x32_bf16 v[80:83], v[184:187], v[208:211], v[80:83]
	v_mfma_f32_16x16x32_bf16 v[68:71], v[168:171], v[216:219], v[68:71]
	v_mfma_f32_16x16x32_bf16 v[64:67], v[184:187], v[216:219], v[64:67]
	s_setprio 0
	s_barrier
	s_add_i32 s52, s45, s33
	v_lshl_add_u64 v[220:221], s[26:27], 0, v[130:131]
	s_mov_b32 m0, s52
	ds_read_b128 v[188:191], v151 offset:16384
	ds_read_b128 v[192:195], v151 offset:17408
	ds_read_b128 v[196:199], v151 offset:18432
	ds_read_b128 v[200:203], v151 offset:19456
	ds_read_b128 v[204:207], v151 offset:20480
	ds_read_b128 v[208:211], v151 offset:21504
	ds_read_b128 v[212:215], v151 offset:22528
	ds_read_b128 v[216:219], v151 offset:23552
	global_load_lds_dwordx4 v[220:221], off
	s_add_i32 m0, s52, 0x2000
	s_add_u32 s52, s26, 0x80000
	v_lshl_add_u64 v[222:223], s[26:27], 0, v[132:133]
	s_addc_u32 s53, s27, 0
	s_add_i32 s54, s46, s33
	global_load_lds_dwordx4 v[222:223], off
	v_lshl_add_u64 v[224:225], s[52:53], 0, v[130:131]
	s_mov_b32 m0, s54
	v_lshl_add_u64 v[226:227], s[28:29], 0, v[132:133]
	global_load_lds_dwordx4 v[224:225], off
	v_lshl_add_u64 v[224:225], s[52:53], 0, v[132:133]
	s_add_i32 m0, s54, 0x2000
	s_nop 0
	global_load_lds_dwordx4 v[224:225], off
	v_lshl_add_u64 v[224:225], s[28:29], 0, v[130:131]
	s_mov_b32 m0, s34
	s_nop 0
	global_load_lds_dwordx4 v[224:225], off
	s_mov_b32 m0, s35
	s_nop 0
	global_load_lds_dwordx4 v[226:227], off
	s_waitcnt vmcnt(8)
	s_waitcnt lgkmcnt(0)
	s_barrier
; #define PG8_STAGE(bufoff, gbase, voff) do { _Pragma("unroll") for (int _i = 0; _i < 2; ++_i) \
;         __builtin_amdgcn_global_load_lds((const unsigned*)((const char*)(gbase) + (voff)[_i]), (PG8_LAS unsigned*)(lds + (bufoff) + ldsw + _i * 8192), 16, 0, 0); } while (0)
; #define PG8_LDA(dst, b, h) do { _Pragma("unroll") for (int m = 0; m < 4; ++m) _Pragma("unroll") for (int k = 0; k < 2; ++k) dst[m][k] = *(const PG8_LAS bf16x8*)(lds + PG8_SA(b, h) + aoff + m * 2048 + k * 1024); } while (0)
; #define PG8_LDB(dst, b, h) do { _Pragma("unroll") for (int n = 0; n < 2; ++n) _Pragma("unroll") for (int k = 0; k < 2; ++k) dst[n][k] = *(const PG8_LAS bf16x8*)(lds + PG8_SB(b, h) + boff + n * 2048 + k * 1024); } while (0)
; #define PG8_MMA(ai, bj, At, Bt) do { __builtin_amdgcn_s_setprio(1); _Pragma("unroll") for (int m = 0; m < 4; ++m) _Pragma("unroll") for (int n = 0; n < 2; ++n) _Pragma("unroll") for (int k = 0; k < 2; ++k) \
;         acc[ai][bj][m][n] = __builtin_amdgcn_mfma_f32_16x16x32_bf16(Bt[n][k], At[m][k], acc[ai][bj][m][n], 0, 0, 0); __builtin_amdgcn_s_setprio(0); } while (0)
; #define PG8_WAIT_V(n) asm volatile("s_waitcnt vmcnt(" #n ")" ::: "memory")
; #define PG8_WAIT_L(n) asm volatile("s_waitcnt lgkmcnt(" #n ")" ::: "memory")
; #define PG8_BAR __builtin_amdgcn_s_barrier()
; #define PG8_SCHED __builtin_amdgcn_sched_barrier(0)
; template <class Epi, class Sched, bool ALIGN_EPI = false, bool SP2 = false>
; __device__ __forceinline__ void gemm_phase(PG8_LAS unsigned char* lds, const Gemm g, const Sched& S, const Epi& E) {
;     ...
;             PG8_WAIT_V(8); PG8_WAIT_L(0); PG8_BAR; PG8_MMA(1, 0, At, B0); PG8_MMA(1, 1, At, B1); PG8_BAR; PG8_SCHED;
;             PG8_LDB(B0, 1, 0); PG8_LDB(B1, 1, 1); PG8_SCHED; PG8_LDA(At, 1, 0); PG8_STAGE(PG8_SA(0, 1), a2 + hstep, voffA);
;             PG8_WAIT_V(8); PG8_WAIT_L(0); PG8_BAR; PG8_MMA(0, 0, At, B0); PG8_MMA(0, 1, At, B1); PG8_BAR; PG8_SCHED;
	s_setprio 1
	s_waitcnt lgkmcnt(0)
	v_mfma_f32_16x16x32_bf16 v[60:63], v[142:145], v[188:191], v[60:63]
	v_mfma_f32_16x16x32_bf16 v[56:59], v[156:159], v[188:191], v[56:59]
	v_mfma_f32_16x16x32_bf16 v[44:47], v[142:145], v[196:199], v[44:47]
	v_mfma_f32_16x16x32_bf16 v[40:43], v[156:159], v[196:199], v[40:43]
	v_mfma_f32_16x16x32_bf16 v[28:31], v[142:145], v[204:207], v[28:31]
	v_mfma_f32_16x16x32_bf16 v[24:27], v[156:159], v[204:207], v[24:27]
	v_mfma_f32_16x16x32_bf16 v[12:15], v[142:145], v[212:215], v[12:15]
	v_mfma_f32_16x16x32_bf16 v[8:11], v[156:159], v[212:215], v[8:11]
	v_mfma_f32_16x16x32_bf16 v[60:63], v[152:155], v[192:195], v[60:63]
	v_mfma_f32_16x16x32_bf16 v[56:59], v[160:163], v[192:195], v[56:59]
	v_mfma_f32_16x16x32_bf16 v[44:47], v[152:155], v[200:203], v[44:47]
	v_mfma_f32_16x16x32_bf16 v[40:43], v[160:163], v[200:203], v[40:43]
	v_mfma_f32_16x16x32_bf16 v[28:31], v[152:155], v[208:211], v[28:31]
	v_mfma_f32_16x16x32_bf16 v[24:27], v[160:163], v[208:211], v[24:27]
	v_mfma_f32_16x16x32_bf16 v[12:15], v[152:155], v[216:219], v[12:15]
	v_mfma_f32_16x16x32_bf16 v[8:11], v[160:163], v[216:219], v[8:11]
	s_setprio 0
	s_setprio 1
	v_mfma_f32_16x16x32_bf16 v[52:55], v[164:167], v[188:191], v[52:55]
	v_mfma_f32_16x16x32_bf16 v[48:51], v[180:183], v[188:191], v[48:51]
	v_mfma_f32_16x16x32_bf16 v[36:39], v[164:167], v[196:199], v[36:39]
	v_mfma_f32_16x16x32_bf16 v[32:35], v[180:183], v[196:199], v[32:35]
	v_mfma_f32_16x16x32_bf16 v[20:23], v[164:167], v[204:207], v[20:23]
	v_mfma_f32_16x16x32_bf16 v[16:19], v[180:183], v[204:207], v[16:19]
	v_mfma_f32_16x16x32_bf16 v[4:7], v[164:167], v[212:215], v[4:7]
	v_mfma_f32_16x16x32_bf16 v[0:3], v[180:183], v[212:215], v[0:3]
	v_mfma_f32_16x16x32_bf16 v[52:55], v[168:171], v[192:195], v[52:55]
	v_mfma_f32_16x16x32_bf16 v[48:51], v[184:187], v[192:195], v[48:51]
	v_mfma_f32_16x16x32_bf16 v[36:39], v[168:171], v[200:203], v[36:39]
	v_mfma_f32_16x16x32_bf16 v[32:35], v[184:187], v[200:203], v[32:35]
	v_mfma_f32_16x16x32_bf16 v[20:23], v[168:171], v[208:211], v[20:23]
	v_mfma_f32_16x16x32_bf16 v[16:19], v[184:187], v[208:211], v[16:19]
	v_mfma_f32_16x16x32_bf16 v[4:7], v[168:171], v[216:219], v[4:7]
	v_mfma_f32_16x16x32_bf16 v[0:3], v[184:187], v[216:219], v[0:3]
	s_setprio 0
	s_barrier
	s_add_i32 s52, 0, 0x18000
	s_add_i32 s53, 0, 0x1c000
	v_add_u32_e32 v160, s52, v147
	v_add_u32_e32 v179, s53, v147
	ds_read_b128 v[142:145], v160
	ds_read_b128 v[152:155], v160 offset:1024
	ds_read_b128 v[156:159], v160 offset:2048
	ds_read_b128 v[160:163], v160 offset:3072
	ds_read_b128 v[164:167], v179
	ds_read_b128 v[168:171], v179 offset:1024
	ds_read_b128 v[180:183], v179 offset:2048
	ds_read_b128 v[184:187], v179 offset:3072
	s_add_u32 s28, s28, 0x80000
	s_addc_u32 s29, s29, 0
	s_mov_b32 m0, s36
	v_lshl_add_u64 v[228:229], s[28:29], 0, v[130:131]
	ds_read_b128 v[188:191], v151 offset:32768
	ds_read_b128 v[192:195], v151 offset:33792
	ds_read_b128 v[196:199], v151 offset:34816
	ds_read_b128 v[200:203], v151 offset:35840
	ds_read_b128 v[204:207], v151 offset:36864
	ds_read_b128 v[208:211], v151 offset:37888
	ds_read_b128 v[212:215], v151 offset:38912
	ds_read_b128 v[216:219], v151 offset:39936
	global_load_lds_dwordx4 v[228:229], off
	v_lshl_add_u64 v[228:229], s[28:29], 0, v[132:133]
	s_mov_b32 m0, s37
	s_nop 0
	global_load_lds_dwordx4 v[228:229], off
	s_waitcnt vmcnt(8)
	s_waitcnt lgkmcnt(0)
	s_barrier
	s_setprio 1
	s_waitcnt lgkmcnt(0)
	v_mfma_f32_16x16x32_bf16 v[124:127], v[142:145], v[188:191], v[124:127]
	v_mfma_f32_16x16x32_bf16 v[120:123], v[156:159], v[188:191], v[120:123]
	v_mfma_f32_16x16x32_bf16 v[108:111], v[142:145], v[196:199], v[108:111]
	v_mfma_f32_16x16x32_bf16 v[104:107], v[156:159], v[196:199], v[104:107]
	v_mfma_f32_16x16x32_bf16 v[92:95], v[142:145], v[204:207], v[92:95]
	v_mfma_f32_16x16x32_bf16 v[88:91], v[156:159], v[204:207], v[88:91]
	v_mfma_f32_16x16x32_bf16 v[76:79], v[142:145], v[212:215], v[76:79]
	v_mfma_f32_16x16x32_bf16 v[72:75], v[156:159], v[212:215], v[72:75]
	v_mfma_f32_16x16x32_bf16 v[124:127], v[152:155], v[192:195], v[124:127]
	v_mfma_f32_16x16x32_bf16 v[120:123], v[160:163], v[192:195], v[120:123]
	v_mfma_f32_16x16x32_bf16 v[108:111], v[152:155], v[200:203], v[108:111]
	v_mfma_f32_16x16x32_bf16 v[104:107], v[160:163], v[200:203], v[104:107]
	v_mfma_f32_16x16x32_bf16 v[92:95], v[152:155], v[208:211], v[92:95]
	v_mfma_f32_16x16x32_bf16 v[88:91], v[160:163], v[208:211], v[88:91]
	v_mfma_f32_16x16x32_bf16 v[76:79], v[152:155], v[216:219], v[76:79]
	v_mfma_f32_16x16x32_bf16 v[72:75], v[160:163], v[216:219], v[72:75]
	s_setprio 0
	s_setprio 1
	v_mfma_f32_16x16x32_bf16 v[116:119], v[164:167], v[188:191], v[116:119]
	v_mfma_f32_16x16x32_bf16 v[112:115], v[180:183], v[188:191], v[112:115]
	v_mfma_f32_16x16x32_bf16 v[100:103], v[164:167], v[196:199], v[100:103]
	v_mfma_f32_16x16x32_bf16 v[96:99], v[180:183], v[196:199], v[96:99]
	v_mfma_f32_16x16x32_bf16 v[84:87], v[164:167], v[204:207], v[84:87]
	v_mfma_f32_16x16x32_bf16 v[80:83], v[180:183], v[204:207], v[80:83]
	v_mfma_f32_16x16x32_bf16 v[68:71], v[164:167], v[212:215], v[68:71]
	v_mfma_f32_16x16x32_bf16 v[64:67], v[180:183], v[212:215], v[64:67]
	v_mfma_f32_16x16x32_bf16 v[116:119], v[168:171], v[192:195], v[116:119]
	v_mfma_f32_16x16x32_bf16 v[112:115], v[184:187], v[192:195], v[112:115]
	v_mfma_f32_16x16x32_bf16 v[100:103], v[168:171], v[200:203], v[100:103]
	v_mfma_f32_16x16x32_bf16 v[96:99], v[184:187], v[200:203], v[96:99]
	v_mfma_f32_16x16x32_bf16 v[84:87], v[168:171], v[208:211], v[84:87]
	v_mfma_f32_16x16x32_bf16 v[80:83], v[184:187], v[208:211], v[80:83]
	v_mfma_f32_16x16x32_bf16 v[68:71], v[168:171], v[216:219], v[68:71]
	v_mfma_f32_16x16x32_bf16 v[64:67], v[184:187], v[216:219], v[64:67]
	s_setprio 0
	s_barrier
; #define PG8_STAGE(bufoff, gbase, voff) do { _Pragma("unroll") for (int _i = 0; _i < 2; ++_i) \
;         __builtin_amdgcn_global_load_lds((const unsigned*)((const char*)(gbase) + (voff)[_i]), (PG8_LAS unsigned*)(lds + (bufoff) + ldsw + _i * 8192), 16, 0, 0); } while (0)
; #define PG8_LDA(dst, b, h) do { _Pragma("unroll") for (int m = 0; m < 4; ++m) _Pragma("unroll") for (int k = 0; k < 2; ++k) dst[m][k] = *(const PG8_LAS bf16x8*)(lds + PG8_SA(b, h) + aoff + m * 2048 + k * 1024); } while (0)
; #define PG8_LDB(dst, b, h) do { _Pragma("unroll") for (int n = 0; n < 2; ++n) _Pragma("unroll") for (int k = 0; k < 2; ++k) dst[n][k] = *(const PG8_LAS bf16x8*)(lds + PG8_SB(b, h) + boff + n * 2048 + k * 1024); } while (0)
; template <class Epi, class Sched, bool ALIGN_EPI = false, bool SP2 = false>
; __device__ __forceinline__ void gemm_phase(PG8_LAS unsigned char* lds, const Gemm g, const Sched& S, const Epi& E) {
;     ...
;         for (int t = 0; t < nt; t += 2) {
;             const bool last = (t == nt - 2);
;             const char* a1 = cA + (size_t)(t + 1) * kstep;
;             const char* a2 = last ? nA : cA + (size_t)(t + 2) * kstep; const char* b2 = last ? nB : cB + (size_t)(t + 2) * kstep;
;             const char* a3 = a2 + kstep; const char* b3 = b2 + kstep;
;             if (last && has_next) S.a_ready(nxt);
;             if constexpr (SP2) {
;             PG8_LDB(B0, 0, 0); PG8_LDB(B1, 0, 1); PG8_SCHED; PG8_LDA(At, 0, 0); PG8_STAGE(PG8_SA(1, 1), a1 + hstep, voffA);
;             PG8_WAIT_V(8); PG8_WAIT_L(0); PG8_BAR; PG8_MMA(0, 0, At, B0); PG8_MMA(0, 1, At, B1); PG8_BAR; PG8_SCHED;
;             PG8_LDA(At, 0, 1); PG8_STAGE(PG8_SB(0, 0), b2, voffB); PG8_STAGE(PG8_SB(0, 1), b2 + hstep, voffB); PG8_STAGE(PG8_SA(0, 0), a2, voffA);
;             PG8_WAIT_V(8); PG8_WAIT_L(0); PG8_BAR; PG8_MMA(1, 0, At, B0); PG8_MMA(1, 1, At, B1); PG8_BAR; PG8_SCHED;
;             PG8_LDB(B0, 1, 0); PG8_LDB(B1, 1, 1); PG8_SCHED; PG8_LDA(At, 1, 0); PG8_STAGE(PG8_SA(0, 1), a2 + hstep, voffA);
;             PG8_WAIT_V(8); PG8_WAIT_L(0); PG8_BAR; PG8_MMA(0, 0, At, B0); PG8_MMA(0, 1, At, B1); PG8_BAR; PG8_SCHED;
;             PG8_LDA(At, 1, 1); PG8_STAGE(PG8_SB(1, 0), b3, voffB); PG8_STAGE(PG8_SB(1, 1), b3 + hstep, voffB); PG8_STAGE(PG8_SA(1, 0), a3, voffA);
;             PG8_WAIT_V(8); PG8_WAIT_L(0); PG8_BAR; PG8_MMA(1, 0, At, B0); PG8_MMA(1, 1, At, B1); PG8_BAR; PG8_SCHED;
	s_add_i32 s28, s52, s33
	v_lshl_add_u64 v[220:221], v[220:221], 0, s[4:5]
	s_mov_b32 m0, s28
	ds_read_b128 v[188:191], v151 offset:49152
	ds_read_b128 v[192:195], v151 offset:50176
	ds_read_b128 v[196:199], v151 offset:51200
	ds_read_b128 v[200:203], v151 offset:52224
	ds_read_b128 v[204:207], v151 offset:53248
	ds_read_b128 v[208:211], v151 offset:54272
	ds_read_b128 v[212:215], v151 offset:55296
	ds_read_b128 v[216:219], v151 offset:56320
	global_load_lds_dwordx4 v[220:221], off
	s_add_i32 m0, s28, 0x2000
	s_add_u32 s26, s26, 0x80080
	v_lshl_add_u64 v[220:221], v[222:223], 0, s[4:5]
	s_addc_u32 s27, s27, 0
	s_add_i32 s28, s53, s33
	global_load_lds_dwordx4 v[220:221], off
	v_lshl_add_u64 v[220:221], s[26:27], 0, v[130:131]
	s_mov_b32 m0, s28
	s_nop 0
	global_load_lds_dwordx4 v[220:221], off
	v_lshl_add_u64 v[220:221], s[26:27], 0, v[132:133]
	s_add_i32 m0, s28, 0x2000
	s_nop 0
	global_load_lds_dwordx4 v[220:221], off
	v_lshl_add_u64 v[220:221], v[224:225], 0, s[4:5]
	s_mov_b32 m0, s41
	s_nop 0
	global_load_lds_dwordx4 v[220:221], off
	v_lshl_add_u64 v[220:221], v[226:227], 0, s[4:5]
	s_mov_b32 m0, s44
	s_nop 0
	global_load_lds_dwordx4 v[220:221], off
	s_waitcnt vmcnt(8)
	s_waitcnt lgkmcnt(0)
	s_barrier
	s_setprio 1
	s_waitcnt lgkmcnt(0)
	v_mfma_f32_16x16x32_bf16 v[60:63], v[142:145], v[188:191], v[60:63]
	v_mfma_f32_16x16x32_bf16 v[56:59], v[156:159], v[188:191], v[56:59]
	v_mfma_f32_16x16x32_bf16 v[44:47], v[142:145], v[196:199], v[44:47]
	v_mfma_f32_16x16x32_bf16 v[40:43], v[156:159], v[196:199], v[40:43]
	v_mfma_f32_16x16x32_bf16 v[28:31], v[142:145], v[204:207], v[28:31]
	v_mfma_f32_16x16x32_bf16 v[24:27], v[156:159], v[204:207], v[24:27]
	v_mfma_f32_16x16x32_bf16 v[12:15], v[142:145], v[212:215], v[12:15]
	v_mfma_f32_16x16x32_bf16 v[8:11], v[156:159], v[212:215], v[8:11]
	v_mfma_f32_16x16x32_bf16 v[60:63], v[152:155], v[192:195], v[60:63]
	v_mfma_f32_16x16x32_bf16 v[56:59], v[160:163], v[192:195], v[56:59]
	v_mfma_f32_16x16x32_bf16 v[44:47], v[152:155], v[200:203], v[44:47]
	v_mfma_f32_16x16x32_bf16 v[40:43], v[160:163], v[200:203], v[40:43]
	v_mfma_f32_16x16x32_bf16 v[28:31], v[152:155], v[208:211], v[28:31]
	v_mfma_f32_16x16x32_bf16 v[24:27], v[160:163], v[208:211], v[24:27]
	v_mfma_f32_16x16x32_bf16 v[12:15], v[152:155], v[216:219], v[12:15]
	v_mfma_f32_16x16x32_bf16 v[8:11], v[160:163], v[216:219], v[8:11]
	s_setprio 0
	s_setprio 1
	v_mfma_f32_16x16x32_bf16 v[52:55], v[164:167], v[188:191], v[52:55]
	v_mfma_f32_16x16x32_bf16 v[48:51], v[180:183], v[188:191], v[48:51]
	v_mfma_f32_16x16x32_bf16 v[36:39], v[164:167], v[196:199], v[36:39]
	v_mfma_f32_16x16x32_bf16 v[32:35], v[180:183], v[196:199], v[32:35]
	v_mfma_f32_16x16x32_bf16 v[20:23], v[164:167], v[204:207], v[20:23]
	v_mfma_f32_16x16x32_bf16 v[16:19], v[180:183], v[204:207], v[16:19]
	v_mfma_f32_16x16x32_bf16 v[4:7], v[164:167], v[212:215], v[4:7]
	v_mfma_f32_16x16x32_bf16 v[0:3], v[180:183], v[212:215], v[0:3]
	v_mfma_f32_16x16x32_bf16 v[52:55], v[168:171], v[192:195], v[52:55]
	v_mfma_f32_16x16x32_bf16 v[48:51], v[184:187], v[192:195], v[48:51]
	v_mfma_f32_16x16x32_bf16 v[36:39], v[168:171], v[200:203], v[36:39]
	v_mfma_f32_16x16x32_bf16 v[32:35], v[184:187], v[200:203], v[32:35]
	v_mfma_f32_16x16x32_bf16 v[20:23], v[168:171], v[208:211], v[20:23]
	v_mfma_f32_16x16x32_bf16 v[16:19], v[184:187], v[208:211], v[16:19]
	v_mfma_f32_16x16x32_bf16 v[4:7], v[168:171], v[216:219], v[4:7]
	v_mfma_f32_16x16x32_bf16 v[0:3], v[184:187], v[216:219], v[0:3]
	s_setprio 0
	s_barrier
	s_add_i32 s51, s51, 2
	s_add_u32 s24, s24, 0x100
	s_addc_u32 s25, s25, 0
	s_add_u32 s49, s49, 0x100
	s_addc_u32 s50, s50, 0
	s_cmp_gt_u32 s51, 29
	s_cbranch_scc0 .LBB0_585
	s_nop 0
	v_readfirstlane_b32 s23, v172
	s_nop 3
	s_lshr_b32 s23, s23, 6
	s_cmp_ge_u32 s23, 4
	s_cbranch_scc0 .Lprio_k1
	s_setprio 1

; #define PG8_STAGE(bufoff, gbase, voff) do { _Pragma("unroll") for (int _i = 0; _i < 2; ++_i) \
;         __builtin_amdgcn_global_load_lds((const unsigned*)((const char*)(gbase) + (voff)[_i]), (PG8_LAS unsigned*)(lds + (bufoff) + ldsw + _i * 8192), 16, 0, 0); } while (0)
; #define PG8_LDA(dst, b, h) do { _Pragma("unroll") for (int m = 0; m < 4; ++m) _Pragma("unroll") for (int k = 0; k < 2; ++k) dst[m][k] = *(const PG8_LAS bf16x8*)(lds + PG8_SA(b, h) + aoff + m * 2048 + k * 1024); } while (0)
; #define PG8_LDB(dst, b, h) do { _Pragma("unroll") for (int n = 0; n < 2; ++n) _Pragma("unroll") for (int k = 0; k < 2; ++k) dst[n][k] = *(const PG8_LAS bf16x8*)(lds + PG8_SB(b, h) + boff + n * 2048 + k * 1024); } while (0)
; #define PG8_MMA(ai, bj, At, Bt) do { __builtin_amdgcn_s_setprio(1); _Pragma("unroll") for (int m = 0; m < 4; ++m) _Pragma("unroll") for (int n = 0; n < 2; ++n) _Pragma("unroll") for (int k = 0; k < 2; ++k) \
;         acc[ai][bj][m][n] = __builtin_amdgcn_mfma_f32_16x16x32_bf16(Bt[n][k], At[m][k], acc[ai][bj][m][n], 0, 0, 0); __builtin_amdgcn_s_setprio(0); } while (0)
; #define PG8_WAIT_V(n) asm volatile("s_waitcnt vmcnt(" #n ")" ::: "memory")
; #define PG8_WAIT_L(n) asm volatile("s_waitcnt lgkmcnt(" #n ")" ::: "memory")
; template <class Epi, class Sched, bool ALIGN_EPI = false, bool SP2 = false>
; __device__ __forceinline__ void gemm_phase(PG8_LAS unsigned char* lds, const Gemm g, const Sched& S, const Epi& E) {
;     ...
;             const bool last = (t == nt - 2);
;             const char* a1 = cA + (size_t)(t + 1) * kstep;
;             const char* a2 = last ? nA : cA + (size_t)(t + 2) * kstep; const char* b2 = last ? nB : cB + (size_t)(t + 2) * kstep;
;             const char* a3 = a2 + kstep; const char* b3 = b2 + kstep;
;             if (last && has_next) S.a_ready(nxt);
;             if constexpr (SP2) {
;             PG8_LDB(B0, 0, 0); PG8_LDB(B1, 0, 1); PG8_SCHED; PG8_LDA(At, 0, 0); PG8_STAGE(PG8_SA(1, 1), a1 + hstep, voffA);
;             PG8_WAIT_V(8); PG8_WAIT_L(0); PG8_BAR; PG8_MMA(0, 0, At, B0); PG8_MMA(0, 1, At, B1); PG8_BAR; PG8_SCHED;
;             PG8_LDA(At, 0, 1); PG8_STAGE(PG8_SB(0, 0), b2, voffB); PG8_STAGE(PG8_SB(0, 1), b2 + hstep, voffB); PG8_STAGE(PG8_SA(0, 0), a2, voffA);
;             PG8_WAIT_V(8); PG8_WAIT_L(0); PG8_BAR; PG8_MMA(1, 0, At, B0); PG8_MMA(1, 1, At, B1); PG8_BAR; PG8_SCHED;
.LBB0_837:
	ds_read_b128 v[146:149], v158
	ds_read_b128 v[150:153], v158 offset:1024
	ds_read_b128 v[162:165], v158 offset:2048
	ds_read_b128 v[166:169], v158 offset:3072
	ds_read_b128 v[180:183], v159
	ds_read_b128 v[184:187], v159 offset:1024
	ds_read_b128 v[188:191], v159 offset:2048
	ds_read_b128 v[192:195], v159 offset:3072
	s_add_u32 s22, s20, 0xfff80080
	s_addc_u32 s23, s21, -1
	s_cmp_eq_u32 s50, 28
	s_cselect_b32 s25, s11, s23
	s_cselect_b32 s24, s46, s22
	s_cselect_b32 s23, s7, s49
	s_cselect_b32 s22, s47, s48
	v_lshl_add_u64 v[170:171], s[20:21], 0, v[138:139]
	s_add_i32 m0, s30, 0xc000
	ds_read_b128 v[196:199], v160
	ds_read_b128 v[200:203], v160 offset:1024
	ds_read_b128 v[204:207], v160 offset:2048
	ds_read_b128 v[208:211], v160 offset:3072
	ds_read_b128 v[212:215], v160 offset:4096
	ds_read_b128 v[216:219], v160 offset:5120
	ds_read_b128 v[220:223], v160 offset:6144
	ds_read_b128 v[224:227], v160 offset:7168
	global_load_lds_dwordx4 v[170:171], off
	v_lshl_add_u64 v[170:171], s[20:21], 0, v[140:141]
	s_add_i32 m0, s30, 0xe000
	s_nop 0
	global_load_lds_dwordx4 v[170:171], off
	s_waitcnt vmcnt(8)
	s_waitcnt lgkmcnt(0)
	s_barrier
	s_setprio 1
	s_waitcnt lgkmcnt(0)
	v_mfma_f32_16x16x32_bf16 v[124:127], v[146:149], v[196:199], v[124:127]
	v_mfma_f32_16x16x32_bf16 v[116:119], v[162:165], v[196:199], v[116:119]
	v_mfma_f32_16x16x32_bf16 v[108:111], v[146:149], v[204:207], v[108:111]
	v_mfma_f32_16x16x32_bf16 v[100:103], v[162:165], v[204:207], v[100:103]
	v_mfma_f32_16x16x32_bf16 v[92:95], v[146:149], v[212:215], v[92:95]
	v_mfma_f32_16x16x32_bf16 v[84:87], v[162:165], v[212:215], v[84:87]
	v_mfma_f32_16x16x32_bf16 v[76:79], v[146:149], v[220:223], v[76:79]
	v_mfma_f32_16x16x32_bf16 v[68:71], v[162:165], v[220:223], v[68:71]
	v_mfma_f32_16x16x32_bf16 v[124:127], v[150:153], v[200:203], v[124:127]
	v_mfma_f32_16x16x32_bf16 v[116:119], v[166:169], v[200:203], v[116:119]
	v_mfma_f32_16x16x32_bf16 v[108:111], v[150:153], v[208:211], v[108:111]
	v_mfma_f32_16x16x32_bf16 v[100:103], v[166:169], v[208:211], v[100:103]
	v_mfma_f32_16x16x32_bf16 v[92:95], v[150:153], v[216:219], v[92:95]
	v_mfma_f32_16x16x32_bf16 v[84:87], v[166:169], v[216:219], v[84:87]
	v_mfma_f32_16x16x32_bf16 v[76:79], v[150:153], v[224:227], v[76:79]
	v_mfma_f32_16x16x32_bf16 v[68:71], v[166:169], v[224:227], v[68:71]
	s_setprio 0
	s_setprio 1
	v_mfma_f32_16x16x32_bf16 v[120:123], v[180:183], v[196:199], v[120:123]
	v_mfma_f32_16x16x32_bf16 v[112:115], v[188:191], v[196:199], v[112:115]
	v_mfma_f32_16x16x32_bf16 v[104:107], v[180:183], v[204:207], v[104:107]
	v_mfma_f32_16x16x32_bf16 v[96:99], v[188:191], v[204:207], v[96:99]
	v_mfma_f32_16x16x32_bf16 v[88:91], v[180:183], v[212:215], v[88:91]
	v_mfma_f32_16x16x32_bf16 v[80:83], v[188:191], v[212:215], v[80:83]
	v_mfma_f32_16x16x32_bf16 v[72:75], v[180:183], v[220:223], v[72:75]
	v_mfma_f32_16x16x32_bf16 v[64:67], v[188:191], v[220:223], v[64:67]
	v_mfma_f32_16x16x32_bf16 v[120:123], v[184:187], v[200:203], v[120:123]
	v_mfma_f32_16x16x32_bf16 v[112:115], v[192:195], v[200:203], v[112:115]
	v_mfma_f32_16x16x32_bf16 v[104:107], v[184:187], v[208:211], v[104:107]
	v_mfma_f32_16x16x32_bf16 v[96:99], v[192:195], v[208:211], v[96:99]
	v_mfma_f32_16x16x32_bf16 v[88:91], v[184:187], v[216:219], v[88:91]
	v_mfma_f32_16x16x32_bf16 v[80:83], v[192:195], v[216:219], v[80:83]
	v_mfma_f32_16x16x32_bf16 v[72:75], v[184:187], v[224:227], v[72:75]
	v_mfma_f32_16x16x32_bf16 v[64:67], v[192:195], v[224:227], v[64:67]
	s_setprio 0
	s_barrier
	s_add_i32 s51, s37, s26
	v_lshl_add_u64 v[170:171], s[22:23], 0, v[134:135]
	s_mov_b32 m0, s51
	ds_read_b128 v[196:199], v160 offset:16384
	ds_read_b128 v[200:203], v160 offset:17408
	ds_read_b128 v[204:207], v160 offset:18432
	ds_read_b128 v[208:211], v160 offset:19456
	ds_read_b128 v[212:215], v160 offset:20480
	ds_read_b128 v[216:219], v160 offset:21504
	ds_read_b128 v[220:223], v160 offset:22528
	ds_read_b128 v[224:227], v160 offset:23552
	global_load_lds_dwordx4 v[170:171], off
	s_add_i32 m0, s51, 0x2000
	s_add_u32 s52, s22, 0x80000
	v_lshl_add_u64 v[228:229], s[22:23], 0, v[130:131]
	s_addc_u32 s53, s23, 0
	s_add_i32 s51, s40, s26
	global_load_lds_dwordx4 v[228:229], off
	v_lshl_add_u64 v[230:231], s[52:53], 0, v[134:135]
	s_mov_b32 m0, s51
	v_lshl_add_u64 v[232:233], s[24:25], 0, v[132:133]
	global_load_lds_dwordx4 v[230:231], off
	v_lshl_add_u64 v[230:231], s[52:53], 0, v[130:131]
	s_add_i32 m0, s51, 0x2000
	s_nop 0
	global_load_lds_dwordx4 v[230:231], off
	v_lshl_add_u64 v[230:231], s[24:25], 0, v[136:137]
	s_mov_b32 m0, s30
	s_nop 0
	global_load_lds_dwordx4 v[230:231], off
	s_mov_b32 m0, s31
	s_nop 0
	global_load_lds_dwordx4 v[232:233], off
	s_waitcnt vmcnt(8)
	s_waitcnt lgkmcnt(0)
	s_barrier
; #define PG8_STAGE(bufoff, gbase, voff) do { _Pragma("unroll") for (int _i = 0; _i < 2; ++_i) \
;         __builtin_amdgcn_global_load_lds((const unsigned*)((const char*)(gbase) + (voff)[_i]), (PG8_LAS unsigned*)(lds + (bufoff) + ldsw + _i * 8192), 16, 0, 0); } while (0)
; #define PG8_LDA(dst, b, h) do { _Pragma("unroll") for (int m = 0; m < 4; ++m) _Pragma("unroll") for (int k = 0; k < 2; ++k) dst[m][k] = *(const PG8_LAS bf16x8*)(lds + PG8_SA(b, h) + aoff + m * 2048 + k * 1024); } while (0)
; #define PG8_LDB(dst, b, h) do { _Pragma("unroll") for (int n = 0; n < 2; ++n) _Pragma("unroll") for (int k = 0; k < 2; ++k) dst[n][k] = *(const PG8_LAS bf16x8*)(lds + PG8_SB(b, h) + boff + n * 2048 + k * 1024); } while (0)
; #define PG8_MMA(ai, bj, At, Bt) do { __builtin_amdgcn_s_setprio(1); _Pragma("unroll") for (int m = 0; m < 4; ++m) _Pragma("unroll") for (int n = 0; n < 2; ++n) _Pragma("unroll") for (int k = 0; k < 2; ++k) \
;         acc[ai][bj][m][n] = __builtin_amdgcn_mfma_f32_16x16x32_bf16(Bt[n][k], At[m][k], acc[ai][bj][m][n], 0, 0, 0); __builtin_amdgcn_s_setprio(0); } while (0)
; #define PG8_WAIT_V(n) asm volatile("s_waitcnt vmcnt(" #n ")" ::: "memory")
; #define PG8_WAIT_L(n) asm volatile("s_waitcnt lgkmcnt(" #n ")" ::: "memory")
; #define PG8_BAR __builtin_amdgcn_s_barrier()
; #define PG8_SCHED __builtin_amdgcn_sched_barrier(0)
; template <class Epi, class Sched, bool ALIGN_EPI = false, bool SP2 = false>
; __device__ __forceinline__ void gemm_phase(PG8_LAS unsigned char* lds, const Gemm g, const Sched& S, const Epi& E) {
;     ...
;             PG8_WAIT_V(8); PG8_WAIT_L(0); PG8_BAR; PG8_MMA(1, 0, At, B0); PG8_MMA(1, 1, At, B1); PG8_BAR; PG8_SCHED;
;             PG8_LDB(B0, 1, 0); PG8_LDB(B1, 1, 1); PG8_SCHED; PG8_LDA(At, 1, 0); PG8_STAGE(PG8_SA(0, 1), a2 + hstep, voffA);
;             PG8_WAIT_V(8); PG8_WAIT_L(0); PG8_BAR; PG8_MMA(0, 0, At, B0); PG8_MMA(0, 1, At, B1); PG8_BAR; PG8_SCHED;
	s_setprio 1
	s_waitcnt lgkmcnt(0)
	v_mfma_f32_16x16x32_bf16 v[60:63], v[146:149], v[196:199], v[60:63]
	v_mfma_f32_16x16x32_bf16 v[52:55], v[162:165], v[196:199], v[52:55]
	v_mfma_f32_16x16x32_bf16 v[44:47], v[146:149], v[204:207], v[44:47]
	v_mfma_f32_16x16x32_bf16 v[36:39], v[162:165], v[204:207], v[36:39]
	v_mfma_f32_16x16x32_bf16 v[28:31], v[146:149], v[212:215], v[28:31]
	v_mfma_f32_16x16x32_bf16 v[20:23], v[162:165], v[212:215], v[20:23]
	v_mfma_f32_16x16x32_bf16 v[12:15], v[146:149], v[220:223], v[12:15]
	v_mfma_f32_16x16x32_bf16 v[4:7], v[162:165], v[220:223], v[4:7]
	v_mfma_f32_16x16x32_bf16 v[60:63], v[150:153], v[200:203], v[60:63]
	v_mfma_f32_16x16x32_bf16 v[52:55], v[166:169], v[200:203], v[52:55]
	v_mfma_f32_16x16x32_bf16 v[44:47], v[150:153], v[208:211], v[44:47]
	v_mfma_f32_16x16x32_bf16 v[36:39], v[166:169], v[208:211], v[36:39]
	v_mfma_f32_16x16x32_bf16 v[28:31], v[150:153], v[216:219], v[28:31]
	v_mfma_f32_16x16x32_bf16 v[20:23], v[166:169], v[216:219], v[20:23]
	v_mfma_f32_16x16x32_bf16 v[12:15], v[150:153], v[224:227], v[12:15]
	v_mfma_f32_16x16x32_bf16 v[4:7], v[166:169], v[224:227], v[4:7]
	s_setprio 0
	s_setprio 1
	v_mfma_f32_16x16x32_bf16 v[56:59], v[180:183], v[196:199], v[56:59]
	v_mfma_f32_16x16x32_bf16 v[48:51], v[188:191], v[196:199], v[48:51]
	v_mfma_f32_16x16x32_bf16 v[40:43], v[180:183], v[204:207], v[40:43]
	v_mfma_f32_16x16x32_bf16 v[32:35], v[188:191], v[204:207], v[32:35]
	v_mfma_f32_16x16x32_bf16 v[24:27], v[180:183], v[212:215], v[24:27]
	v_mfma_f32_16x16x32_bf16 v[16:19], v[188:191], v[212:215], v[16:19]
	v_mfma_f32_16x16x32_bf16 v[8:11], v[180:183], v[220:223], v[8:11]
	v_mfma_f32_16x16x32_bf16 v[0:3], v[188:191], v[220:223], v[0:3]
	v_mfma_f32_16x16x32_bf16 v[56:59], v[184:187], v[200:203], v[56:59]
	v_mfma_f32_16x16x32_bf16 v[48:51], v[192:195], v[200:203], v[48:51]
	v_mfma_f32_16x16x32_bf16 v[40:43], v[184:187], v[208:211], v[40:43]
	v_mfma_f32_16x16x32_bf16 v[32:35], v[192:195], v[208:211], v[32:35]
	v_mfma_f32_16x16x32_bf16 v[24:27], v[184:187], v[216:219], v[24:27]
	v_mfma_f32_16x16x32_bf16 v[16:19], v[192:195], v[216:219], v[16:19]
	v_mfma_f32_16x16x32_bf16 v[8:11], v[184:187], v[224:227], v[8:11]
	v_mfma_f32_16x16x32_bf16 v[0:3], v[192:195], v[224:227], v[0:3]
	s_setprio 0
	s_barrier
	s_add_i32 s51, 0, 0x18000
	v_add_u32_e32 v161, s51, v155
	s_add_i32 s52, 0, 0x1c000
	ds_read_b128 v[146:149], v161
	ds_read_b128 v[150:153], v161 offset:1024
	ds_read_b128 v[162:165], v161 offset:2048
	ds_read_b128 v[166:169], v161 offset:3072
	v_add_u32_e32 v161, s52, v155
	ds_read_b128 v[180:183], v161
	ds_read_b128 v[184:187], v161 offset:1024
	ds_read_b128 v[188:191], v161 offset:2048
	ds_read_b128 v[192:195], v161 offset:3072
	s_add_u32 s24, s24, 0x80000
	s_addc_u32 s25, s25, 0
	s_mov_b32 m0, s33
	v_lshl_add_u64 v[234:235], s[24:25], 0, v[136:137]
	ds_read_b128 v[196:199], v160 offset:32768
	ds_read_b128 v[200:203], v160 offset:33792
	ds_read_b128 v[204:207], v160 offset:34816
	ds_read_b128 v[208:211], v160 offset:35840
	ds_read_b128 v[212:215], v160 offset:36864
	ds_read_b128 v[216:219], v160 offset:37888
	ds_read_b128 v[220:223], v160 offset:38912
	ds_read_b128 v[224:227], v160 offset:39936
	global_load_lds_dwordx4 v[234:235], off
	v_lshl_add_u64 v[234:235], s[24:25], 0, v[132:133]
	s_mov_b32 m0, s34
	s_nop 0
	global_load_lds_dwordx4 v[234:235], off
	s_waitcnt vmcnt(8)
	s_waitcnt lgkmcnt(0)
	s_barrier
	s_setprio 1
	s_waitcnt lgkmcnt(0)
	v_mfma_f32_16x16x32_bf16 v[124:127], v[146:149], v[196:199], v[124:127]
	v_mfma_f32_16x16x32_bf16 v[116:119], v[162:165], v[196:199], v[116:119]
	v_mfma_f32_16x16x32_bf16 v[108:111], v[146:149], v[204:207], v[108:111]
	v_mfma_f32_16x16x32_bf16 v[100:103], v[162:165], v[204:207], v[100:103]
	v_mfma_f32_16x16x32_bf16 v[92:95], v[146:149], v[212:215], v[92:95]
	v_mfma_f32_16x16x32_bf16 v[84:87], v[162:165], v[212:215], v[84:87]
	v_mfma_f32_16x16x32_bf16 v[76:79], v[146:149], v[220:223], v[76:79]
	v_mfma_f32_16x16x32_bf16 v[68:71], v[162:165], v[220:223], v[68:71]
	v_mfma_f32_16x16x32_bf16 v[124:127], v[150:153], v[200:203], v[124:127]
	v_mfma_f32_16x16x32_bf16 v[116:119], v[166:169], v[200:203], v[116:119]
	v_mfma_f32_16x16x32_bf16 v[108:111], v[150:153], v[208:211], v[108:111]
	v_mfma_f32_16x16x32_bf16 v[100:103], v[166:169], v[208:211], v[100:103]
	v_mfma_f32_16x16x32_bf16 v[92:95], v[150:153], v[216:219], v[92:95]
	v_mfma_f32_16x16x32_bf16 v[84:87], v[166:169], v[216:219], v[84:87]
	v_mfma_f32_16x16x32_bf16 v[76:79], v[150:153], v[224:227], v[76:79]
	v_mfma_f32_16x16x32_bf16 v[68:71], v[166:169], v[224:227], v[68:71]
	s_setprio 0
	s_setprio 1
	v_mfma_f32_16x16x32_bf16 v[120:123], v[180:183], v[196:199], v[120:123]
	v_mfma_f32_16x16x32_bf16 v[112:115], v[188:191], v[196:199], v[112:115]
	v_mfma_f32_16x16x32_bf16 v[104:107], v[180:183], v[204:207], v[104:107]
	v_mfma_f32_16x16x32_bf16 v[96:99], v[188:191], v[204:207], v[96:99]
	v_mfma_f32_16x16x32_bf16 v[88:91], v[180:183], v[212:215], v[88:91]
	v_mfma_f32_16x16x32_bf16 v[80:83], v[188:191], v[212:215], v[80:83]
	v_mfma_f32_16x16x32_bf16 v[72:75], v[180:183], v[220:223], v[72:75]
	v_mfma_f32_16x16x32_bf16 v[64:67], v[188:191], v[220:223], v[64:67]
	v_mfma_f32_16x16x32_bf16 v[120:123], v[184:187], v[200:203], v[120:123]
	v_mfma_f32_16x16x32_bf16 v[112:115], v[192:195], v[200:203], v[112:115]
	v_mfma_f32_16x16x32_bf16 v[104:107], v[184:187], v[208:211], v[104:107]
	v_mfma_f32_16x16x32_bf16 v[96:99], v[192:195], v[208:211], v[96:99]
	v_mfma_f32_16x16x32_bf16 v[88:91], v[184:187], v[216:219], v[88:91]
	v_mfma_f32_16x16x32_bf16 v[80:83], v[192:195], v[216:219], v[80:83]
	v_mfma_f32_16x16x32_bf16 v[72:75], v[184:187], v[224:227], v[72:75]
	v_mfma_f32_16x16x32_bf16 v[64:67], v[192:195], v[224:227], v[64:67]
	s_setprio 0
	s_barrier
; #define PG8_STAGE(bufoff, gbase, voff) do { _Pragma("unroll") for (int _i = 0; _i < 2; ++_i) \
;         __builtin_amdgcn_global_load_lds((const unsigned*)((const char*)(gbase) + (voff)[_i]), (PG8_LAS unsigned*)(lds + (bufoff) + ldsw + _i * 8192), 16, 0, 0); } while (0)
; #define PG8_LDA(dst, b, h) do { _Pragma("unroll") for (int m = 0; m < 4; ++m) _Pragma("unroll") for (int k = 0; k < 2; ++k) dst[m][k] = *(const PG8_LAS bf16x8*)(lds + PG8_SA(b, h) + aoff + m * 2048 + k * 1024); } while (0)
; #define PG8_LDB(dst, b, h) do { _Pragma("unroll") for (int n = 0; n < 2; ++n) _Pragma("unroll") for (int k = 0; k < 2; ++k) dst[n][k] = *(const PG8_LAS bf16x8*)(lds + PG8_SB(b, h) + boff + n * 2048 + k * 1024); } while (0)
; template <class Epi, class Sched, bool ALIGN_EPI = false, bool SP2 = false>
; __device__ __forceinline__ void gemm_phase(PG8_LAS unsigned char* lds, const Gemm g, const Sched& S, const Epi& E) {
;     ...
;         for (int t = 0; t < nt; t += 2) {
;             const bool last = (t == nt - 2);
;             const char* a1 = cA + (size_t)(t + 1) * kstep;
;             const char* a2 = last ? nA : cA + (size_t)(t + 2) * kstep; const char* b2 = last ? nB : cB + (size_t)(t + 2) * kstep;
;             const char* a3 = a2 + kstep; const char* b3 = b2 + kstep;
;             if (last && has_next) S.a_ready(nxt);
;             if constexpr (SP2) {
;             PG8_LDB(B0, 0, 0); PG8_LDB(B1, 0, 1); PG8_SCHED; PG8_LDA(At, 0, 0); PG8_STAGE(PG8_SA(1, 1), a1 + hstep, voffA);
;             PG8_WAIT_V(8); PG8_WAIT_L(0); PG8_BAR; PG8_MMA(0, 0, At, B0); PG8_MMA(0, 1, At, B1); PG8_BAR; PG8_SCHED;
;             PG8_LDA(At, 0, 1); PG8_STAGE(PG8_SB(0, 0), b2, voffB); PG8_STAGE(PG8_SB(0, 1), b2 + hstep, voffB); PG8_STAGE(PG8_SA(0, 0), a2, voffA);
;             PG8_WAIT_V(8); PG8_WAIT_L(0); PG8_BAR; PG8_MMA(1, 0, At, B0); PG8_MMA(1, 1, At, B1); PG8_BAR; PG8_SCHED;
;             PG8_LDB(B0, 1, 0); PG8_LDB(B1, 1, 1); PG8_SCHED; PG8_LDA(At, 1, 0); PG8_STAGE(PG8_SA(0, 1), a2 + hstep, voffA);
;             PG8_WAIT_V(8); PG8_WAIT_L(0); PG8_BAR; PG8_MMA(0, 0, At, B0); PG8_MMA(0, 1, At, B1); PG8_BAR; PG8_SCHED;
;             PG8_LDA(At, 1, 1); PG8_STAGE(PG8_SB(1, 0), b3, voffB); PG8_STAGE(PG8_SB(1, 1), b3 + hstep, voffB); PG8_STAGE(PG8_SA(1, 0), a3, voffA);
;             PG8_WAIT_V(8); PG8_WAIT_L(0); PG8_BAR; PG8_MMA(1, 0, At, B0); PG8_MMA(1, 1, At, B1); PG8_BAR; PG8_SCHED;
	s_add_i32 s24, s51, s26
	v_lshl_add_u64 v[170:171], v[170:171], 0, s[2:3]
	s_mov_b32 m0, s24
	ds_read_b128 v[196:199], v160 offset:49152
	ds_read_b128 v[200:203], v160 offset:50176
	ds_read_b128 v[204:207], v160 offset:51200
	ds_read_b128 v[208:211], v160 offset:52224
	ds_read_b128 v[212:215], v160 offset:53248
	ds_read_b128 v[216:219], v160 offset:54272
	ds_read_b128 v[220:223], v160 offset:55296
	ds_read_b128 v[224:227], v160 offset:56320
	global_load_lds_dwordx4 v[170:171], off
	s_add_i32 m0, s24, 0x2000
	s_add_u32 s22, s22, 0x80080
	v_lshl_add_u64 v[170:171], v[228:229], 0, s[2:3]
	s_addc_u32 s23, s23, 0
	s_add_i32 s24, s52, s26
	global_load_lds_dwordx4 v[170:171], off
	v_lshl_add_u64 v[170:171], s[22:23], 0, v[134:135]
	s_mov_b32 m0, s24
	s_nop 0
	global_load_lds_dwordx4 v[170:171], off
	v_lshl_add_u64 v[170:171], s[22:23], 0, v[130:131]
	s_add_i32 m0, s24, 0x2000
	s_nop 0
	global_load_lds_dwordx4 v[170:171], off
	v_lshl_add_u64 v[170:171], v[230:231], 0, s[2:3]
	s_mov_b32 m0, s35
	s_nop 0
	global_load_lds_dwordx4 v[170:171], off
	v_lshl_add_u64 v[170:171], v[232:233], 0, s[2:3]
	s_mov_b32 m0, s36
	s_nop 0
	global_load_lds_dwordx4 v[170:171], off
	s_waitcnt vmcnt(8)
	s_waitcnt lgkmcnt(0)
	s_barrier
	s_setprio 1
	s_waitcnt lgkmcnt(0)
	v_mfma_f32_16x16x32_bf16 v[60:63], v[146:149], v[196:199], v[60:63]
	v_mfma_f32_16x16x32_bf16 v[52:55], v[162:165], v[196:199], v[52:55]
	v_mfma_f32_16x16x32_bf16 v[44:47], v[146:149], v[204:207], v[44:47]
	v_mfma_f32_16x16x32_bf16 v[36:39], v[162:165], v[204:207], v[36:39]
	v_mfma_f32_16x16x32_bf16 v[28:31], v[146:149], v[212:215], v[28:31]
	v_mfma_f32_16x16x32_bf16 v[20:23], v[162:165], v[212:215], v[20:23]
	v_mfma_f32_16x16x32_bf16 v[12:15], v[146:149], v[220:223], v[12:15]
	v_mfma_f32_16x16x32_bf16 v[4:7], v[162:165], v[220:223], v[4:7]
	v_mfma_f32_16x16x32_bf16 v[60:63], v[150:153], v[200:203], v[60:63]
	v_mfma_f32_16x16x32_bf16 v[52:55], v[166:169], v[200:203], v[52:55]
	v_mfma_f32_16x16x32_bf16 v[44:47], v[150:153], v[208:211], v[44:47]
	v_mfma_f32_16x16x32_bf16 v[36:39], v[166:169], v[208:211], v[36:39]
	v_mfma_f32_16x16x32_bf16 v[28:31], v[150:153], v[216:219], v[28:31]
	v_mfma_f32_16x16x32_bf16 v[20:23], v[166:169], v[216:219], v[20:23]
	v_mfma_f32_16x16x32_bf16 v[12:15], v[150:153], v[224:227], v[12:15]
	v_mfma_f32_16x16x32_bf16 v[4:7], v[166:169], v[224:227], v[4:7]
	s_setprio 0
	s_setprio 1
	v_mfma_f32_16x16x32_bf16 v[56:59], v[180:183], v[196:199], v[56:59]
	v_mfma_f32_16x16x32_bf16 v[48:51], v[188:191], v[196:199], v[48:51]
	v_mfma_f32_16x16x32_bf16 v[40:43], v[180:183], v[204:207], v[40:43]
	v_mfma_f32_16x16x32_bf16 v[32:35], v[188:191], v[204:207], v[32:35]
	v_mfma_f32_16x16x32_bf16 v[24:27], v[180:183], v[212:215], v[24:27]
	v_mfma_f32_16x16x32_bf16 v[16:19], v[188:191], v[212:215], v[16:19]
	v_mfma_f32_16x16x32_bf16 v[8:11], v[180:183], v[220:223], v[8:11]
	v_mfma_f32_16x16x32_bf16 v[0:3], v[188:191], v[220:223], v[0:3]
	v_mfma_f32_16x16x32_bf16 v[56:59], v[184:187], v[200:203], v[56:59]
	v_mfma_f32_16x16x32_bf16 v[48:51], v[192:195], v[200:203], v[48:51]
	v_mfma_f32_16x16x32_bf16 v[40:43], v[184:187], v[208:211], v[40:43]
	v_mfma_f32_16x16x32_bf16 v[32:35], v[192:195], v[208:211], v[32:35]
	v_mfma_f32_16x16x32_bf16 v[24:27], v[184:187], v[216:219], v[24:27]
	v_mfma_f32_16x16x32_bf16 v[16:19], v[192:195], v[216:219], v[16:19]
	v_mfma_f32_16x16x32_bf16 v[8:11], v[184:187], v[224:227], v[8:11]
	v_mfma_f32_16x16x32_bf16 v[0:3], v[192:195], v[224:227], v[0:3]
	s_setprio 0
	s_barrier
	s_add_i32 s50, s50, 2
	s_add_u32 s20, s20, 0x100
	s_addc_u32 s21, s21, 0
	s_add_u32 s48, s48, 0x100
	s_addc_u32 s49, s49, 0
	s_cmp_gt_u32 s50, 29
	s_cbranch_scc0 .LBB0_837
	s_nop 0
	v_readfirstlane_b32 s11, v172
	s_nop 3
	s_lshr_b32 s11, s11, 6
	s_cmp_ge_u32 s11, 4
	s_cbranch_scc0 .Lprio_k2
	s_setprio 1

; #define PG8_STAGE(bufoff, gbase, voff) do { _Pragma("unroll") for (int _i = 0; _i < 2; ++_i) \
;         __builtin_amdgcn_global_load_lds((const unsigned*)((const char*)(gbase) + (voff)[_i]), (PG8_LAS unsigned*)(lds + (bufoff) + ldsw + _i * 8192), 16, 0, 0); } while (0)
; #define PG8_LDA(dst, b, h) do { _Pragma("unroll") for (int m = 0; m < 4; ++m) _Pragma("unroll") for (int k = 0; k < 2; ++k) dst[m][k] = *(const PG8_LAS bf16x8*)(lds + PG8_SA(b, h) + aoff + m * 2048 + k * 1024); } while (0)
; #define PG8_LDB(dst, b, h) do { _Pragma("unroll") for (int n = 0; n < 2; ++n) _Pragma("unroll") for (int k = 0; k < 2; ++k) dst[n][k] = *(const PG8_LAS bf16x8*)(lds + PG8_SB(b, h) + boff + n * 2048 + k * 1024); } while (0)
; #define PG8_MMA(ai, bj, At, Bt) do { __builtin_amdgcn_s_setprio(1); _Pragma("unroll") for (int m = 0; m < 4; ++m) _Pragma("unroll") for (int n = 0; n < 2; ++n) _Pragma("unroll") for (int k = 0; k < 2; ++k) \
;         acc[ai][bj][m][n] = __builtin_amdgcn_mfma_f32_16x16x32_bf16(Bt[n][k], At[m][k], acc[ai][bj][m][n], 0, 0, 0); __builtin_amdgcn_s_setprio(0); } while (0)
; #define PG8_WAIT_V(n) asm volatile("s_waitcnt vmcnt(" #n ")" ::: "memory")
; #define PG8_WAIT_L(n) asm volatile("s_waitcnt lgkmcnt(" #n ")" ::: "memory")
; template <class Epi, class Sched, bool ALIGN_EPI = false, bool SP2 = false>
; __device__ __forceinline__ void gemm_phase(PG8_LAS unsigned char* lds, const Gemm g, const Sched& S, const Epi& E) {
;     ...
;             const bool last = (t == nt - 2);
;             const char* a1 = cA + (size_t)(t + 1) * kstep;
;             const char* a2 = last ? nA : cA + (size_t)(t + 2) * kstep; const char* b2 = last ? nB : cB + (size_t)(t + 2) * kstep;
;             const char* a3 = a2 + kstep; const char* b3 = b2 + kstep;
;             if (last && has_next) S.a_ready(nxt);
;             if constexpr (SP2) {
;             PG8_LDB(B0, 0, 0); PG8_LDB(B1, 0, 1); PG8_SCHED; PG8_LDA(At, 0, 0); PG8_STAGE(PG8_SA(1, 1), a1 + hstep, voffA);
;             PG8_WAIT_V(8); PG8_WAIT_L(0); PG8_BAR; PG8_MMA(0, 0, At, B0); PG8_MMA(0, 1, At, B1); PG8_BAR; PG8_SCHED;
;             PG8_LDA(At, 0, 1); PG8_STAGE(PG8_SB(0, 0), b2, voffB); PG8_STAGE(PG8_SB(0, 1), b2 + hstep, voffB); PG8_STAGE(PG8_SA(0, 0), a2, voffA);
;             PG8_WAIT_V(8); PG8_WAIT_L(0); PG8_BAR; PG8_MMA(1, 0, At, B0); PG8_MMA(1, 1, At, B1); PG8_BAR; PG8_SCHED;
.LBB0_1080:
	ds_read_b128 v[142:145], v151
	ds_read_b128 v[154:157], v151 offset:1024
	ds_read_b128 v[158:161], v151 offset:2048
	ds_read_b128 v[162:165], v151 offset:3072
	ds_read_b128 v[166:169], v152
	ds_read_b128 v[180:183], v152 offset:1024
	ds_read_b128 v[184:187], v152 offset:2048
	ds_read_b128 v[188:191], v152 offset:3072
	s_add_u32 s20, s18, 0x100
	s_addc_u32 s21, s19, 0
	s_cmpk_eq_i32 s49, 0x54
	s_cselect_b32 s25, s13, s21
	s_cselect_b32 s24, s12, s20
	s_cselect_b32 s23, s17, s48
	s_cselect_b32 s22, s16, s47
	v_lshl_add_u64 v[146:147], s[18:19], 0, v[134:135]
	s_add_i32 m0, s29, 0xc000
	ds_read_b128 v[192:195], v153
	ds_read_b128 v[196:199], v153 offset:1024
	ds_read_b128 v[200:203], v153 offset:2048
	ds_read_b128 v[204:207], v153 offset:3072
	ds_read_b128 v[208:211], v153 offset:4096
	ds_read_b128 v[212:215], v153 offset:5120
	ds_read_b128 v[216:219], v153 offset:6144
	ds_read_b128 v[220:223], v153 offset:7168
	global_load_lds_dwordx4 v[146:147], off
	v_lshl_add_u64 v[146:147], s[18:19], 0, v[136:137]
	s_add_i32 m0, s29, 0xe000
	s_nop 0
	global_load_lds_dwordx4 v[146:147], off
	s_waitcnt vmcnt(8)
	s_waitcnt lgkmcnt(0)
	s_barrier
	s_setprio 1
	s_waitcnt lgkmcnt(0)
	v_mfma_f32_16x16x32_bf16 v[124:127], v[142:145], v[192:195], v[124:127]
	v_mfma_f32_16x16x32_bf16 v[120:123], v[158:161], v[192:195], v[120:123]
	v_mfma_f32_16x16x32_bf16 v[108:111], v[142:145], v[200:203], v[108:111]
	v_mfma_f32_16x16x32_bf16 v[104:107], v[158:161], v[200:203], v[104:107]
	v_mfma_f32_16x16x32_bf16 v[92:95], v[142:145], v[208:211], v[92:95]
	v_mfma_f32_16x16x32_bf16 v[88:91], v[158:161], v[208:211], v[88:91]
	v_mfma_f32_16x16x32_bf16 v[76:79], v[142:145], v[216:219], v[76:79]
	v_mfma_f32_16x16x32_bf16 v[72:75], v[158:161], v[216:219], v[72:75]
	v_mfma_f32_16x16x32_bf16 v[124:127], v[154:157], v[196:199], v[124:127]
	v_mfma_f32_16x16x32_bf16 v[120:123], v[162:165], v[196:199], v[120:123]
	v_mfma_f32_16x16x32_bf16 v[108:111], v[154:157], v[204:207], v[108:111]
	v_mfma_f32_16x16x32_bf16 v[104:107], v[162:165], v[204:207], v[104:107]
	v_mfma_f32_16x16x32_bf16 v[92:95], v[154:157], v[212:215], v[92:95]
	v_mfma_f32_16x16x32_bf16 v[88:91], v[162:165], v[212:215], v[88:91]
	v_mfma_f32_16x16x32_bf16 v[76:79], v[154:157], v[220:223], v[76:79]
	v_mfma_f32_16x16x32_bf16 v[72:75], v[162:165], v[220:223], v[72:75]
	s_setprio 0
	s_setprio 1
	v_mfma_f32_16x16x32_bf16 v[116:119], v[166:169], v[192:195], v[116:119]
	v_mfma_f32_16x16x32_bf16 v[112:115], v[184:187], v[192:195], v[112:115]
	v_mfma_f32_16x16x32_bf16 v[100:103], v[166:169], v[200:203], v[100:103]
	v_mfma_f32_16x16x32_bf16 v[96:99], v[184:187], v[200:203], v[96:99]
	v_mfma_f32_16x16x32_bf16 v[84:87], v[166:169], v[208:211], v[84:87]
	v_mfma_f32_16x16x32_bf16 v[80:83], v[184:187], v[208:211], v[80:83]
	v_mfma_f32_16x16x32_bf16 v[68:71], v[166:169], v[216:219], v[68:71]
	v_mfma_f32_16x16x32_bf16 v[64:67], v[184:187], v[216:219], v[64:67]
	v_mfma_f32_16x16x32_bf16 v[116:119], v[180:183], v[196:199], v[116:119]
	v_mfma_f32_16x16x32_bf16 v[112:115], v[188:191], v[196:199], v[112:115]
	v_mfma_f32_16x16x32_bf16 v[100:103], v[180:183], v[204:207], v[100:103]
	v_mfma_f32_16x16x32_bf16 v[96:99], v[188:191], v[204:207], v[96:99]
	v_mfma_f32_16x16x32_bf16 v[84:87], v[180:183], v[212:215], v[84:87]
	v_mfma_f32_16x16x32_bf16 v[80:83], v[188:191], v[212:215], v[80:83]
	v_mfma_f32_16x16x32_bf16 v[68:71], v[180:183], v[220:223], v[68:71]
	v_mfma_f32_16x16x32_bf16 v[64:67], v[188:191], v[220:223], v[64:67]
	s_setprio 0
	s_barrier
	s_add_i32 s18, s37, s28
	v_lshl_add_u64 v[146:147], s[22:23], 0, v[130:131]
	s_mov_b32 m0, s18
	ds_read_b128 v[192:195], v153 offset:16384
	ds_read_b128 v[196:199], v153 offset:17408
	ds_read_b128 v[200:203], v153 offset:18432
	ds_read_b128 v[204:207], v153 offset:19456
	ds_read_b128 v[208:211], v153 offset:20480
	ds_read_b128 v[212:215], v153 offset:21504
	ds_read_b128 v[216:219], v153 offset:22528
	ds_read_b128 v[220:223], v153 offset:23552
	global_load_lds_dwordx4 v[146:147], off
	s_add_i32 m0, s18, 0x2000
	s_add_u32 s18, s22, 0x160000
	v_lshl_add_u64 v[170:171], s[22:23], 0, v[132:133]
	s_addc_u32 s19, s23, 0
	s_add_i32 s50, s40, s28
	global_load_lds_dwordx4 v[170:171], off
	v_lshl_add_u64 v[224:225], s[18:19], 0, v[130:131]
	s_mov_b32 m0, s50
	v_lshl_add_u64 v[226:227], s[24:25], 0, v[132:133]
	global_load_lds_dwordx4 v[224:225], off
	v_lshl_add_u64 v[224:225], s[18:19], 0, v[132:133]
	s_add_i32 m0, s50, 0x2000
	s_nop 0
	global_load_lds_dwordx4 v[224:225], off
	v_lshl_add_u64 v[224:225], s[24:25], 0, v[130:131]
	s_mov_b32 m0, s29
	s_nop 0
	global_load_lds_dwordx4 v[224:225], off
	s_mov_b32 m0, s30
	s_nop 0
	global_load_lds_dwordx4 v[226:227], off
	s_waitcnt vmcnt(8)
	s_waitcnt lgkmcnt(0)
	s_barrier
; #define PG8_STAGE(bufoff, gbase, voff) do { _Pragma("unroll") for (int _i = 0; _i < 2; ++_i) \
;         __builtin_amdgcn_global_load_lds((const unsigned*)((const char*)(gbase) + (voff)[_i]), (PG8_LAS unsigned*)(lds + (bufoff) + ldsw + _i * 8192), 16, 0, 0); } while (0)
; #define PG8_LDA(dst, b, h) do { _Pragma("unroll") for (int m = 0; m < 4; ++m) _Pragma("unroll") for (int k = 0; k < 2; ++k) dst[m][k] = *(const PG8_LAS bf16x8*)(lds + PG8_SA(b, h) + aoff + m * 2048 + k * 1024); } while (0)
; #define PG8_LDB(dst, b, h) do { _Pragma("unroll") for (int n = 0; n < 2; ++n) _Pragma("unroll") for (int k = 0; k < 2; ++k) dst[n][k] = *(const PG8_LAS bf16x8*)(lds + PG8_SB(b, h) + boff + n * 2048 + k * 1024); } while (0)
; #define PG8_MMA(ai, bj, At, Bt) do { __builtin_amdgcn_s_setprio(1); _Pragma("unroll") for (int m = 0; m < 4; ++m) _Pragma("unroll") for (int n = 0; n < 2; ++n) _Pragma("unroll") for (int k = 0; k < 2; ++k) \
;         acc[ai][bj][m][n] = __builtin_amdgcn_mfma_f32_16x16x32_bf16(Bt[n][k], At[m][k], acc[ai][bj][m][n], 0, 0, 0); __builtin_amdgcn_s_setprio(0); } while (0)
; #define PG8_WAIT_V(n) asm volatile("s_waitcnt vmcnt(" #n ")" ::: "memory")
; #define PG8_WAIT_L(n) asm volatile("s_waitcnt lgkmcnt(" #n ")" ::: "memory")
; #define PG8_BAR __builtin_amdgcn_s_barrier()
; #define PG8_SCHED __builtin_amdgcn_sched_barrier(0)
; template <class Epi, class Sched, bool ALIGN_EPI = false, bool SP2 = false>
; __device__ __forceinline__ void gemm_phase(PG8_LAS unsigned char* lds, const Gemm g, const Sched& S, const Epi& E) {
;     ...
;             PG8_WAIT_V(8); PG8_WAIT_L(0); PG8_BAR; PG8_MMA(1, 0, At, B0); PG8_MMA(1, 1, At, B1); PG8_BAR; PG8_SCHED;
;             PG8_LDB(B0, 1, 0); PG8_LDB(B1, 1, 1); PG8_SCHED; PG8_LDA(At, 1, 0); PG8_STAGE(PG8_SA(0, 1), a2 + hstep, voffA);
;             PG8_WAIT_V(8); PG8_WAIT_L(0); PG8_BAR; PG8_MMA(0, 0, At, B0); PG8_MMA(0, 1, At, B1); PG8_BAR; PG8_SCHED;
	s_setprio 1
	s_waitcnt lgkmcnt(0)
	v_mfma_f32_16x16x32_bf16 v[60:63], v[142:145], v[192:195], v[60:63]
	v_mfma_f32_16x16x32_bf16 v[56:59], v[158:161], v[192:195], v[56:59]
	v_mfma_f32_16x16x32_bf16 v[44:47], v[142:145], v[200:203], v[44:47]
	v_mfma_f32_16x16x32_bf16 v[40:43], v[158:161], v[200:203], v[40:43]
	v_mfma_f32_16x16x32_bf16 v[28:31], v[142:145], v[208:211], v[28:31]
	v_mfma_f32_16x16x32_bf16 v[24:27], v[158:161], v[208:211], v[24:27]
	v_mfma_f32_16x16x32_bf16 v[12:15], v[142:145], v[216:219], v[12:15]
	v_mfma_f32_16x16x32_bf16 v[8:11], v[158:161], v[216:219], v[8:11]
	v_mfma_f32_16x16x32_bf16 v[60:63], v[154:157], v[196:199], v[60:63]
	v_mfma_f32_16x16x32_bf16 v[56:59], v[162:165], v[196:199], v[56:59]
	v_mfma_f32_16x16x32_bf16 v[44:47], v[154:157], v[204:207], v[44:47]
	v_mfma_f32_16x16x32_bf16 v[40:43], v[162:165], v[204:207], v[40:43]
	v_mfma_f32_16x16x32_bf16 v[28:31], v[154:157], v[212:215], v[28:31]
	v_mfma_f32_16x16x32_bf16 v[24:27], v[162:165], v[212:215], v[24:27]
	v_mfma_f32_16x16x32_bf16 v[12:15], v[154:157], v[220:223], v[12:15]
	v_mfma_f32_16x16x32_bf16 v[8:11], v[162:165], v[220:223], v[8:11]
	s_setprio 0
	s_setprio 1
	v_mfma_f32_16x16x32_bf16 v[52:55], v[166:169], v[192:195], v[52:55]
	v_mfma_f32_16x16x32_bf16 v[48:51], v[184:187], v[192:195], v[48:51]
	v_mfma_f32_16x16x32_bf16 v[36:39], v[166:169], v[200:203], v[36:39]
	v_mfma_f32_16x16x32_bf16 v[32:35], v[184:187], v[200:203], v[32:35]
	v_mfma_f32_16x16x32_bf16 v[20:23], v[166:169], v[208:211], v[20:23]
	v_mfma_f32_16x16x32_bf16 v[16:19], v[184:187], v[208:211], v[16:19]
	v_mfma_f32_16x16x32_bf16 v[4:7], v[166:169], v[216:219], v[4:7]
	v_mfma_f32_16x16x32_bf16 v[0:3], v[184:187], v[216:219], v[0:3]
	v_mfma_f32_16x16x32_bf16 v[52:55], v[180:183], v[196:199], v[52:55]
	v_mfma_f32_16x16x32_bf16 v[48:51], v[188:191], v[196:199], v[48:51]
	v_mfma_f32_16x16x32_bf16 v[36:39], v[180:183], v[204:207], v[36:39]
	v_mfma_f32_16x16x32_bf16 v[32:35], v[188:191], v[204:207], v[32:35]
	v_mfma_f32_16x16x32_bf16 v[20:23], v[180:183], v[212:215], v[20:23]
	v_mfma_f32_16x16x32_bf16 v[16:19], v[188:191], v[212:215], v[16:19]
	v_mfma_f32_16x16x32_bf16 v[4:7], v[180:183], v[220:223], v[4:7]
	v_mfma_f32_16x16x32_bf16 v[0:3], v[188:191], v[220:223], v[0:3]
	s_setprio 0
	s_barrier
	s_add_i32 s50, 0, 0x18000
	s_add_i32 s51, 0, 0x1c000
	v_add_u32_e32 v162, s50, v149
	v_add_u32_e32 v179, s51, v149
	ds_read_b128 v[142:145], v162
	ds_read_b128 v[154:157], v162 offset:1024
	ds_read_b128 v[158:161], v162 offset:2048
	ds_read_b128 v[162:165], v162 offset:3072
	ds_read_b128 v[166:169], v179
	ds_read_b128 v[180:183], v179 offset:1024
	ds_read_b128 v[184:187], v179 offset:2048
	ds_read_b128 v[188:191], v179 offset:3072
	s_add_u32 s18, s24, 0x160000
	s_addc_u32 s19, s25, 0
	s_mov_b32 m0, s31
	v_lshl_add_u64 v[228:229], s[18:19], 0, v[130:131]
	ds_read_b128 v[192:195], v153 offset:32768
	ds_read_b128 v[196:199], v153 offset:33792
	ds_read_b128 v[200:203], v153 offset:34816
	ds_read_b128 v[204:207], v153 offset:35840
	ds_read_b128 v[208:211], v153 offset:36864
	ds_read_b128 v[212:215], v153 offset:37888
	ds_read_b128 v[216:219], v153 offset:38912
	ds_read_b128 v[220:223], v153 offset:39936
	global_load_lds_dwordx4 v[228:229], off
	v_lshl_add_u64 v[228:229], s[18:19], 0, v[132:133]
	s_mov_b32 m0, s33
	s_nop 0
	global_load_lds_dwordx4 v[228:229], off
	s_waitcnt vmcnt(8)
	s_waitcnt lgkmcnt(0)
	s_barrier
	s_setprio 1
	s_waitcnt lgkmcnt(0)
	v_mfma_f32_16x16x32_bf16 v[124:127], v[142:145], v[192:195], v[124:127]
	v_mfma_f32_16x16x32_bf16 v[120:123], v[158:161], v[192:195], v[120:123]
	v_mfma_f32_16x16x32_bf16 v[108:111], v[142:145], v[200:203], v[108:111]
	v_mfma_f32_16x16x32_bf16 v[104:107], v[158:161], v[200:203], v[104:107]
	v_mfma_f32_16x16x32_bf16 v[92:95], v[142:145], v[208:211], v[92:95]
	v_mfma_f32_16x16x32_bf16 v[88:91], v[158:161], v[208:211], v[88:91]
	v_mfma_f32_16x16x32_bf16 v[76:79], v[142:145], v[216:219], v[76:79]
	v_mfma_f32_16x16x32_bf16 v[72:75], v[158:161], v[216:219], v[72:75]
	v_mfma_f32_16x16x32_bf16 v[124:127], v[154:157], v[196:199], v[124:127]
	v_mfma_f32_16x16x32_bf16 v[120:123], v[162:165], v[196:199], v[120:123]
	v_mfma_f32_16x16x32_bf16 v[108:111], v[154:157], v[204:207], v[108:111]
	v_mfma_f32_16x16x32_bf16 v[104:107], v[162:165], v[204:207], v[104:107]
	v_mfma_f32_16x16x32_bf16 v[92:95], v[154:157], v[212:215], v[92:95]
	v_mfma_f32_16x16x32_bf16 v[88:91], v[162:165], v[212:215], v[88:91]
	v_mfma_f32_16x16x32_bf16 v[76:79], v[154:157], v[220:223], v[76:79]
	v_mfma_f32_16x16x32_bf16 v[72:75], v[162:165], v[220:223], v[72:75]
	s_setprio 0
	s_setprio 1
	v_mfma_f32_16x16x32_bf16 v[116:119], v[166:169], v[192:195], v[116:119]
	v_mfma_f32_16x16x32_bf16 v[112:115], v[184:187], v[192:195], v[112:115]
	v_mfma_f32_16x16x32_bf16 v[100:103], v[166:169], v[200:203], v[100:103]
	v_mfma_f32_16x16x32_bf16 v[96:99], v[184:187], v[200:203], v[96:99]
	v_mfma_f32_16x16x32_bf16 v[84:87], v[166:169], v[208:211], v[84:87]
	v_mfma_f32_16x16x32_bf16 v[80:83], v[184:187], v[208:211], v[80:83]
	v_mfma_f32_16x16x32_bf16 v[68:71], v[166:169], v[216:219], v[68:71]
	v_mfma_f32_16x16x32_bf16 v[64:67], v[184:187], v[216:219], v[64:67]
	v_mfma_f32_16x16x32_bf16 v[116:119], v[180:183], v[196:199], v[116:119]
	v_mfma_f32_16x16x32_bf16 v[112:115], v[188:191], v[196:199], v[112:115]
	v_mfma_f32_16x16x32_bf16 v[100:103], v[180:183], v[204:207], v[100:103]
	v_mfma_f32_16x16x32_bf16 v[96:99], v[188:191], v[204:207], v[96:99]
	v_mfma_f32_16x16x32_bf16 v[84:87], v[180:183], v[212:215], v[84:87]
	v_mfma_f32_16x16x32_bf16 v[80:83], v[188:191], v[212:215], v[80:83]
	v_mfma_f32_16x16x32_bf16 v[68:71], v[180:183], v[220:223], v[68:71]
	v_mfma_f32_16x16x32_bf16 v[64:67], v[188:191], v[220:223], v[64:67]
	s_setprio 0
	s_barrier
; #define PG8_STAGE(bufoff, gbase, voff) do { _Pragma("unroll") for (int _i = 0; _i < 2; ++_i) \
;         __builtin_amdgcn_global_load_lds((const unsigned*)((const char*)(gbase) + (voff)[_i]), (PG8_LAS unsigned*)(lds + (bufoff) + ldsw + _i * 8192), 16, 0, 0); } while (0)
; #define PG8_LDA(dst, b, h) do { _Pragma("unroll") for (int m = 0; m < 4; ++m) _Pragma("unroll") for (int k = 0; k < 2; ++k) dst[m][k] = *(const PG8_LAS bf16x8*)(lds + PG8_SA(b, h) + aoff + m * 2048 + k * 1024); } while (0)
; #define PG8_LDB(dst, b, h) do { _Pragma("unroll") for (int n = 0; n < 2; ++n) _Pragma("unroll") for (int k = 0; k < 2; ++k) dst[n][k] = *(const PG8_LAS bf16x8*)(lds + PG8_SB(b, h) + boff + n * 2048 + k * 1024); } while (0)
; template <class Epi, class Sched, bool ALIGN_EPI = false, bool SP2 = false>
; __device__ __forceinline__ void gemm_phase(PG8_LAS unsigned char* lds, const Gemm g, const Sched& S, const Epi& E) {
;     ...
;         for (int t = 0; t < nt; t += 2) {
;             const bool last = (t == nt - 2);
;             const char* a1 = cA + (size_t)(t + 1) * kstep;
;             const char* a2 = last ? nA : cA + (size_t)(t + 2) * kstep; const char* b2 = last ? nB : cB + (size_t)(t + 2) * kstep;
;             const char* a3 = a2 + kstep; const char* b3 = b2 + kstep;
;             if (last && has_next) S.a_ready(nxt);
;             if constexpr (SP2) {
;             PG8_LDB(B0, 0, 0); PG8_LDB(B1, 0, 1); PG8_SCHED; PG8_LDA(At, 0, 0); PG8_STAGE(PG8_SA(1, 1), a1 + hstep, voffA);
;             PG8_WAIT_V(8); PG8_WAIT_L(0); PG8_BAR; PG8_MMA(0, 0, At, B0); PG8_MMA(0, 1, At, B1); PG8_BAR; PG8_SCHED;
;             PG8_LDA(At, 0, 1); PG8_STAGE(PG8_SB(0, 0), b2, voffB); PG8_STAGE(PG8_SB(0, 1), b2 + hstep, voffB); PG8_STAGE(PG8_SA(0, 0), a2, voffA);
;             PG8_WAIT_V(8); PG8_WAIT_L(0); PG8_BAR; PG8_MMA(1, 0, At, B0); PG8_MMA(1, 1, At, B1); PG8_BAR; PG8_SCHED;
;             PG8_LDB(B0, 1, 0); PG8_LDB(B1, 1, 1); PG8_SCHED; PG8_LDA(At, 1, 0); PG8_STAGE(PG8_SA(0, 1), a2 + hstep, voffA);
;             PG8_WAIT_V(8); PG8_WAIT_L(0); PG8_BAR; PG8_MMA(0, 0, At, B0); PG8_MMA(0, 1, At, B1); PG8_BAR; PG8_SCHED;
;             PG8_LDA(At, 1, 1); PG8_STAGE(PG8_SB(1, 0), b3, voffB); PG8_STAGE(PG8_SB(1, 1), b3 + hstep, voffB); PG8_STAGE(PG8_SA(1, 0), a3, voffA);
;             PG8_WAIT_V(8); PG8_WAIT_L(0); PG8_BAR; PG8_MMA(1, 0, At, B0); PG8_MMA(1, 1, At, B1); PG8_BAR; PG8_SCHED;
	s_add_i32 s18, s50, s28
	v_lshl_add_u64 v[146:147], v[146:147], 0, s[4:5]
	s_mov_b32 m0, s18
	ds_read_b128 v[192:195], v153 offset:49152
	ds_read_b128 v[196:199], v153 offset:50176
	ds_read_b128 v[200:203], v153 offset:51200
	ds_read_b128 v[204:207], v153 offset:52224
	ds_read_b128 v[208:211], v153 offset:53248
	ds_read_b128 v[212:215], v153 offset:54272
	ds_read_b128 v[216:219], v153 offset:55296
	ds_read_b128 v[220:223], v153 offset:56320
	global_load_lds_dwordx4 v[146:147], off
	s_add_i32 m0, s18, 0x2000
	s_add_u32 s18, s22, 0x160080
	v_lshl_add_u64 v[146:147], v[170:171], 0, s[4:5]
	s_addc_u32 s19, s23, 0
	s_add_i32 s22, s51, s28
	global_load_lds_dwordx4 v[146:147], off
	v_lshl_add_u64 v[146:147], s[18:19], 0, v[130:131]
	s_mov_b32 m0, s22
	s_nop 0
	global_load_lds_dwordx4 v[146:147], off
	v_lshl_add_u64 v[146:147], s[18:19], 0, v[132:133]
	s_add_i32 m0, s22, 0x2000
	s_nop 0
	global_load_lds_dwordx4 v[146:147], off
	v_lshl_add_u64 v[146:147], v[224:225], 0, s[4:5]
	s_mov_b32 m0, s35
	s_nop 0
	global_load_lds_dwordx4 v[146:147], off
	v_lshl_add_u64 v[146:147], v[226:227], 0, s[4:5]
	s_mov_b32 m0, s36
	s_nop 0
	global_load_lds_dwordx4 v[146:147], off
	s_waitcnt vmcnt(8)
	s_waitcnt lgkmcnt(0)
	s_barrier
	s_setprio 1
	s_waitcnt lgkmcnt(0)
	v_mfma_f32_16x16x32_bf16 v[60:63], v[142:145], v[192:195], v[60:63]
	v_mfma_f32_16x16x32_bf16 v[56:59], v[158:161], v[192:195], v[56:59]
	v_mfma_f32_16x16x32_bf16 v[44:47], v[142:145], v[200:203], v[44:47]
	v_mfma_f32_16x16x32_bf16 v[40:43], v[158:161], v[200:203], v[40:43]
	v_mfma_f32_16x16x32_bf16 v[28:31], v[142:145], v[208:211], v[28:31]
	v_mfma_f32_16x16x32_bf16 v[24:27], v[158:161], v[208:211], v[24:27]
	v_mfma_f32_16x16x32_bf16 v[12:15], v[142:145], v[216:219], v[12:15]
	v_mfma_f32_16x16x32_bf16 v[8:11], v[158:161], v[216:219], v[8:11]
	v_mfma_f32_16x16x32_bf16 v[60:63], v[154:157], v[196:199], v[60:63]
	v_mfma_f32_16x16x32_bf16 v[56:59], v[162:165], v[196:199], v[56:59]
	v_mfma_f32_16x16x32_bf16 v[44:47], v[154:157], v[204:207], v[44:47]
	v_mfma_f32_16x16x32_bf16 v[40:43], v[162:165], v[204:207], v[40:43]
	v_mfma_f32_16x16x32_bf16 v[28:31], v[154:157], v[212:215], v[28:31]
	v_mfma_f32_16x16x32_bf16 v[24:27], v[162:165], v[212:215], v[24:27]
	v_mfma_f32_16x16x32_bf16 v[12:15], v[154:157], v[220:223], v[12:15]
	v_mfma_f32_16x16x32_bf16 v[8:11], v[162:165], v[220:223], v[8:11]
	s_setprio 0
	s_setprio 1
	v_mfma_f32_16x16x32_bf16 v[52:55], v[166:169], v[192:195], v[52:55]
	v_mfma_f32_16x16x32_bf16 v[48:51], v[184:187], v[192:195], v[48:51]
	v_mfma_f32_16x16x32_bf16 v[36:39], v[166:169], v[200:203], v[36:39]
	v_mfma_f32_16x16x32_bf16 v[32:35], v[184:187], v[200:203], v[32:35]
	v_mfma_f32_16x16x32_bf16 v[20:23], v[166:169], v[208:211], v[20:23]
	v_mfma_f32_16x16x32_bf16 v[16:19], v[184:187], v[208:211], v[16:19]
	v_mfma_f32_16x16x32_bf16 v[4:7], v[166:169], v[216:219], v[4:7]
	v_mfma_f32_16x16x32_bf16 v[0:3], v[184:187], v[216:219], v[0:3]
	v_mfma_f32_16x16x32_bf16 v[52:55], v[180:183], v[196:199], v[52:55]
	v_mfma_f32_16x16x32_bf16 v[48:51], v[188:191], v[196:199], v[48:51]
	v_mfma_f32_16x16x32_bf16 v[36:39], v[180:183], v[204:207], v[36:39]
	v_mfma_f32_16x16x32_bf16 v[32:35], v[188:191], v[204:207], v[32:35]
	v_mfma_f32_16x16x32_bf16 v[20:23], v[180:183], v[212:215], v[20:23]
	v_mfma_f32_16x16x32_bf16 v[16:19], v[188:191], v[212:215], v[16:19]
	v_mfma_f32_16x16x32_bf16 v[4:7], v[180:183], v[220:223], v[4:7]
	v_mfma_f32_16x16x32_bf16 v[0:3], v[188:191], v[220:223], v[0:3]
	s_setprio 0
	s_barrier
	s_add_i32 s49, s49, 2
	s_add_u32 s47, s47, 0x100
	s_addc_u32 s48, s48, 0
	s_cmpk_gt_u32 s49, 0x55
	s_mov_b64 s[18:19], s[20:21]
	s_cbranch_scc0 .LBB0_1080
	s_nop 0
	v_readfirstlane_b32 s18, v172
	s_nop 3
	s_lshr_b32 s18, s18, 6
	s_cmp_ge_u32 s18, 4
	s_cbranch_scc0 .Lprio_k3
	s_setprio 1

; #define PG8_STAGE(bufoff, gbase, voff) do { _Pragma("unroll") for (int _i = 0; _i < 2; ++_i) \
;         __builtin_amdgcn_global_load_lds((const unsigned*)((const char*)(gbase) + (voff)[_i]), (PG8_LAS unsigned*)(lds + (bufoff) + ldsw + _i * 8192), 16, 0, 0); } while (0)
; #define PG8_LDA(dst, b, h) do { _Pragma("unroll") for (int m = 0; m < 4; ++m) _Pragma("unroll") for (int k = 0; k < 2; ++k) dst[m][k] = *(const PG8_LAS bf16x8*)(lds + PG8_SA(b, h) + aoff + m * 2048 + k * 1024); } while (0)
; #define PG8_LDB(dst, b, h) do { _Pragma("unroll") for (int n = 0; n < 2; ++n) _Pragma("unroll") for (int k = 0; k < 2; ++k) dst[n][k] = *(const PG8_LAS bf16x8*)(lds + PG8_SB(b, h) + boff + n * 2048 + k * 1024); } while (0)
; #define PG8_MMA(ai, bj, At, Bt) do { __builtin_amdgcn_s_setprio(1); _Pragma("unroll") for (int m = 0; m < 4; ++m) _Pragma("unroll") for (int n = 0; n < 2; ++n) _Pragma("unroll") for (int k = 0; k < 2; ++k) \
;         acc[ai][bj][m][n] = __builtin_amdgcn_mfma_f32_16x16x32_bf16(Bt[n][k], At[m][k], acc[ai][bj][m][n], 0, 0, 0); __builtin_amdgcn_s_setprio(0); } while (0)
; #define PG8_WAIT_V(n) asm volatile("s_waitcnt vmcnt(" #n ")" ::: "memory")
; #define PG8_WAIT_L(n) asm volatile("s_waitcnt lgkmcnt(" #n ")" ::: "memory")
; template <class Epi, class Sched, bool ALIGN_EPI = false, bool SP2 = false>
; __device__ __forceinline__ void gemm_phase(PG8_LAS unsigned char* lds, const Gemm g, const Sched& S, const Epi& E) {
;     ...
;             const bool last = (t == nt - 2);
;             const char* a1 = cA + (size_t)(t + 1) * kstep;
;             const char* a2 = last ? nA : cA + (size_t)(t + 2) * kstep; const char* b2 = last ? nB : cB + (size_t)(t + 2) * kstep;
;             const char* a3 = a2 + kstep; const char* b3 = b2 + kstep;
;             if (last && has_next) S.a_ready(nxt);
;             if constexpr (SP2) {
;             PG8_LDB(B0, 0, 0); PG8_LDB(B1, 0, 1); PG8_SCHED; PG8_LDA(At, 0, 0); PG8_STAGE(PG8_SA(1, 1), a1 + hstep, voffA);
;             PG8_WAIT_V(8); PG8_WAIT_L(0); PG8_BAR; PG8_MMA(0, 0, At, B0); PG8_MMA(0, 1, At, B1); PG8_BAR; PG8_SCHED;
;             PG8_LDA(At, 0, 1); PG8_STAGE(PG8_SB(0, 0), b2, voffB); PG8_STAGE(PG8_SB(0, 1), b2 + hstep, voffB); PG8_STAGE(PG8_SA(0, 0), a2, voffA);
;             PG8_WAIT_V(8); PG8_WAIT_L(0); PG8_BAR; PG8_MMA(1, 0, At, B0); PG8_MMA(1, 1, At, B1); PG8_BAR; PG8_SCHED;
.LBB0_1181:
	ds_read_b128 v[146:149], v154
	ds_read_b128 v[158:161], v154 offset:1024
	ds_read_b128 v[162:165], v154 offset:2048
	ds_read_b128 v[166:169], v154 offset:3072
	ds_read_b128 v[180:183], v155
	ds_read_b128 v[184:187], v155 offset:1024
	ds_read_b128 v[188:191], v155 offset:2048
	ds_read_b128 v[192:195], v155 offset:3072
	s_add_u32 s22, s20, 0xfff80080
	s_addc_u32 s23, s21, -1
	s_cmp_eq_u32 s48, 28
	s_cselect_b32 s25, s11, s23
	s_cselect_b32 s24, s44, s22
	s_cselect_b32 s23, s7, s47
	s_cselect_b32 s22, s45, s46
	v_lshl_add_u64 v[170:171], s[20:21], 0, v[138:139]
	s_add_i32 m0, s17, 0xc000
	ds_read_b128 v[196:199], v156
	ds_read_b128 v[200:203], v156 offset:1024
	ds_read_b128 v[204:207], v156 offset:2048
	ds_read_b128 v[208:211], v156 offset:3072
	ds_read_b128 v[212:215], v156 offset:4096
	ds_read_b128 v[216:219], v156 offset:5120
	ds_read_b128 v[220:223], v156 offset:6144
	ds_read_b128 v[224:227], v156 offset:7168
	global_load_lds_dwordx4 v[170:171], off
	v_lshl_add_u64 v[170:171], s[20:21], 0, v[140:141]
	s_add_i32 m0, s17, 0xe000
	s_nop 0
	global_load_lds_dwordx4 v[170:171], off
	s_waitcnt vmcnt(8)
	s_waitcnt lgkmcnt(0)
	s_barrier
	s_setprio 1
	s_waitcnt lgkmcnt(0)
	v_mfma_f32_16x16x32_bf16 v[124:127], v[146:149], v[196:199], v[124:127]
	v_mfma_f32_16x16x32_bf16 v[120:123], v[162:165], v[196:199], v[120:123]
	v_mfma_f32_16x16x32_bf16 v[112:115], v[146:149], v[204:207], v[112:115]
	v_mfma_f32_16x16x32_bf16 v[104:107], v[162:165], v[204:207], v[104:107]
	v_mfma_f32_16x16x32_bf16 v[96:99], v[146:149], v[212:215], v[96:99]
	v_mfma_f32_16x16x32_bf16 v[88:91], v[162:165], v[212:215], v[88:91]
	v_mfma_f32_16x16x32_bf16 v[80:83], v[146:149], v[220:223], v[80:83]
	v_mfma_f32_16x16x32_bf16 v[72:75], v[162:165], v[220:223], v[72:75]
	v_mfma_f32_16x16x32_bf16 v[124:127], v[158:161], v[200:203], v[124:127]
	v_mfma_f32_16x16x32_bf16 v[120:123], v[166:169], v[200:203], v[120:123]
	v_mfma_f32_16x16x32_bf16 v[112:115], v[158:161], v[208:211], v[112:115]
	v_mfma_f32_16x16x32_bf16 v[104:107], v[166:169], v[208:211], v[104:107]
	v_mfma_f32_16x16x32_bf16 v[96:99], v[158:161], v[216:219], v[96:99]
	v_mfma_f32_16x16x32_bf16 v[88:91], v[166:169], v[216:219], v[88:91]
	v_mfma_f32_16x16x32_bf16 v[80:83], v[158:161], v[224:227], v[80:83]
	v_mfma_f32_16x16x32_bf16 v[72:75], v[166:169], v[224:227], v[72:75]
	s_setprio 0
	s_setprio 1
	v_mfma_f32_16x16x32_bf16 v[116:119], v[180:183], v[196:199], v[116:119]
	v_mfma_f32_16x16x32_bf16 v[108:111], v[188:191], v[196:199], v[108:111]
	v_mfma_f32_16x16x32_bf16 v[100:103], v[180:183], v[204:207], v[100:103]
	v_mfma_f32_16x16x32_bf16 v[92:95], v[188:191], v[204:207], v[92:95]
	v_mfma_f32_16x16x32_bf16 v[84:87], v[180:183], v[212:215], v[84:87]
	v_mfma_f32_16x16x32_bf16 v[76:79], v[188:191], v[212:215], v[76:79]
	v_mfma_f32_16x16x32_bf16 v[68:71], v[180:183], v[220:223], v[68:71]
	v_mfma_f32_16x16x32_bf16 v[64:67], v[188:191], v[220:223], v[64:67]
	v_mfma_f32_16x16x32_bf16 v[116:119], v[184:187], v[200:203], v[116:119]
	v_mfma_f32_16x16x32_bf16 v[108:111], v[192:195], v[200:203], v[108:111]
	v_mfma_f32_16x16x32_bf16 v[100:103], v[184:187], v[208:211], v[100:103]
	v_mfma_f32_16x16x32_bf16 v[92:95], v[192:195], v[208:211], v[92:95]
	v_mfma_f32_16x16x32_bf16 v[84:87], v[184:187], v[216:219], v[84:87]
	v_mfma_f32_16x16x32_bf16 v[76:79], v[192:195], v[216:219], v[76:79]
	v_mfma_f32_16x16x32_bf16 v[68:71], v[184:187], v[224:227], v[68:71]
	v_mfma_f32_16x16x32_bf16 v[64:67], v[192:195], v[224:227], v[64:67]
	s_setprio 0
	s_barrier
	s_add_i32 s49, s35, s28
	v_lshl_add_u64 v[170:171], s[22:23], 0, v[132:133]
	s_mov_b32 m0, s49
	ds_read_b128 v[196:199], v156 offset:16384
	ds_read_b128 v[200:203], v156 offset:17408
	ds_read_b128 v[204:207], v156 offset:18432
	ds_read_b128 v[208:211], v156 offset:19456
	ds_read_b128 v[212:215], v156 offset:20480
	ds_read_b128 v[216:219], v156 offset:21504
	ds_read_b128 v[220:223], v156 offset:22528
	ds_read_b128 v[224:227], v156 offset:23552
	global_load_lds_dwordx4 v[170:171], off
	s_add_i32 m0, s49, 0x2000
	s_add_u32 s50, s22, 0x80000
	v_lshl_add_u64 v[228:229], s[22:23], 0, v[136:137]
	s_addc_u32 s51, s23, 0
	s_add_i32 s49, s36, s28
	global_load_lds_dwordx4 v[228:229], off
	v_lshl_add_u64 v[230:231], s[50:51], 0, v[132:133]
	s_mov_b32 m0, s49
	v_lshl_add_u64 v[232:233], s[24:25], 0, v[134:135]
	global_load_lds_dwordx4 v[230:231], off
	v_lshl_add_u64 v[230:231], s[50:51], 0, v[136:137]
	s_add_i32 m0, s49, 0x2000
	s_nop 0
	global_load_lds_dwordx4 v[230:231], off
	v_lshl_add_u64 v[230:231], s[24:25], 0, v[130:131]
	s_mov_b32 m0, s17
	s_nop 0
	global_load_lds_dwordx4 v[230:231], off
	s_mov_b32 m0, s29
	s_nop 0
	global_load_lds_dwordx4 v[232:233], off
	s_waitcnt vmcnt(8)
	s_waitcnt lgkmcnt(0)
	s_barrier
; #define PG8_STAGE(bufoff, gbase, voff) do { _Pragma("unroll") for (int _i = 0; _i < 2; ++_i) \
;         __builtin_amdgcn_global_load_lds((const unsigned*)((const char*)(gbase) + (voff)[_i]), (PG8_LAS unsigned*)(lds + (bufoff) + ldsw + _i * 8192), 16, 0, 0); } while (0)
; #define PG8_LDA(dst, b, h) do { _Pragma("unroll") for (int m = 0; m < 4; ++m) _Pragma("unroll") for (int k = 0; k < 2; ++k) dst[m][k] = *(const PG8_LAS bf16x8*)(lds + PG8_SA(b, h) + aoff + m * 2048 + k * 1024); } while (0)
; #define PG8_LDB(dst, b, h) do { _Pragma("unroll") for (int n = 0; n < 2; ++n) _Pragma("unroll") for (int k = 0; k < 2; ++k) dst[n][k] = *(const PG8_LAS bf16x8*)(lds + PG8_SB(b, h) + boff + n * 2048 + k * 1024); } while (0)
; #define PG8_MMA(ai, bj, At, Bt) do { __builtin_amdgcn_s_setprio(1); _Pragma("unroll") for (int m = 0; m < 4; ++m) _Pragma("unroll") for (int n = 0; n < 2; ++n) _Pragma("unroll") for (int k = 0; k < 2; ++k) \
;         acc[ai][bj][m][n] = __builtin_amdgcn_mfma_f32_16x16x32_bf16(Bt[n][k], At[m][k], acc[ai][bj][m][n], 0, 0, 0); __builtin_amdgcn_s_setprio(0); } while (0)
; #define PG8_WAIT_V(n) asm volatile("s_waitcnt vmcnt(" #n ")" ::: "memory")
; #define PG8_WAIT_L(n) asm volatile("s_waitcnt lgkmcnt(" #n ")" ::: "memory")
; #define PG8_BAR __builtin_amdgcn_s_barrier()
; #define PG8_SCHED __builtin_amdgcn_sched_barrier(0)
; template <class Epi, class Sched, bool ALIGN_EPI = false, bool SP2 = false>
; __device__ __forceinline__ void gemm_phase(PG8_LAS unsigned char* lds, const Gemm g, const Sched& S, const Epi& E) {
;     ...
;             PG8_WAIT_V(8); PG8_WAIT_L(0); PG8_BAR; PG8_MMA(1, 0, At, B0); PG8_MMA(1, 1, At, B1); PG8_BAR; PG8_SCHED;
;             PG8_LDB(B0, 1, 0); PG8_LDB(B1, 1, 1); PG8_SCHED; PG8_LDA(At, 1, 0); PG8_STAGE(PG8_SA(0, 1), a2 + hstep, voffA);
;             PG8_WAIT_V(8); PG8_WAIT_L(0); PG8_BAR; PG8_MMA(0, 0, At, B0); PG8_MMA(0, 1, At, B1); PG8_BAR; PG8_SCHED;
	s_setprio 1
	s_waitcnt lgkmcnt(0)
	v_mfma_f32_16x16x32_bf16 v[60:63], v[146:149], v[196:199], v[60:63]
	v_mfma_f32_16x16x32_bf16 v[56:59], v[162:165], v[196:199], v[56:59]
	v_mfma_f32_16x16x32_bf16 v[52:55], v[146:149], v[204:207], v[52:55]
	v_mfma_f32_16x16x32_bf16 v[44:47], v[162:165], v[204:207], v[44:47]
	v_mfma_f32_16x16x32_bf16 v[36:39], v[146:149], v[212:215], v[36:39]
	v_mfma_f32_16x16x32_bf16 v[28:31], v[162:165], v[212:215], v[28:31]
	v_mfma_f32_16x16x32_bf16 v[20:23], v[146:149], v[220:223], v[20:23]
	v_mfma_f32_16x16x32_bf16 v[12:15], v[162:165], v[220:223], v[12:15]
	v_mfma_f32_16x16x32_bf16 v[60:63], v[158:161], v[200:203], v[60:63]
	v_mfma_f32_16x16x32_bf16 v[56:59], v[166:169], v[200:203], v[56:59]
	v_mfma_f32_16x16x32_bf16 v[52:55], v[158:161], v[208:211], v[52:55]
	v_mfma_f32_16x16x32_bf16 v[44:47], v[166:169], v[208:211], v[44:47]
	v_mfma_f32_16x16x32_bf16 v[36:39], v[158:161], v[216:219], v[36:39]
	v_mfma_f32_16x16x32_bf16 v[28:31], v[166:169], v[216:219], v[28:31]
	v_mfma_f32_16x16x32_bf16 v[20:23], v[158:161], v[224:227], v[20:23]
	v_mfma_f32_16x16x32_bf16 v[12:15], v[166:169], v[224:227], v[12:15]
	s_setprio 0
	s_setprio 1
	v_mfma_f32_16x16x32_bf16 v[48:51], v[180:183], v[196:199], v[48:51]
	v_mfma_f32_16x16x32_bf16 v[40:43], v[188:191], v[196:199], v[40:43]
	v_mfma_f32_16x16x32_bf16 v[32:35], v[180:183], v[204:207], v[32:35]
	v_mfma_f32_16x16x32_bf16 v[24:27], v[188:191], v[204:207], v[24:27]
	v_mfma_f32_16x16x32_bf16 v[16:19], v[180:183], v[212:215], v[16:19]
	v_mfma_f32_16x16x32_bf16 v[8:11], v[188:191], v[212:215], v[8:11]
	v_mfma_f32_16x16x32_bf16 v[4:7], v[180:183], v[220:223], v[4:7]
	v_mfma_f32_16x16x32_bf16 v[0:3], v[188:191], v[220:223], v[0:3]
	v_mfma_f32_16x16x32_bf16 v[48:51], v[184:187], v[200:203], v[48:51]
	v_mfma_f32_16x16x32_bf16 v[40:43], v[192:195], v[200:203], v[40:43]
	v_mfma_f32_16x16x32_bf16 v[32:35], v[184:187], v[208:211], v[32:35]
	v_mfma_f32_16x16x32_bf16 v[24:27], v[192:195], v[208:211], v[24:27]
	v_mfma_f32_16x16x32_bf16 v[16:19], v[184:187], v[216:219], v[16:19]
	v_mfma_f32_16x16x32_bf16 v[8:11], v[192:195], v[216:219], v[8:11]
	v_mfma_f32_16x16x32_bf16 v[4:7], v[184:187], v[224:227], v[4:7]
	v_mfma_f32_16x16x32_bf16 v[0:3], v[192:195], v[224:227], v[0:3]
	s_setprio 0
	s_barrier
	s_add_i32 s49, 0, 0x18000
	v_add_u32_e32 v157, s49, v151
	s_add_i32 s50, 0, 0x1c000
	ds_read_b128 v[146:149], v157
	ds_read_b128 v[158:161], v157 offset:1024
	ds_read_b128 v[162:165], v157 offset:2048
	ds_read_b128 v[166:169], v157 offset:3072
	v_add_u32_e32 v157, s50, v151
	ds_read_b128 v[180:183], v157
	ds_read_b128 v[184:187], v157 offset:1024
	ds_read_b128 v[188:191], v157 offset:2048
	ds_read_b128 v[192:195], v157 offset:3072
	s_add_u32 s24, s24, 0x80000
	s_addc_u32 s25, s25, 0
	s_mov_b32 m0, s30
	v_lshl_add_u64 v[234:235], s[24:25], 0, v[130:131]
	ds_read_b128 v[196:199], v156 offset:32768
	ds_read_b128 v[200:203], v156 offset:33792
	ds_read_b128 v[204:207], v156 offset:34816
	ds_read_b128 v[208:211], v156 offset:35840
	ds_read_b128 v[212:215], v156 offset:36864
	ds_read_b128 v[216:219], v156 offset:37888
	ds_read_b128 v[220:223], v156 offset:38912
	ds_read_b128 v[224:227], v156 offset:39936
	global_load_lds_dwordx4 v[234:235], off
	v_lshl_add_u64 v[234:235], s[24:25], 0, v[134:135]
	s_mov_b32 m0, s31
	s_nop 0
	global_load_lds_dwordx4 v[234:235], off
	s_waitcnt vmcnt(8)
	s_waitcnt lgkmcnt(0)
	s_barrier
	s_setprio 1
	s_waitcnt lgkmcnt(0)
	v_mfma_f32_16x16x32_bf16 v[124:127], v[146:149], v[196:199], v[124:127]
	v_mfma_f32_16x16x32_bf16 v[120:123], v[162:165], v[196:199], v[120:123]
	v_mfma_f32_16x16x32_bf16 v[112:115], v[146:149], v[204:207], v[112:115]
	v_mfma_f32_16x16x32_bf16 v[104:107], v[162:165], v[204:207], v[104:107]
	v_mfma_f32_16x16x32_bf16 v[96:99], v[146:149], v[212:215], v[96:99]
	v_mfma_f32_16x16x32_bf16 v[88:91], v[162:165], v[212:215], v[88:91]
	v_mfma_f32_16x16x32_bf16 v[80:83], v[146:149], v[220:223], v[80:83]
	v_mfma_f32_16x16x32_bf16 v[72:75], v[162:165], v[220:223], v[72:75]
	v_mfma_f32_16x16x32_bf16 v[124:127], v[158:161], v[200:203], v[124:127]
	v_mfma_f32_16x16x32_bf16 v[120:123], v[166:169], v[200:203], v[120:123]
	v_mfma_f32_16x16x32_bf16 v[112:115], v[158:161], v[208:211], v[112:115]
	v_mfma_f32_16x16x32_bf16 v[104:107], v[166:169], v[208:211], v[104:107]
	v_mfma_f32_16x16x32_bf16 v[96:99], v[158:161], v[216:219], v[96:99]
	v_mfma_f32_16x16x32_bf16 v[88:91], v[166:169], v[216:219], v[88:91]
	v_mfma_f32_16x16x32_bf16 v[80:83], v[158:161], v[224:227], v[80:83]
	v_mfma_f32_16x16x32_bf16 v[72:75], v[166:169], v[224:227], v[72:75]
	s_setprio 0
	s_setprio 1
	v_mfma_f32_16x16x32_bf16 v[116:119], v[180:183], v[196:199], v[116:119]
	v_mfma_f32_16x16x32_bf16 v[108:111], v[188:191], v[196:199], v[108:111]
	v_mfma_f32_16x16x32_bf16 v[100:103], v[180:183], v[204:207], v[100:103]
	v_mfma_f32_16x16x32_bf16 v[92:95], v[188:191], v[204:207], v[92:95]
	v_mfma_f32_16x16x32_bf16 v[84:87], v[180:183], v[212:215], v[84:87]
	v_mfma_f32_16x16x32_bf16 v[76:79], v[188:191], v[212:215], v[76:79]
	v_mfma_f32_16x16x32_bf16 v[68:71], v[180:183], v[220:223], v[68:71]
	v_mfma_f32_16x16x32_bf16 v[64:67], v[188:191], v[220:223], v[64:67]
	v_mfma_f32_16x16x32_bf16 v[116:119], v[184:187], v[200:203], v[116:119]
	v_mfma_f32_16x16x32_bf16 v[108:111], v[192:195], v[200:203], v[108:111]
	v_mfma_f32_16x16x32_bf16 v[100:103], v[184:187], v[208:211], v[100:103]
	v_mfma_f32_16x16x32_bf16 v[92:95], v[192:195], v[208:211], v[92:95]
	v_mfma_f32_16x16x32_bf16 v[84:87], v[184:187], v[216:219], v[84:87]
	v_mfma_f32_16x16x32_bf16 v[76:79], v[192:195], v[216:219], v[76:79]
	v_mfma_f32_16x16x32_bf16 v[68:71], v[184:187], v[224:227], v[68:71]
	v_mfma_f32_16x16x32_bf16 v[64:67], v[192:195], v[224:227], v[64:67]
	s_setprio 0
	s_barrier
; #define PG8_STAGE(bufoff, gbase, voff) do { _Pragma("unroll") for (int _i = 0; _i < 2; ++_i) \
;         __builtin_amdgcn_global_load_lds((const unsigned*)((const char*)(gbase) + (voff)[_i]), (PG8_LAS unsigned*)(lds + (bufoff) + ldsw + _i * 8192), 16, 0, 0); } while (0)
; #define PG8_LDA(dst, b, h) do { _Pragma("unroll") for (int m = 0; m < 4; ++m) _Pragma("unroll") for (int k = 0; k < 2; ++k) dst[m][k] = *(const PG8_LAS bf16x8*)(lds + PG8_SA(b, h) + aoff + m * 2048 + k * 1024); } while (0)
; #define PG8_LDB(dst, b, h) do { _Pragma("unroll") for (int n = 0; n < 2; ++n) _Pragma("unroll") for (int k = 0; k < 2; ++k) dst[n][k] = *(const PG8_LAS bf16x8*)(lds + PG8_SB(b, h) + boff + n * 2048 + k * 1024); } while (0)
; template <class Epi, class Sched, bool ALIGN_EPI = false, bool SP2 = false>
; __device__ __forceinline__ void gemm_phase(PG8_LAS unsigned char* lds, const Gemm g, const Sched& S, const Epi& E) {
;     ...
;         for (int t = 0; t < nt; t += 2) {
;             const bool last = (t == nt - 2);
;             const char* a1 = cA + (size_t)(t + 1) * kstep;
;             const char* a2 = last ? nA : cA + (size_t)(t + 2) * kstep; const char* b2 = last ? nB : cB + (size_t)(t + 2) * kstep;
;             const char* a3 = a2 + kstep; const char* b3 = b2 + kstep;
;             if (last && has_next) S.a_ready(nxt);
;             if constexpr (SP2) {
;             PG8_LDB(B0, 0, 0); PG8_LDB(B1, 0, 1); PG8_SCHED; PG8_LDA(At, 0, 0); PG8_STAGE(PG8_SA(1, 1), a1 + hstep, voffA);
;             PG8_WAIT_V(8); PG8_WAIT_L(0); PG8_BAR; PG8_MMA(0, 0, At, B0); PG8_MMA(0, 1, At, B1); PG8_BAR; PG8_SCHED;
;             PG8_LDA(At, 0, 1); PG8_STAGE(PG8_SB(0, 0), b2, voffB); PG8_STAGE(PG8_SB(0, 1), b2 + hstep, voffB); PG8_STAGE(PG8_SA(0, 0), a2, voffA);
;             PG8_WAIT_V(8); PG8_WAIT_L(0); PG8_BAR; PG8_MMA(1, 0, At, B0); PG8_MMA(1, 1, At, B1); PG8_BAR; PG8_SCHED;
;             PG8_LDB(B0, 1, 0); PG8_LDB(B1, 1, 1); PG8_SCHED; PG8_LDA(At, 1, 0); PG8_STAGE(PG8_SA(0, 1), a2 + hstep, voffA);
;             PG8_WAIT_V(8); PG8_WAIT_L(0); PG8_BAR; PG8_MMA(0, 0, At, B0); PG8_MMA(0, 1, At, B1); PG8_BAR; PG8_SCHED;
;             PG8_LDA(At, 1, 1); PG8_STAGE(PG8_SB(1, 0), b3, voffB); PG8_STAGE(PG8_SB(1, 1), b3 + hstep, voffB); PG8_STAGE(PG8_SA(1, 0), a3, voffA);
;             PG8_WAIT_V(8); PG8_WAIT_L(0); PG8_BAR; PG8_MMA(1, 0, At, B0); PG8_MMA(1, 1, At, B1); PG8_BAR; PG8_SCHED;
	s_add_i32 s24, s49, s28
	v_lshl_add_u64 v[170:171], v[170:171], 0, s[2:3]
	s_mov_b32 m0, s24
	ds_read_b128 v[196:199], v156 offset:49152
	ds_read_b128 v[200:203], v156 offset:50176
	ds_read_b128 v[204:207], v156 offset:51200
	ds_read_b128 v[208:211], v156 offset:52224
	ds_read_b128 v[212:215], v156 offset:53248
	ds_read_b128 v[216:219], v156 offset:54272
	ds_read_b128 v[220:223], v156 offset:55296
	ds_read_b128 v[224:227], v156 offset:56320
	global_load_lds_dwordx4 v[170:171], off
	s_add_i32 m0, s24, 0x2000
	s_add_u32 s22, s22, 0x80080
	v_lshl_add_u64 v[170:171], v[228:229], 0, s[2:3]
	s_addc_u32 s23, s23, 0
	s_add_i32 s24, s50, s28
	global_load_lds_dwordx4 v[170:171], off
	v_lshl_add_u64 v[170:171], s[22:23], 0, v[132:133]
	s_mov_b32 m0, s24
	s_nop 0
	global_load_lds_dwordx4 v[170:171], off
	v_lshl_add_u64 v[170:171], s[22:23], 0, v[136:137]
	s_add_i32 m0, s24, 0x2000
	s_nop 0
	global_load_lds_dwordx4 v[170:171], off
	v_lshl_add_u64 v[170:171], v[230:231], 0, s[2:3]
	s_mov_b32 m0, s33
	s_nop 0
	global_load_lds_dwordx4 v[170:171], off
	v_lshl_add_u64 v[170:171], v[232:233], 0, s[2:3]
	s_mov_b32 m0, s34
	s_nop 0
	global_load_lds_dwordx4 v[170:171], off
	s_waitcnt vmcnt(8)
	s_waitcnt lgkmcnt(0)
	s_barrier
	s_setprio 1
	s_waitcnt lgkmcnt(0)
	v_mfma_f32_16x16x32_bf16 v[60:63], v[146:149], v[196:199], v[60:63]
	v_mfma_f32_16x16x32_bf16 v[56:59], v[162:165], v[196:199], v[56:59]
	v_mfma_f32_16x16x32_bf16 v[52:55], v[146:149], v[204:207], v[52:55]
	v_mfma_f32_16x16x32_bf16 v[44:47], v[162:165], v[204:207], v[44:47]
	v_mfma_f32_16x16x32_bf16 v[36:39], v[146:149], v[212:215], v[36:39]
	v_mfma_f32_16x16x32_bf16 v[28:31], v[162:165], v[212:215], v[28:31]
	v_mfma_f32_16x16x32_bf16 v[20:23], v[146:149], v[220:223], v[20:23]
	v_mfma_f32_16x16x32_bf16 v[12:15], v[162:165], v[220:223], v[12:15]
	v_mfma_f32_16x16x32_bf16 v[60:63], v[158:161], v[200:203], v[60:63]
	v_mfma_f32_16x16x32_bf16 v[56:59], v[166:169], v[200:203], v[56:59]
	v_mfma_f32_16x16x32_bf16 v[52:55], v[158:161], v[208:211], v[52:55]
	v_mfma_f32_16x16x32_bf16 v[44:47], v[166:169], v[208:211], v[44:47]
	v_mfma_f32_16x16x32_bf16 v[36:39], v[158:161], v[216:219], v[36:39]
	v_mfma_f32_16x16x32_bf16 v[28:31], v[166:169], v[216:219], v[28:31]
	v_mfma_f32_16x16x32_bf16 v[20:23], v[158:161], v[224:227], v[20:23]
	v_mfma_f32_16x16x32_bf16 v[12:15], v[166:169], v[224:227], v[12:15]
	s_setprio 0
	s_setprio 1
	v_mfma_f32_16x16x32_bf16 v[48:51], v[180:183], v[196:199], v[48:51]
	v_mfma_f32_16x16x32_bf16 v[40:43], v[188:191], v[196:199], v[40:43]
	v_mfma_f32_16x16x32_bf16 v[32:35], v[180:183], v[204:207], v[32:35]
	v_mfma_f32_16x16x32_bf16 v[24:27], v[188:191], v[204:207], v[24:27]
	v_mfma_f32_16x16x32_bf16 v[16:19], v[180:183], v[212:215], v[16:19]
	v_mfma_f32_16x16x32_bf16 v[8:11], v[188:191], v[212:215], v[8:11]
	v_mfma_f32_16x16x32_bf16 v[4:7], v[180:183], v[220:223], v[4:7]
	v_mfma_f32_16x16x32_bf16 v[0:3], v[188:191], v[220:223], v[0:3]
	v_mfma_f32_16x16x32_bf16 v[48:51], v[184:187], v[200:203], v[48:51]
	v_mfma_f32_16x16x32_bf16 v[40:43], v[192:195], v[200:203], v[40:43]
	v_mfma_f32_16x16x32_bf16 v[32:35], v[184:187], v[208:211], v[32:35]
	v_mfma_f32_16x16x32_bf16 v[24:27], v[192:195], v[208:211], v[24:27]
	v_mfma_f32_16x16x32_bf16 v[16:19], v[184:187], v[216:219], v[16:19]
	v_mfma_f32_16x16x32_bf16 v[8:11], v[192:195], v[216:219], v[8:11]
	v_mfma_f32_16x16x32_bf16 v[4:7], v[184:187], v[224:227], v[4:7]
	v_mfma_f32_16x16x32_bf16 v[0:3], v[192:195], v[224:227], v[0:3]
	s_setprio 0
	s_barrier
	s_add_i32 s48, s48, 2
	s_add_u32 s20, s20, 0x100
	s_addc_u32 s21, s21, 0
	s_add_u32 s46, s46, 0x100
	s_addc_u32 s47, s47, 0
	s_cmp_gt_u32 s48, 29
	s_cbranch_scc0 .LBB0_1181
	s_nop 0
	v_readfirstlane_b32 s7, v172
	s_nop 3
	s_lshr_b32 s7, s7, 6
	s_cmp_ge_u32 s7, 4
	s_cbranch_scc0 .Lprio_k4
	s_setprio 1

; #define PG8_STAGE(bufoff, gbase, voff) do { _Pragma("unroll") for (int _i = 0; _i < 2; ++_i) \
;         __builtin_amdgcn_global_load_lds((const unsigned*)((const char*)(gbase) + (voff)[_i]), (PG8_LAS unsigned*)(lds + (bufoff) + ldsw + _i * 8192), 16, 0, 0); } while (0)
; #define PG8_LDA(dst, b, h) do { _Pragma("unroll") for (int m = 0; m < 4; ++m) _Pragma("unroll") for (int k = 0; k < 2; ++k) dst[m][k] = *(const PG8_LAS bf16x8*)(lds + PG8_SA(b, h) + aoff + m * 2048 + k * 1024); } while (0)
; #define PG8_LDB(dst, b, h) do { _Pragma("unroll") for (int n = 0; n < 2; ++n) _Pragma("unroll") for (int k = 0; k < 2; ++k) dst[n][k] = *(const PG8_LAS bf16x8*)(lds + PG8_SB(b, h) + boff + n * 2048 + k * 1024); } while (0)
; #define PG8_MMA(ai, bj, At, Bt) do { __builtin_amdgcn_s_setprio(1); _Pragma("unroll") for (int m = 0; m < 4; ++m) _Pragma("unroll") for (int n = 0; n < 2; ++n) _Pragma("unroll") for (int k = 0; k < 2; ++k) \
;         acc[ai][bj][m][n] = __builtin_amdgcn_mfma_f32_16x16x32_bf16(Bt[n][k], At[m][k], acc[ai][bj][m][n], 0, 0, 0); __builtin_amdgcn_s_setprio(0); } while (0)
; #define PG8_WAIT_V(n) asm volatile("s_waitcnt vmcnt(" #n ")" ::: "memory")
; #define PG8_WAIT_L(n) asm volatile("s_waitcnt lgkmcnt(" #n ")" ::: "memory")
; template <class Epi, class Sched, bool ALIGN_EPI = false, bool SP2 = false>
; __device__ __forceinline__ void gemm_phase(PG8_LAS unsigned char* lds, const Gemm g, const Sched& S, const Epi& E) {
;     ...
;             const bool last = (t == nt - 2);
;             const char* a1 = cA + (size_t)(t + 1) * kstep;
;             const char* a2 = last ? nA : cA + (size_t)(t + 2) * kstep; const char* b2 = last ? nB : cB + (size_t)(t + 2) * kstep;
;             const char* a3 = a2 + kstep; const char* b3 = b2 + kstep;
;             if (last && has_next) S.a_ready(nxt);
;             if constexpr (SP2) {
;             PG8_LDB(B0, 0, 0); PG8_LDB(B1, 0, 1); PG8_SCHED; PG8_LDA(At, 0, 0); PG8_STAGE(PG8_SA(1, 1), a1 + hstep, voffA);
;             PG8_WAIT_V(8); PG8_WAIT_L(0); PG8_BAR; PG8_MMA(0, 0, At, B0); PG8_MMA(0, 1, At, B1); PG8_BAR; PG8_SCHED;
;             PG8_LDA(At, 0, 1); PG8_STAGE(PG8_SB(0, 0), b2, voffB); PG8_STAGE(PG8_SB(0, 1), b2 + hstep, voffB); PG8_STAGE(PG8_SA(0, 0), a2, voffA);
;             PG8_WAIT_V(8); PG8_WAIT_L(0); PG8_BAR; PG8_MMA(1, 0, At, B0); PG8_MMA(1, 1, At, B1); PG8_BAR; PG8_SCHED;
.LBB0_1457:
	ds_read_b128 v[142:145], v151
	ds_read_b128 v[154:157], v151 offset:1024
	ds_read_b128 v[158:161], v151 offset:2048
	ds_read_b128 v[162:165], v151 offset:3072
	ds_read_b128 v[166:169], v152
	ds_read_b128 v[178:181], v152 offset:1024
	ds_read_b128 v[182:185], v152 offset:2048
	ds_read_b128 v[186:189], v152 offset:3072
	s_add_u32 s24, s22, 0x100
	s_addc_u32 s25, s23, 0
	s_cmp_eq_u32 s47, 28
	s_cselect_b32 s29, s15, s25
	s_cselect_b32 s28, s21, s24
	s_cselect_b32 s27, s13, s46
	s_cselect_b32 s26, s44, s45
	v_lshl_add_u64 v[146:147], s[22:23], 0, v[134:135]
	s_add_i32 m0, s34, 0xc000
	ds_read_b128 v[190:193], v153
	ds_read_b128 v[194:197], v153 offset:1024
	ds_read_b128 v[198:201], v153 offset:2048
	ds_read_b128 v[202:205], v153 offset:3072
	ds_read_b128 v[206:209], v153 offset:4096
	ds_read_b128 v[210:213], v153 offset:5120
	ds_read_b128 v[214:217], v153 offset:6144
	ds_read_b128 v[218:221], v153 offset:7168
	global_load_lds_dwordx4 v[146:147], off
	v_lshl_add_u64 v[146:147], s[22:23], 0, v[136:137]
	s_add_i32 m0, s34, 0xe000
	s_nop 0
	global_load_lds_dwordx4 v[146:147], off
	s_waitcnt vmcnt(8)
	s_waitcnt lgkmcnt(0)
	s_barrier
	s_setprio 1
	s_waitcnt lgkmcnt(0)
	v_mfma_f32_16x16x32_bf16 v[124:127], v[142:145], v[190:193], v[124:127]
	v_mfma_f32_16x16x32_bf16 v[120:123], v[158:161], v[190:193], v[120:123]
	v_mfma_f32_16x16x32_bf16 v[108:111], v[142:145], v[198:201], v[108:111]
	v_mfma_f32_16x16x32_bf16 v[104:107], v[158:161], v[198:201], v[104:107]
	v_mfma_f32_16x16x32_bf16 v[92:95], v[142:145], v[206:209], v[92:95]
	v_mfma_f32_16x16x32_bf16 v[88:91], v[158:161], v[206:209], v[88:91]
	v_mfma_f32_16x16x32_bf16 v[76:79], v[142:145], v[214:217], v[76:79]
	v_mfma_f32_16x16x32_bf16 v[72:75], v[158:161], v[214:217], v[72:75]
	v_mfma_f32_16x16x32_bf16 v[124:127], v[154:157], v[194:197], v[124:127]
	v_mfma_f32_16x16x32_bf16 v[120:123], v[162:165], v[194:197], v[120:123]
	v_mfma_f32_16x16x32_bf16 v[108:111], v[154:157], v[202:205], v[108:111]
	v_mfma_f32_16x16x32_bf16 v[104:107], v[162:165], v[202:205], v[104:107]
	v_mfma_f32_16x16x32_bf16 v[92:95], v[154:157], v[210:213], v[92:95]
	v_mfma_f32_16x16x32_bf16 v[88:91], v[162:165], v[210:213], v[88:91]
	v_mfma_f32_16x16x32_bf16 v[76:79], v[154:157], v[218:221], v[76:79]
	v_mfma_f32_16x16x32_bf16 v[72:75], v[162:165], v[218:221], v[72:75]
	s_setprio 0
	s_setprio 1
	v_mfma_f32_16x16x32_bf16 v[116:119], v[166:169], v[190:193], v[116:119]
	v_mfma_f32_16x16x32_bf16 v[112:115], v[182:185], v[190:193], v[112:115]
	v_mfma_f32_16x16x32_bf16 v[100:103], v[166:169], v[198:201], v[100:103]
	v_mfma_f32_16x16x32_bf16 v[96:99], v[182:185], v[198:201], v[96:99]
	v_mfma_f32_16x16x32_bf16 v[84:87], v[166:169], v[206:209], v[84:87]
	v_mfma_f32_16x16x32_bf16 v[80:83], v[182:185], v[206:209], v[80:83]
	v_mfma_f32_16x16x32_bf16 v[68:71], v[166:169], v[214:217], v[68:71]
	v_mfma_f32_16x16x32_bf16 v[64:67], v[182:185], v[214:217], v[64:67]
	v_mfma_f32_16x16x32_bf16 v[116:119], v[178:181], v[194:197], v[116:119]
	v_mfma_f32_16x16x32_bf16 v[112:115], v[186:189], v[194:197], v[112:115]
	v_mfma_f32_16x16x32_bf16 v[100:103], v[178:181], v[202:205], v[100:103]
	v_mfma_f32_16x16x32_bf16 v[96:99], v[186:189], v[202:205], v[96:99]
	v_mfma_f32_16x16x32_bf16 v[84:87], v[178:181], v[210:213], v[84:87]
	v_mfma_f32_16x16x32_bf16 v[80:83], v[186:189], v[210:213], v[80:83]
	v_mfma_f32_16x16x32_bf16 v[68:71], v[178:181], v[218:221], v[68:71]
	v_mfma_f32_16x16x32_bf16 v[64:67], v[186:189], v[218:221], v[64:67]
	s_setprio 0
	s_barrier
	s_add_i32 s22, s41, s33
	v_lshl_add_u64 v[146:147], s[26:27], 0, v[130:131]
	s_mov_b32 m0, s22
	ds_read_b128 v[190:193], v153 offset:16384
	ds_read_b128 v[194:197], v153 offset:17408
	ds_read_b128 v[198:201], v153 offset:18432
	ds_read_b128 v[202:205], v153 offset:19456
	ds_read_b128 v[206:209], v153 offset:20480
	ds_read_b128 v[210:213], v153 offset:21504
	ds_read_b128 v[214:217], v153 offset:22528
	ds_read_b128 v[218:221], v153 offset:23552
	global_load_lds_dwordx4 v[146:147], off
	s_add_i32 m0, s22, 0x2000
	s_add_u32 s22, s26, 0x80000
	v_lshl_add_u64 v[170:171], s[26:27], 0, v[132:133]
	s_addc_u32 s23, s27, 0
	s_add_i32 s48, s42, s33
	global_load_lds_dwordx4 v[170:171], off
	v_lshl_add_u64 v[222:223], s[22:23], 0, v[130:131]
	s_mov_b32 m0, s48
	v_lshl_add_u64 v[224:225], s[28:29], 0, v[132:133]
	global_load_lds_dwordx4 v[222:223], off
	v_lshl_add_u64 v[222:223], s[22:23], 0, v[132:133]
	s_add_i32 m0, s48, 0x2000
	s_nop 0
	global_load_lds_dwordx4 v[222:223], off
	v_lshl_add_u64 v[222:223], s[28:29], 0, v[130:131]
	s_mov_b32 m0, s34
	s_nop 0
	global_load_lds_dwordx4 v[222:223], off
	s_mov_b32 m0, s35
	s_nop 0
	global_load_lds_dwordx4 v[224:225], off
	s_waitcnt vmcnt(8)
	s_waitcnt lgkmcnt(0)
	s_barrier
; #define PG8_STAGE(bufoff, gbase, voff) do { _Pragma("unroll") for (int _i = 0; _i < 2; ++_i) \
;         __builtin_amdgcn_global_load_lds((const unsigned*)((const char*)(gbase) + (voff)[_i]), (PG8_LAS unsigned*)(lds + (bufoff) + ldsw + _i * 8192), 16, 0, 0); } while (0)
; #define PG8_LDA(dst, b, h) do { _Pragma("unroll") for (int m = 0; m < 4; ++m) _Pragma("unroll") for (int k = 0; k < 2; ++k) dst[m][k] = *(const PG8_LAS bf16x8*)(lds + PG8_SA(b, h) + aoff + m * 2048 + k * 1024); } while (0)
; #define PG8_LDB(dst, b, h) do { _Pragma("unroll") for (int n = 0; n < 2; ++n) _Pragma("unroll") for (int k = 0; k < 2; ++k) dst[n][k] = *(const PG8_LAS bf16x8*)(lds + PG8_SB(b, h) + boff + n * 2048 + k * 1024); } while (0)
; #define PG8_MMA(ai, bj, At, Bt) do { __builtin_amdgcn_s_setprio(1); _Pragma("unroll") for (int m = 0; m < 4; ++m) _Pragma("unroll") for (int n = 0; n < 2; ++n) _Pragma("unroll") for (int k = 0; k < 2; ++k) \
;         acc[ai][bj][m][n] = __builtin_amdgcn_mfma_f32_16x16x32_bf16(Bt[n][k], At[m][k], acc[ai][bj][m][n], 0, 0, 0); __builtin_amdgcn_s_setprio(0); } while (0)
; #define PG8_WAIT_V(n) asm volatile("s_waitcnt vmcnt(" #n ")" ::: "memory")
; #define PG8_WAIT_L(n) asm volatile("s_waitcnt lgkmcnt(" #n ")" ::: "memory")
; #define PG8_BAR __builtin_amdgcn_s_barrier()
; #define PG8_SCHED __builtin_amdgcn_sched_barrier(0)
; template <class Epi, class Sched, bool ALIGN_EPI = false, bool SP2 = false>
; __device__ __forceinline__ void gemm_phase(PG8_LAS unsigned char* lds, const Gemm g, const Sched& S, const Epi& E) {
;     ...
;             PG8_WAIT_V(8); PG8_WAIT_L(0); PG8_BAR; PG8_MMA(1, 0, At, B0); PG8_MMA(1, 1, At, B1); PG8_BAR; PG8_SCHED;
;             PG8_LDB(B0, 1, 0); PG8_LDB(B1, 1, 1); PG8_SCHED; PG8_LDA(At, 1, 0); PG8_STAGE(PG8_SA(0, 1), a2 + hstep, voffA);
;             PG8_WAIT_V(8); PG8_WAIT_L(0); PG8_BAR; PG8_MMA(0, 0, At, B0); PG8_MMA(0, 1, At, B1); PG8_BAR; PG8_SCHED;
	s_setprio 1
	s_waitcnt lgkmcnt(0)
	v_mfma_f32_16x16x32_bf16 v[60:63], v[142:145], v[190:193], v[60:63]
	v_mfma_f32_16x16x32_bf16 v[56:59], v[158:161], v[190:193], v[56:59]
	v_mfma_f32_16x16x32_bf16 v[44:47], v[142:145], v[198:201], v[44:47]
	v_mfma_f32_16x16x32_bf16 v[40:43], v[158:161], v[198:201], v[40:43]
	v_mfma_f32_16x16x32_bf16 v[28:31], v[142:145], v[206:209], v[28:31]
	v_mfma_f32_16x16x32_bf16 v[24:27], v[158:161], v[206:209], v[24:27]
	v_mfma_f32_16x16x32_bf16 v[12:15], v[142:145], v[214:217], v[12:15]
	v_mfma_f32_16x16x32_bf16 v[8:11], v[158:161], v[214:217], v[8:11]
	v_mfma_f32_16x16x32_bf16 v[60:63], v[154:157], v[194:197], v[60:63]
	v_mfma_f32_16x16x32_bf16 v[56:59], v[162:165], v[194:197], v[56:59]
	v_mfma_f32_16x16x32_bf16 v[44:47], v[154:157], v[202:205], v[44:47]
	v_mfma_f32_16x16x32_bf16 v[40:43], v[162:165], v[202:205], v[40:43]
	v_mfma_f32_16x16x32_bf16 v[28:31], v[154:157], v[210:213], v[28:31]
	v_mfma_f32_16x16x32_bf16 v[24:27], v[162:165], v[210:213], v[24:27]
	v_mfma_f32_16x16x32_bf16 v[12:15], v[154:157], v[218:221], v[12:15]
	v_mfma_f32_16x16x32_bf16 v[8:11], v[162:165], v[218:221], v[8:11]
	s_setprio 0
	s_setprio 1
	v_mfma_f32_16x16x32_bf16 v[52:55], v[166:169], v[190:193], v[52:55]
	v_mfma_f32_16x16x32_bf16 v[48:51], v[182:185], v[190:193], v[48:51]
	v_mfma_f32_16x16x32_bf16 v[36:39], v[166:169], v[198:201], v[36:39]
	v_mfma_f32_16x16x32_bf16 v[32:35], v[182:185], v[198:201], v[32:35]
	v_mfma_f32_16x16x32_bf16 v[20:23], v[166:169], v[206:209], v[20:23]
	v_mfma_f32_16x16x32_bf16 v[16:19], v[182:185], v[206:209], v[16:19]
	v_mfma_f32_16x16x32_bf16 v[4:7], v[166:169], v[214:217], v[4:7]
	v_mfma_f32_16x16x32_bf16 v[0:3], v[182:185], v[214:217], v[0:3]
	v_mfma_f32_16x16x32_bf16 v[52:55], v[178:181], v[194:197], v[52:55]
	v_mfma_f32_16x16x32_bf16 v[48:51], v[186:189], v[194:197], v[48:51]
	v_mfma_f32_16x16x32_bf16 v[36:39], v[178:181], v[202:205], v[36:39]
	v_mfma_f32_16x16x32_bf16 v[32:35], v[186:189], v[202:205], v[32:35]
	v_mfma_f32_16x16x32_bf16 v[20:23], v[178:181], v[210:213], v[20:23]
	v_mfma_f32_16x16x32_bf16 v[16:19], v[186:189], v[210:213], v[16:19]
	v_mfma_f32_16x16x32_bf16 v[4:7], v[178:181], v[218:221], v[4:7]
	v_mfma_f32_16x16x32_bf16 v[0:3], v[186:189], v[218:221], v[0:3]
	s_setprio 0
	s_barrier
	s_add_i32 s48, 0, 0x18000
	s_add_i32 s49, 0, 0x1c000
	v_add_u32_e32 v162, s48, v149
	v_add_u32_e32 v186, s49, v149
	ds_read_b128 v[142:145], v162
	ds_read_b128 v[154:157], v162 offset:1024
	ds_read_b128 v[158:161], v162 offset:2048
	ds_read_b128 v[162:165], v162 offset:3072
	ds_read_b128 v[166:169], v186
	ds_read_b128 v[178:181], v186 offset:1024
	ds_read_b128 v[182:185], v186 offset:2048
	ds_read_b128 v[186:189], v186 offset:3072
	s_add_u32 s22, s28, 0x80000
	s_addc_u32 s23, s29, 0
	s_mov_b32 m0, s36
	v_lshl_add_u64 v[226:227], s[22:23], 0, v[130:131]
	ds_read_b128 v[190:193], v153 offset:32768
	ds_read_b128 v[194:197], v153 offset:33792
	ds_read_b128 v[198:201], v153 offset:34816
	ds_read_b128 v[202:205], v153 offset:35840
	ds_read_b128 v[206:209], v153 offset:36864
	ds_read_b128 v[210:213], v153 offset:37888
	ds_read_b128 v[214:217], v153 offset:38912
	ds_read_b128 v[218:221], v153 offset:39936
	global_load_lds_dwordx4 v[226:227], off
	v_lshl_add_u64 v[226:227], s[22:23], 0, v[132:133]
	s_mov_b32 m0, s37
	s_nop 0
	global_load_lds_dwordx4 v[226:227], off
	s_waitcnt vmcnt(8)
	s_waitcnt lgkmcnt(0)
	s_barrier
	s_setprio 1
	s_waitcnt lgkmcnt(0)
	v_mfma_f32_16x16x32_bf16 v[124:127], v[142:145], v[190:193], v[124:127]
	v_mfma_f32_16x16x32_bf16 v[120:123], v[158:161], v[190:193], v[120:123]
	v_mfma_f32_16x16x32_bf16 v[108:111], v[142:145], v[198:201], v[108:111]
	v_mfma_f32_16x16x32_bf16 v[104:107], v[158:161], v[198:201], v[104:107]
	v_mfma_f32_16x16x32_bf16 v[92:95], v[142:145], v[206:209], v[92:95]
	v_mfma_f32_16x16x32_bf16 v[88:91], v[158:161], v[206:209], v[88:91]
	v_mfma_f32_16x16x32_bf16 v[76:79], v[142:145], v[214:217], v[76:79]
	v_mfma_f32_16x16x32_bf16 v[72:75], v[158:161], v[214:217], v[72:75]
	v_mfma_f32_16x16x32_bf16 v[124:127], v[154:157], v[194:197], v[124:127]
	v_mfma_f32_16x16x32_bf16 v[120:123], v[162:165], v[194:197], v[120:123]
	v_mfma_f32_16x16x32_bf16 v[108:111], v[154:157], v[202:205], v[108:111]
	v_mfma_f32_16x16x32_bf16 v[104:107], v[162:165], v[202:205], v[104:107]
	v_mfma_f32_16x16x32_bf16 v[92:95], v[154:157], v[210:213], v[92:95]
	v_mfma_f32_16x16x32_bf16 v[88:91], v[162:165], v[210:213], v[88:91]
	v_mfma_f32_16x16x32_bf16 v[76:79], v[154:157], v[218:221], v[76:79]
	v_mfma_f32_16x16x32_bf16 v[72:75], v[162:165], v[218:221], v[72:75]
	s_setprio 0
	s_setprio 1
	v_mfma_f32_16x16x32_bf16 v[116:119], v[166:169], v[190:193], v[116:119]
	v_mfma_f32_16x16x32_bf16 v[112:115], v[182:185], v[190:193], v[112:115]
	v_mfma_f32_16x16x32_bf16 v[100:103], v[166:169], v[198:201], v[100:103]
	v_mfma_f32_16x16x32_bf16 v[96:99], v[182:185], v[198:201], v[96:99]
	v_mfma_f32_16x16x32_bf16 v[84:87], v[166:169], v[206:209], v[84:87]
	v_mfma_f32_16x16x32_bf16 v[80:83], v[182:185], v[206:209], v[80:83]
	v_mfma_f32_16x16x32_bf16 v[68:71], v[166:169], v[214:217], v[68:71]
	v_mfma_f32_16x16x32_bf16 v[64:67], v[182:185], v[214:217], v[64:67]
	v_mfma_f32_16x16x32_bf16 v[116:119], v[178:181], v[194:197], v[116:119]
	v_mfma_f32_16x16x32_bf16 v[112:115], v[186:189], v[194:197], v[112:115]
	v_mfma_f32_16x16x32_bf16 v[100:103], v[178:181], v[202:205], v[100:103]
	v_mfma_f32_16x16x32_bf16 v[96:99], v[186:189], v[202:205], v[96:99]
	v_mfma_f32_16x16x32_bf16 v[84:87], v[178:181], v[210:213], v[84:87]
	v_mfma_f32_16x16x32_bf16 v[80:83], v[186:189], v[210:213], v[80:83]
	v_mfma_f32_16x16x32_bf16 v[68:71], v[178:181], v[218:221], v[68:71]
	v_mfma_f32_16x16x32_bf16 v[64:67], v[186:189], v[218:221], v[64:67]
	s_setprio 0
	s_barrier
; #define PG8_STAGE(bufoff, gbase, voff) do { _Pragma("unroll") for (int _i = 0; _i < 2; ++_i) \
;         __builtin_amdgcn_global_load_lds((const unsigned*)((const char*)(gbase) + (voff)[_i]), (PG8_LAS unsigned*)(lds + (bufoff) + ldsw + _i * 8192), 16, 0, 0); } while (0)
; #define PG8_LDA(dst, b, h) do { _Pragma("unroll") for (int m = 0; m < 4; ++m) _Pragma("unroll") for (int k = 0; k < 2; ++k) dst[m][k] = *(const PG8_LAS bf16x8*)(lds + PG8_SA(b, h) + aoff + m * 2048 + k * 1024); } while (0)
; #define PG8_LDB(dst, b, h) do { _Pragma("unroll") for (int n = 0; n < 2; ++n) _Pragma("unroll") for (int k = 0; k < 2; ++k) dst[n][k] = *(const PG8_LAS bf16x8*)(lds + PG8_SB(b, h) + boff + n * 2048 + k * 1024); } while (0)
; template <class Epi, class Sched, bool ALIGN_EPI = false, bool SP2 = false>
; __device__ __forceinline__ void gemm_phase(PG8_LAS unsigned char* lds, const Gemm g, const Sched& S, const Epi& E) {
;     ...
;         for (int t = 0; t < nt; t += 2) {
;             const bool last = (t == nt - 2);
;             const char* a1 = cA + (size_t)(t + 1) * kstep;
;             const char* a2 = last ? nA : cA + (size_t)(t + 2) * kstep; const char* b2 = last ? nB : cB + (size_t)(t + 2) * kstep;
;             const char* a3 = a2 + kstep; const char* b3 = b2 + kstep;
;             if (last && has_next) S.a_ready(nxt);
;             if constexpr (SP2) {
;             PG8_LDB(B0, 0, 0); PG8_LDB(B1, 0, 1); PG8_SCHED; PG8_LDA(At, 0, 0); PG8_STAGE(PG8_SA(1, 1), a1 + hstep, voffA);
;             PG8_WAIT_V(8); PG8_WAIT_L(0); PG8_BAR; PG8_MMA(0, 0, At, B0); PG8_MMA(0, 1, At, B1); PG8_BAR; PG8_SCHED;
;             PG8_LDA(At, 0, 1); PG8_STAGE(PG8_SB(0, 0), b2, voffB); PG8_STAGE(PG8_SB(0, 1), b2 + hstep, voffB); PG8_STAGE(PG8_SA(0, 0), a2, voffA);
;             PG8_WAIT_V(8); PG8_WAIT_L(0); PG8_BAR; PG8_MMA(1, 0, At, B0); PG8_MMA(1, 1, At, B1); PG8_BAR; PG8_SCHED;
;             PG8_LDB(B0, 1, 0); PG8_LDB(B1, 1, 1); PG8_SCHED; PG8_LDA(At, 1, 0); PG8_STAGE(PG8_SA(0, 1), a2 + hstep, voffA);
;             PG8_WAIT_V(8); PG8_WAIT_L(0); PG8_BAR; PG8_MMA(0, 0, At, B0); PG8_MMA(0, 1, At, B1); PG8_BAR; PG8_SCHED;
;             PG8_LDA(At, 1, 1); PG8_STAGE(PG8_SB(1, 0), b3, voffB); PG8_STAGE(PG8_SB(1, 1), b3 + hstep, voffB); PG8_STAGE(PG8_SA(1, 0), a3, voffA);
;             PG8_WAIT_V(8); PG8_WAIT_L(0); PG8_BAR; PG8_MMA(1, 0, At, B0); PG8_MMA(1, 1, At, B1); PG8_BAR; PG8_SCHED;
	s_add_i32 s22, s48, s33
	v_lshl_add_u64 v[146:147], v[146:147], 0, s[4:5]
	s_mov_b32 m0, s22
	ds_read_b128 v[190:193], v153 offset:49152
	ds_read_b128 v[194:197], v153 offset:50176
	ds_read_b128 v[198:201], v153 offset:51200
	ds_read_b128 v[202:205], v153 offset:52224
	ds_read_b128 v[206:209], v153 offset:53248
	ds_read_b128 v[210:213], v153 offset:54272
	ds_read_b128 v[214:217], v153 offset:55296
	ds_read_b128 v[218:221], v153 offset:56320
	global_load_lds_dwordx4 v[146:147], off
	s_add_i32 m0, s22, 0x2000
	s_add_u32 s22, s26, 0x80080
	v_lshl_add_u64 v[146:147], v[170:171], 0, s[4:5]
	s_addc_u32 s23, s27, 0
	s_add_i32 s26, s49, s33
	global_load_lds_dwordx4 v[146:147], off
	v_lshl_add_u64 v[146:147], s[22:23], 0, v[130:131]
	s_mov_b32 m0, s26
	s_nop 0
	global_load_lds_dwordx4 v[146:147], off
	v_lshl_add_u64 v[146:147], s[22:23], 0, v[132:133]
	s_add_i32 m0, s26, 0x2000
	s_nop 0
	global_load_lds_dwordx4 v[146:147], off
	v_lshl_add_u64 v[146:147], v[222:223], 0, s[4:5]
	s_mov_b32 m0, s39
	s_nop 0
	global_load_lds_dwordx4 v[146:147], off
	v_lshl_add_u64 v[146:147], v[224:225], 0, s[4:5]
	s_mov_b32 m0, s40
	s_nop 0
	global_load_lds_dwordx4 v[146:147], off
	s_waitcnt vmcnt(8)
	s_waitcnt lgkmcnt(0)
	s_barrier
	s_setprio 1
	s_waitcnt lgkmcnt(0)
	v_mfma_f32_16x16x32_bf16 v[60:63], v[142:145], v[190:193], v[60:63]
	v_mfma_f32_16x16x32_bf16 v[56:59], v[158:161], v[190:193], v[56:59]
	v_mfma_f32_16x16x32_bf16 v[44:47], v[142:145], v[198:201], v[44:47]
	v_mfma_f32_16x16x32_bf16 v[40:43], v[158:161], v[198:201], v[40:43]
	v_mfma_f32_16x16x32_bf16 v[28:31], v[142:145], v[206:209], v[28:31]
	v_mfma_f32_16x16x32_bf16 v[24:27], v[158:161], v[206:209], v[24:27]
	v_mfma_f32_16x16x32_bf16 v[12:15], v[142:145], v[214:217], v[12:15]
	v_mfma_f32_16x16x32_bf16 v[8:11], v[158:161], v[214:217], v[8:11]
	v_mfma_f32_16x16x32_bf16 v[60:63], v[154:157], v[194:197], v[60:63]
	v_mfma_f32_16x16x32_bf16 v[56:59], v[162:165], v[194:197], v[56:59]
	v_mfma_f32_16x16x32_bf16 v[44:47], v[154:157], v[202:205], v[44:47]
	v_mfma_f32_16x16x32_bf16 v[40:43], v[162:165], v[202:205], v[40:43]
	v_mfma_f32_16x16x32_bf16 v[28:31], v[154:157], v[210:213], v[28:31]
	v_mfma_f32_16x16x32_bf16 v[24:27], v[162:165], v[210:213], v[24:27]
	v_mfma_f32_16x16x32_bf16 v[12:15], v[154:157], v[218:221], v[12:15]
	v_mfma_f32_16x16x32_bf16 v[8:11], v[162:165], v[218:221], v[8:11]
	s_setprio 0
	s_setprio 1
	v_mfma_f32_16x16x32_bf16 v[52:55], v[166:169], v[190:193], v[52:55]
	v_mfma_f32_16x16x32_bf16 v[48:51], v[182:185], v[190:193], v[48:51]
	v_mfma_f32_16x16x32_bf16 v[36:39], v[166:169], v[198:201], v[36:39]
	v_mfma_f32_16x16x32_bf16 v[32:35], v[182:185], v[198:201], v[32:35]
	v_mfma_f32_16x16x32_bf16 v[20:23], v[166:169], v[206:209], v[20:23]
	v_mfma_f32_16x16x32_bf16 v[16:19], v[182:185], v[206:209], v[16:19]
	v_mfma_f32_16x16x32_bf16 v[4:7], v[166:169], v[214:217], v[4:7]
	v_mfma_f32_16x16x32_bf16 v[0:3], v[182:185], v[214:217], v[0:3]
	v_mfma_f32_16x16x32_bf16 v[52:55], v[178:181], v[194:197], v[52:55]
	v_mfma_f32_16x16x32_bf16 v[48:51], v[186:189], v[194:197], v[48:51]
	v_mfma_f32_16x16x32_bf16 v[36:39], v[178:181], v[202:205], v[36:39]
	v_mfma_f32_16x16x32_bf16 v[32:35], v[186:189], v[202:205], v[32:35]
	v_mfma_f32_16x16x32_bf16 v[20:23], v[178:181], v[210:213], v[20:23]
	v_mfma_f32_16x16x32_bf16 v[16:19], v[186:189], v[210:213], v[16:19]
	v_mfma_f32_16x16x32_bf16 v[4:7], v[178:181], v[218:221], v[4:7]
	v_mfma_f32_16x16x32_bf16 v[0:3], v[186:189], v[218:221], v[0:3]
	s_setprio 0
	s_barrier
	s_add_i32 s47, s47, 2
	s_add_u32 s45, s45, 0x100
	s_addc_u32 s46, s46, 0
	s_cmp_gt_u32 s47, 29
	s_mov_b64 s[22:23], s[24:25]
	s_cbranch_scc0 .LBB0_1457
	s_nop 0
	v_readfirstlane_b32 s21, v172
	s_nop 3
	s_lshr_b32 s21, s21, 6
	s_cmp_ge_u32 s21, 4
	s_cbranch_scc0 .Lprio_k5
	s_setprio 1

; #define PG8_STAGE(bufoff, gbase, voff) do { _Pragma("unroll") for (int _i = 0; _i < 2; ++_i) \
;         __builtin_amdgcn_global_load_lds((const unsigned*)((const char*)(gbase) + (voff)[_i]), (PG8_LAS unsigned*)(lds + (bufoff) + ldsw + _i * 8192), 16, 0, 0); } while (0)
; #define PG8_LDA(dst, b, h) do { _Pragma("unroll") for (int m = 0; m < 4; ++m) _Pragma("unroll") for (int k = 0; k < 2; ++k) dst[m][k] = *(const PG8_LAS bf16x8*)(lds + PG8_SA(b, h) + aoff + m * 2048 + k * 1024); } while (0)
; #define PG8_LDB(dst, b, h) do { _Pragma("unroll") for (int n = 0; n < 2; ++n) _Pragma("unroll") for (int k = 0; k < 2; ++k) dst[n][k] = *(const PG8_LAS bf16x8*)(lds + PG8_SB(b, h) + boff + n * 2048 + k * 1024); } while (0)
; #define PG8_MMA(ai, bj, At, Bt) do { __builtin_amdgcn_s_setprio(1); _Pragma("unroll") for (int m = 0; m < 4; ++m) _Pragma("unroll") for (int n = 0; n < 2; ++n) _Pragma("unroll") for (int k = 0; k < 2; ++k) \
;         acc[ai][bj][m][n] = __builtin_amdgcn_mfma_f32_16x16x32_bf16(Bt[n][k], At[m][k], acc[ai][bj][m][n], 0, 0, 0); __builtin_amdgcn_s_setprio(0); } while (0)
; #define PG8_WAIT_V(n) asm volatile("s_waitcnt vmcnt(" #n ")" ::: "memory")
; #define PG8_WAIT_L(n) asm volatile("s_waitcnt lgkmcnt(" #n ")" ::: "memory")
; template <class Epi, class Sched, bool ALIGN_EPI = false, bool SP2 = false>
; __device__ __forceinline__ void gemm_phase(PG8_LAS unsigned char* lds, const Gemm g, const Sched& S, const Epi& E) {
;     ...
;             const bool last = (t == nt - 2);
;             const char* a1 = cA + (size_t)(t + 1) * kstep;
;             const char* a2 = last ? nA : cA + (size_t)(t + 2) * kstep; const char* b2 = last ? nB : cB + (size_t)(t + 2) * kstep;
;             const char* a3 = a2 + kstep; const char* b3 = b2 + kstep;
;             if (last && has_next) S.a_ready(nxt);
;             if constexpr (SP2) {
;             PG8_LDB(B0, 0, 0); PG8_LDB(B1, 0, 1); PG8_SCHED; PG8_LDA(At, 0, 0); PG8_STAGE(PG8_SA(1, 1), a1 + hstep, voffA);
;             PG8_WAIT_V(8); PG8_WAIT_L(0); PG8_BAR; PG8_MMA(0, 0, At, B0); PG8_MMA(0, 1, At, B1); PG8_BAR; PG8_SCHED;
;             PG8_LDA(At, 0, 1); PG8_STAGE(PG8_SB(0, 0), b2, voffB); PG8_STAGE(PG8_SB(0, 1), b2 + hstep, voffB); PG8_STAGE(PG8_SA(0, 0), a2, voffA);
;             PG8_WAIT_V(8); PG8_WAIT_L(0); PG8_BAR; PG8_MMA(1, 0, At, B0); PG8_MMA(1, 1, At, B1); PG8_BAR; PG8_SCHED;
.LBB0_1712:
	ds_read_b128 v[144:147], v156
	ds_read_b128 v[148:151], v156 offset:1024
	ds_read_b128 v[160:163], v156 offset:2048
	ds_read_b128 v[164:167], v156 offset:3072
	ds_read_b128 v[168:171], v157
	ds_read_b128 v[174:177], v157 offset:1024
	ds_read_b128 v[178:181], v157 offset:2048
	ds_read_b128 v[182:185], v157 offset:3072
	s_add_u32 s20, s18, 0xfff80080
	s_addc_u32 s21, s19, -1
	s_cmp_eq_u32 s44, 28
	s_cselect_b32 s23, s11, s21
	s_cselect_b32 s22, s40, s20
	s_cselect_b32 s21, s9, s43
	s_cselect_b32 s20, s41, s42
	v_lshl_add_u64 v[218:219], s[18:19], 0, v[136:137]
	s_add_i32 m0, s17, 0xc000
	ds_read_b128 v[186:189], v158
	ds_read_b128 v[190:193], v158 offset:1024
	ds_read_b128 v[194:197], v158 offset:2048
	ds_read_b128 v[198:201], v158 offset:3072
	ds_read_b128 v[202:205], v158 offset:4096
	ds_read_b128 v[206:209], v158 offset:5120
	ds_read_b128 v[210:213], v158 offset:6144
	ds_read_b128 v[214:217], v158 offset:7168
	global_load_lds_dwordx4 v[218:219], off
	v_lshl_add_u64 v[218:219], s[18:19], 0, v[138:139]
	s_add_i32 m0, s17, 0xe000
	s_nop 0
	global_load_lds_dwordx4 v[218:219], off
	s_waitcnt vmcnt(8)
	s_waitcnt lgkmcnt(0)
	s_barrier
	s_setprio 1
	s_waitcnt lgkmcnt(0)
	v_mfma_f32_16x16x32_bf16 v[124:127], v[144:147], v[186:189], v[124:127]
	v_mfma_f32_16x16x32_bf16 v[120:123], v[160:163], v[186:189], v[120:123]
	v_mfma_f32_16x16x32_bf16 v[108:111], v[144:147], v[194:197], v[108:111]
	v_mfma_f32_16x16x32_bf16 v[104:107], v[160:163], v[194:197], v[104:107]
	v_mfma_f32_16x16x32_bf16 v[92:95], v[144:147], v[202:205], v[92:95]
	v_mfma_f32_16x16x32_bf16 v[88:91], v[160:163], v[202:205], v[88:91]
	v_mfma_f32_16x16x32_bf16 v[76:79], v[144:147], v[210:213], v[76:79]
	v_mfma_f32_16x16x32_bf16 v[72:75], v[160:163], v[210:213], v[72:75]
	v_mfma_f32_16x16x32_bf16 v[124:127], v[148:151], v[190:193], v[124:127]
	v_mfma_f32_16x16x32_bf16 v[120:123], v[164:167], v[190:193], v[120:123]
	v_mfma_f32_16x16x32_bf16 v[108:111], v[148:151], v[198:201], v[108:111]
	v_mfma_f32_16x16x32_bf16 v[104:107], v[164:167], v[198:201], v[104:107]
	v_mfma_f32_16x16x32_bf16 v[92:95], v[148:151], v[206:209], v[92:95]
	v_mfma_f32_16x16x32_bf16 v[88:91], v[164:167], v[206:209], v[88:91]
	v_mfma_f32_16x16x32_bf16 v[76:79], v[148:151], v[214:217], v[76:79]
	v_mfma_f32_16x16x32_bf16 v[72:75], v[164:167], v[214:217], v[72:75]
	s_setprio 0
	s_setprio 1
	v_mfma_f32_16x16x32_bf16 v[116:119], v[168:171], v[186:189], v[116:119]
	v_mfma_f32_16x16x32_bf16 v[112:115], v[178:181], v[186:189], v[112:115]
	v_mfma_f32_16x16x32_bf16 v[100:103], v[168:171], v[194:197], v[100:103]
	v_mfma_f32_16x16x32_bf16 v[96:99], v[178:181], v[194:197], v[96:99]
	v_mfma_f32_16x16x32_bf16 v[84:87], v[168:171], v[202:205], v[84:87]
	v_mfma_f32_16x16x32_bf16 v[80:83], v[178:181], v[202:205], v[80:83]
	v_mfma_f32_16x16x32_bf16 v[68:71], v[168:171], v[210:213], v[68:71]
	v_mfma_f32_16x16x32_bf16 v[64:67], v[178:181], v[210:213], v[64:67]
	v_mfma_f32_16x16x32_bf16 v[116:119], v[174:177], v[190:193], v[116:119]
	v_mfma_f32_16x16x32_bf16 v[112:115], v[182:185], v[190:193], v[112:115]
	v_mfma_f32_16x16x32_bf16 v[100:103], v[174:177], v[198:201], v[100:103]
	v_mfma_f32_16x16x32_bf16 v[96:99], v[182:185], v[198:201], v[96:99]
	v_mfma_f32_16x16x32_bf16 v[84:87], v[174:177], v[206:209], v[84:87]
	v_mfma_f32_16x16x32_bf16 v[80:83], v[182:185], v[206:209], v[80:83]
	v_mfma_f32_16x16x32_bf16 v[68:71], v[174:177], v[214:217], v[68:71]
	v_mfma_f32_16x16x32_bf16 v[64:67], v[182:185], v[214:217], v[64:67]
	s_setprio 0
	s_barrier
	s_add_i32 s45, s34, s26
	v_lshl_add_u64 v[218:219], s[20:21], 0, v[132:133]
	s_mov_b32 m0, s45
	ds_read_b128 v[186:189], v158 offset:16384
	ds_read_b128 v[190:193], v158 offset:17408
	ds_read_b128 v[194:197], v158 offset:18432
	ds_read_b128 v[198:201], v158 offset:19456
	ds_read_b128 v[202:205], v158 offset:20480
	ds_read_b128 v[206:209], v158 offset:21504
	ds_read_b128 v[210:213], v158 offset:22528
	ds_read_b128 v[214:217], v158 offset:23552
	global_load_lds_dwordx4 v[218:219], off
	s_add_i32 m0, s45, 0x2000
	s_add_u32 s46, s20, 0x80000
	v_lshl_add_u64 v[220:221], s[20:21], 0, v[128:129]
	s_addc_u32 s47, s21, 0
	s_add_i32 s45, s35, s26
	global_load_lds_dwordx4 v[220:221], off
	v_lshl_add_u64 v[222:223], s[46:47], 0, v[132:133]
	s_mov_b32 m0, s45
	v_lshl_add_u64 v[224:225], s[22:23], 0, v[130:131]
	global_load_lds_dwordx4 v[222:223], off
	v_lshl_add_u64 v[222:223], s[46:47], 0, v[128:129]
	s_add_i32 m0, s45, 0x2000
	s_nop 0
	global_load_lds_dwordx4 v[222:223], off
	v_lshl_add_u64 v[222:223], s[22:23], 0, v[134:135]
	s_mov_b32 m0, s17
	s_nop 0
	global_load_lds_dwordx4 v[222:223], off
	s_mov_b32 m0, s28
	s_nop 0
	global_load_lds_dwordx4 v[224:225], off
	s_waitcnt vmcnt(8)
	s_waitcnt lgkmcnt(0)
	s_barrier
; #define PG8_STAGE(bufoff, gbase, voff) do { _Pragma("unroll") for (int _i = 0; _i < 2; ++_i) \
;         __builtin_amdgcn_global_load_lds((const unsigned*)((const char*)(gbase) + (voff)[_i]), (PG8_LAS unsigned*)(lds + (bufoff) + ldsw + _i * 8192), 16, 0, 0); } while (0)
; #define PG8_LDA(dst, b, h) do { _Pragma("unroll") for (int m = 0; m < 4; ++m) _Pragma("unroll") for (int k = 0; k < 2; ++k) dst[m][k] = *(const PG8_LAS bf16x8*)(lds + PG8_SA(b, h) + aoff + m * 2048 + k * 1024); } while (0)
; #define PG8_LDB(dst, b, h) do { _Pragma("unroll") for (int n = 0; n < 2; ++n) _Pragma("unroll") for (int k = 0; k < 2; ++k) dst[n][k] = *(const PG8_LAS bf16x8*)(lds + PG8_SB(b, h) + boff + n * 2048 + k * 1024); } while (0)
; #define PG8_MMA(ai, bj, At, Bt) do { __builtin_amdgcn_s_setprio(1); _Pragma("unroll") for (int m = 0; m < 4; ++m) _Pragma("unroll") for (int n = 0; n < 2; ++n) _Pragma("unroll") for (int k = 0; k < 2; ++k) \
;         acc[ai][bj][m][n] = __builtin_amdgcn_mfma_f32_16x16x32_bf16(Bt[n][k], At[m][k], acc[ai][bj][m][n], 0, 0, 0); __builtin_amdgcn_s_setprio(0); } while (0)
; #define PG8_WAIT_V(n) asm volatile("s_waitcnt vmcnt(" #n ")" ::: "memory")
; #define PG8_WAIT_L(n) asm volatile("s_waitcnt lgkmcnt(" #n ")" ::: "memory")
; #define PG8_BAR __builtin_amdgcn_s_barrier()
; #define PG8_SCHED __builtin_amdgcn_sched_barrier(0)
; template <class Epi, class Sched, bool ALIGN_EPI = false, bool SP2 = false>
; __device__ __forceinline__ void gemm_phase(PG8_LAS unsigned char* lds, const Gemm g, const Sched& S, const Epi& E) {
;     ...
;             PG8_WAIT_V(8); PG8_WAIT_L(0); PG8_BAR; PG8_MMA(1, 0, At, B0); PG8_MMA(1, 1, At, B1); PG8_BAR; PG8_SCHED;
;             PG8_LDB(B0, 1, 0); PG8_LDB(B1, 1, 1); PG8_SCHED; PG8_LDA(At, 1, 0); PG8_STAGE(PG8_SA(0, 1), a2 + hstep, voffA);
;             PG8_WAIT_V(8); PG8_WAIT_L(0); PG8_BAR; PG8_MMA(0, 0, At, B0); PG8_MMA(0, 1, At, B1); PG8_BAR; PG8_SCHED;
	s_setprio 1
	s_waitcnt lgkmcnt(0)
	v_mfma_f32_16x16x32_bf16 v[60:63], v[144:147], v[186:189], v[60:63]
	v_mfma_f32_16x16x32_bf16 v[56:59], v[160:163], v[186:189], v[56:59]
	v_mfma_f32_16x16x32_bf16 v[44:47], v[144:147], v[194:197], v[44:47]
	v_mfma_f32_16x16x32_bf16 v[40:43], v[160:163], v[194:197], v[40:43]
	v_mfma_f32_16x16x32_bf16 v[28:31], v[144:147], v[202:205], v[28:31]
	v_mfma_f32_16x16x32_bf16 v[24:27], v[160:163], v[202:205], v[24:27]
	v_mfma_f32_16x16x32_bf16 v[12:15], v[144:147], v[210:213], v[12:15]
	v_mfma_f32_16x16x32_bf16 v[8:11], v[160:163], v[210:213], v[8:11]
	v_mfma_f32_16x16x32_bf16 v[60:63], v[148:151], v[190:193], v[60:63]
	v_mfma_f32_16x16x32_bf16 v[56:59], v[164:167], v[190:193], v[56:59]
	v_mfma_f32_16x16x32_bf16 v[44:47], v[148:151], v[198:201], v[44:47]
	v_mfma_f32_16x16x32_bf16 v[40:43], v[164:167], v[198:201], v[40:43]
	v_mfma_f32_16x16x32_bf16 v[28:31], v[148:151], v[206:209], v[28:31]
	v_mfma_f32_16x16x32_bf16 v[24:27], v[164:167], v[206:209], v[24:27]
	v_mfma_f32_16x16x32_bf16 v[12:15], v[148:151], v[214:217], v[12:15]
	v_mfma_f32_16x16x32_bf16 v[8:11], v[164:167], v[214:217], v[8:11]
	s_setprio 0
	s_setprio 1
	v_mfma_f32_16x16x32_bf16 v[52:55], v[168:171], v[186:189], v[52:55]
	v_mfma_f32_16x16x32_bf16 v[48:51], v[178:181], v[186:189], v[48:51]
	v_mfma_f32_16x16x32_bf16 v[36:39], v[168:171], v[194:197], v[36:39]
	v_mfma_f32_16x16x32_bf16 v[32:35], v[178:181], v[194:197], v[32:35]
	v_mfma_f32_16x16x32_bf16 v[20:23], v[168:171], v[202:205], v[20:23]
	v_mfma_f32_16x16x32_bf16 v[16:19], v[178:181], v[202:205], v[16:19]
	v_mfma_f32_16x16x32_bf16 v[4:7], v[168:171], v[210:213], v[4:7]
	v_mfma_f32_16x16x32_bf16 v[0:3], v[178:181], v[210:213], v[0:3]
	v_mfma_f32_16x16x32_bf16 v[52:55], v[174:177], v[190:193], v[52:55]
	v_mfma_f32_16x16x32_bf16 v[48:51], v[182:185], v[190:193], v[48:51]
	v_mfma_f32_16x16x32_bf16 v[36:39], v[174:177], v[198:201], v[36:39]
	v_mfma_f32_16x16x32_bf16 v[32:35], v[182:185], v[198:201], v[32:35]
	v_mfma_f32_16x16x32_bf16 v[20:23], v[174:177], v[206:209], v[20:23]
	v_mfma_f32_16x16x32_bf16 v[16:19], v[182:185], v[206:209], v[16:19]
	v_mfma_f32_16x16x32_bf16 v[4:7], v[174:177], v[214:217], v[4:7]
	v_mfma_f32_16x16x32_bf16 v[0:3], v[182:185], v[214:217], v[0:3]
	s_setprio 0
	s_barrier
	s_add_i32 s45, 0, 0x18000
	v_add_u32_e32 v159, s45, v153
	s_add_i32 s46, 0, 0x1c000
	ds_read_b128 v[144:147], v159
	ds_read_b128 v[148:151], v159 offset:1024
	ds_read_b128 v[160:163], v159 offset:2048
	ds_read_b128 v[164:167], v159 offset:3072
	v_add_u32_e32 v159, s46, v153
	ds_read_b128 v[168:171], v159
	ds_read_b128 v[174:177], v159 offset:1024
	ds_read_b128 v[178:181], v159 offset:2048
	ds_read_b128 v[182:185], v159 offset:3072
	s_add_u32 s22, s22, 0x80000
	s_addc_u32 s23, s23, 0
	s_mov_b32 m0, s29
	v_lshl_add_u64 v[226:227], s[22:23], 0, v[134:135]
	ds_read_b128 v[186:189], v158 offset:32768
	ds_read_b128 v[190:193], v158 offset:33792
	ds_read_b128 v[194:197], v158 offset:34816
	ds_read_b128 v[198:201], v158 offset:35840
	ds_read_b128 v[202:205], v158 offset:36864
	ds_read_b128 v[206:209], v158 offset:37888
	ds_read_b128 v[210:213], v158 offset:38912
	ds_read_b128 v[214:217], v158 offset:39936
	global_load_lds_dwordx4 v[226:227], off
	v_lshl_add_u64 v[226:227], s[22:23], 0, v[130:131]
	s_mov_b32 m0, s30
	s_nop 0
	global_load_lds_dwordx4 v[226:227], off
	s_waitcnt vmcnt(8)
	s_waitcnt lgkmcnt(0)
	s_barrier
	s_setprio 1
	s_waitcnt lgkmcnt(0)
	v_mfma_f32_16x16x32_bf16 v[124:127], v[144:147], v[186:189], v[124:127]
	v_mfma_f32_16x16x32_bf16 v[120:123], v[160:163], v[186:189], v[120:123]
	v_mfma_f32_16x16x32_bf16 v[108:111], v[144:147], v[194:197], v[108:111]
	v_mfma_f32_16x16x32_bf16 v[104:107], v[160:163], v[194:197], v[104:107]
	v_mfma_f32_16x16x32_bf16 v[92:95], v[144:147], v[202:205], v[92:95]
	v_mfma_f32_16x16x32_bf16 v[88:91], v[160:163], v[202:205], v[88:91]
	v_mfma_f32_16x16x32_bf16 v[76:79], v[144:147], v[210:213], v[76:79]
	v_mfma_f32_16x16x32_bf16 v[72:75], v[160:163], v[210:213], v[72:75]
	v_mfma_f32_16x16x32_bf16 v[124:127], v[148:151], v[190:193], v[124:127]
	v_mfma_f32_16x16x32_bf16 v[120:123], v[164:167], v[190:193], v[120:123]
	v_mfma_f32_16x16x32_bf16 v[108:111], v[148:151], v[198:201], v[108:111]
	v_mfma_f32_16x16x32_bf16 v[104:107], v[164:167], v[198:201], v[104:107]
	v_mfma_f32_16x16x32_bf16 v[92:95], v[148:151], v[206:209], v[92:95]
	v_mfma_f32_16x16x32_bf16 v[88:91], v[164:167], v[206:209], v[88:91]
	v_mfma_f32_16x16x32_bf16 v[76:79], v[148:151], v[214:217], v[76:79]
	v_mfma_f32_16x16x32_bf16 v[72:75], v[164:167], v[214:217], v[72:75]
	s_setprio 0
	s_setprio 1
	v_mfma_f32_16x16x32_bf16 v[116:119], v[168:171], v[186:189], v[116:119]
	v_mfma_f32_16x16x32_bf16 v[112:115], v[178:181], v[186:189], v[112:115]
	v_mfma_f32_16x16x32_bf16 v[100:103], v[168:171], v[194:197], v[100:103]
	v_mfma_f32_16x16x32_bf16 v[96:99], v[178:181], v[194:197], v[96:99]
	v_mfma_f32_16x16x32_bf16 v[84:87], v[168:171], v[202:205], v[84:87]
	v_mfma_f32_16x16x32_bf16 v[80:83], v[178:181], v[202:205], v[80:83]
	v_mfma_f32_16x16x32_bf16 v[68:71], v[168:171], v[210:213], v[68:71]
	v_mfma_f32_16x16x32_bf16 v[64:67], v[178:181], v[210:213], v[64:67]
	v_mfma_f32_16x16x32_bf16 v[116:119], v[174:177], v[190:193], v[116:119]
	v_mfma_f32_16x16x32_bf16 v[112:115], v[182:185], v[190:193], v[112:115]
	v_mfma_f32_16x16x32_bf16 v[100:103], v[174:177], v[198:201], v[100:103]
	v_mfma_f32_16x16x32_bf16 v[96:99], v[182:185], v[198:201], v[96:99]
	v_mfma_f32_16x16x32_bf16 v[84:87], v[174:177], v[206:209], v[84:87]
	v_mfma_f32_16x16x32_bf16 v[80:83], v[182:185], v[206:209], v[80:83]
	v_mfma_f32_16x16x32_bf16 v[68:71], v[174:177], v[214:217], v[68:71]
	v_mfma_f32_16x16x32_bf16 v[64:67], v[182:185], v[214:217], v[64:67]
	s_setprio 0
	s_barrier
; #define PG8_STAGE(bufoff, gbase, voff) do { _Pragma("unroll") for (int _i = 0; _i < 2; ++_i) \
;         __builtin_amdgcn_global_load_lds((const unsigned*)((const char*)(gbase) + (voff)[_i]), (PG8_LAS unsigned*)(lds + (bufoff) + ldsw + _i * 8192), 16, 0, 0); } while (0)
; #define PG8_LDA(dst, b, h) do { _Pragma("unroll") for (int m = 0; m < 4; ++m) _Pragma("unroll") for (int k = 0; k < 2; ++k) dst[m][k] = *(const PG8_LAS bf16x8*)(lds + PG8_SA(b, h) + aoff + m * 2048 + k * 1024); } while (0)
; #define PG8_LDB(dst, b, h) do { _Pragma("unroll") for (int n = 0; n < 2; ++n) _Pragma("unroll") for (int k = 0; k < 2; ++k) dst[n][k] = *(const PG8_LAS bf16x8*)(lds + PG8_SB(b, h) + boff + n * 2048 + k * 1024); } while (0)
; template <class Epi, class Sched, bool ALIGN_EPI = false, bool SP2 = false>
; __device__ __forceinline__ void gemm_phase(PG8_LAS unsigned char* lds, const Gemm g, const Sched& S, const Epi& E) {
;     ...
;         for (int t = 0; t < nt; t += 2) {
;             const bool last = (t == nt - 2);
;             const char* a1 = cA + (size_t)(t + 1) * kstep;
;             const char* a2 = last ? nA : cA + (size_t)(t + 2) * kstep; const char* b2 = last ? nB : cB + (size_t)(t + 2) * kstep;
;             const char* a3 = a2 + kstep; const char* b3 = b2 + kstep;
;             if (last && has_next) S.a_ready(nxt);
;             if constexpr (SP2) {
;             PG8_LDB(B0, 0, 0); PG8_LDB(B1, 0, 1); PG8_SCHED; PG8_LDA(At, 0, 0); PG8_STAGE(PG8_SA(1, 1), a1 + hstep, voffA);
;             PG8_WAIT_V(8); PG8_WAIT_L(0); PG8_BAR; PG8_MMA(0, 0, At, B0); PG8_MMA(0, 1, At, B1); PG8_BAR; PG8_SCHED;
;             PG8_LDA(At, 0, 1); PG8_STAGE(PG8_SB(0, 0), b2, voffB); PG8_STAGE(PG8_SB(0, 1), b2 + hstep, voffB); PG8_STAGE(PG8_SA(0, 0), a2, voffA);
;             PG8_WAIT_V(8); PG8_WAIT_L(0); PG8_BAR; PG8_MMA(1, 0, At, B0); PG8_MMA(1, 1, At, B1); PG8_BAR; PG8_SCHED;
;             PG8_LDB(B0, 1, 0); PG8_LDB(B1, 1, 1); PG8_SCHED; PG8_LDA(At, 1, 0); PG8_STAGE(PG8_SA(0, 1), a2 + hstep, voffA);
;             PG8_WAIT_V(8); PG8_WAIT_L(0); PG8_BAR; PG8_MMA(0, 0, At, B0); PG8_MMA(0, 1, At, B1); PG8_BAR; PG8_SCHED;
;             PG8_LDA(At, 1, 1); PG8_STAGE(PG8_SB(1, 0), b3, voffB); PG8_STAGE(PG8_SB(1, 1), b3 + hstep, voffB); PG8_STAGE(PG8_SA(1, 0), a3, voffA);
;             PG8_WAIT_V(8); PG8_WAIT_L(0); PG8_BAR; PG8_MMA(1, 0, At, B0); PG8_MMA(1, 1, At, B1); PG8_BAR; PG8_SCHED;
	s_add_i32 s22, s45, s26
	v_lshl_add_u64 v[218:219], v[218:219], 0, s[2:3]
	s_mov_b32 m0, s22
	ds_read_b128 v[186:189], v158 offset:49152
	ds_read_b128 v[190:193], v158 offset:50176
	ds_read_b128 v[194:197], v158 offset:51200
	ds_read_b128 v[198:201], v158 offset:52224
	ds_read_b128 v[202:205], v158 offset:53248
	ds_read_b128 v[206:209], v158 offset:54272
	ds_read_b128 v[210:213], v158 offset:55296
	ds_read_b128 v[214:217], v158 offset:56320
	global_load_lds_dwordx4 v[218:219], off
	s_add_i32 m0, s22, 0x2000
	s_add_u32 s20, s20, 0x80080
	v_lshl_add_u64 v[218:219], v[220:221], 0, s[2:3]
	s_addc_u32 s21, s21, 0
	s_add_i32 s22, s46, s26
	global_load_lds_dwordx4 v[218:219], off
	v_lshl_add_u64 v[218:219], s[20:21], 0, v[132:133]
	s_mov_b32 m0, s22
	s_nop 0
	global_load_lds_dwordx4 v[218:219], off
	v_lshl_add_u64 v[218:219], s[20:21], 0, v[128:129]
	s_add_i32 m0, s22, 0x2000
	s_nop 0
	global_load_lds_dwordx4 v[218:219], off
	v_lshl_add_u64 v[218:219], v[222:223], 0, s[2:3]
	s_mov_b32 m0, s31
	s_nop 0
	global_load_lds_dwordx4 v[218:219], off
	v_lshl_add_u64 v[218:219], v[224:225], 0, s[2:3]
	s_mov_b32 m0, s33
	s_nop 0
	global_load_lds_dwordx4 v[218:219], off
	s_waitcnt vmcnt(8)
	s_waitcnt lgkmcnt(0)
	s_barrier
	s_setprio 1
	s_waitcnt lgkmcnt(0)
	v_mfma_f32_16x16x32_bf16 v[60:63], v[144:147], v[186:189], v[60:63]
	v_mfma_f32_16x16x32_bf16 v[56:59], v[160:163], v[186:189], v[56:59]
	v_mfma_f32_16x16x32_bf16 v[44:47], v[144:147], v[194:197], v[44:47]
	v_mfma_f32_16x16x32_bf16 v[40:43], v[160:163], v[194:197], v[40:43]
	v_mfma_f32_16x16x32_bf16 v[28:31], v[144:147], v[202:205], v[28:31]
	v_mfma_f32_16x16x32_bf16 v[24:27], v[160:163], v[202:205], v[24:27]
	v_mfma_f32_16x16x32_bf16 v[12:15], v[144:147], v[210:213], v[12:15]
	v_mfma_f32_16x16x32_bf16 v[8:11], v[160:163], v[210:213], v[8:11]
	v_mfma_f32_16x16x32_bf16 v[60:63], v[148:151], v[190:193], v[60:63]
	v_mfma_f32_16x16x32_bf16 v[56:59], v[164:167], v[190:193], v[56:59]
	v_mfma_f32_16x16x32_bf16 v[44:47], v[148:151], v[198:201], v[44:47]
	v_mfma_f32_16x16x32_bf16 v[40:43], v[164:167], v[198:201], v[40:43]
	v_mfma_f32_16x16x32_bf16 v[28:31], v[148:151], v[206:209], v[28:31]
	v_mfma_f32_16x16x32_bf16 v[24:27], v[164:167], v[206:209], v[24:27]
	v_mfma_f32_16x16x32_bf16 v[12:15], v[148:151], v[214:217], v[12:15]
	v_mfma_f32_16x16x32_bf16 v[8:11], v[164:167], v[214:217], v[8:11]
	s_setprio 0
	s_setprio 1
	v_mfma_f32_16x16x32_bf16 v[52:55], v[168:171], v[186:189], v[52:55]
	v_mfma_f32_16x16x32_bf16 v[48:51], v[178:181], v[186:189], v[48:51]
	v_mfma_f32_16x16x32_bf16 v[36:39], v[168:171], v[194:197], v[36:39]
	v_mfma_f32_16x16x32_bf16 v[32:35], v[178:181], v[194:197], v[32:35]
	v_mfma_f32_16x16x32_bf16 v[20:23], v[168:171], v[202:205], v[20:23]
	v_mfma_f32_16x16x32_bf16 v[16:19], v[178:181], v[202:205], v[16:19]
	v_mfma_f32_16x16x32_bf16 v[4:7], v[168:171], v[210:213], v[4:7]
	v_mfma_f32_16x16x32_bf16 v[0:3], v[178:181], v[210:213], v[0:3]
	v_mfma_f32_16x16x32_bf16 v[52:55], v[174:177], v[190:193], v[52:55]
	v_mfma_f32_16x16x32_bf16 v[48:51], v[182:185], v[190:193], v[48:51]
	v_mfma_f32_16x16x32_bf16 v[36:39], v[174:177], v[198:201], v[36:39]
	v_mfma_f32_16x16x32_bf16 v[32:35], v[182:185], v[198:201], v[32:35]
	v_mfma_f32_16x16x32_bf16 v[20:23], v[174:177], v[206:209], v[20:23]
	v_mfma_f32_16x16x32_bf16 v[16:19], v[182:185], v[206:209], v[16:19]
	v_mfma_f32_16x16x32_bf16 v[4:7], v[174:177], v[214:217], v[4:7]
	v_mfma_f32_16x16x32_bf16 v[0:3], v[182:185], v[214:217], v[0:3]
	s_setprio 0
	s_barrier
	s_add_i32 s44, s44, 2
	s_add_u32 s18, s18, 0x100
	s_addc_u32 s19, s19, 0
	s_add_u32 s42, s42, 0x100
	s_addc_u32 s43, s43, 0
	s_cmp_gt_u32 s44, 29
	s_cbranch_scc0 .LBB0_1712
	s_nop 0
	v_readfirstlane_b32 s9, v172
	s_nop 3
	s_lshr_b32 s9, s9, 6
	s_cmp_ge_u32 s9, 4
	s_cbranch_scc0 .Lprio_k6
	s_setprio 1

; #define PG8_STAGE(bufoff, gbase, voff) do { _Pragma("unroll") for (int _i = 0; _i < 2; ++_i) \
;         __builtin_amdgcn_global_load_lds((const unsigned*)((const char*)(gbase) + (voff)[_i]), (PG8_LAS unsigned*)(lds + (bufoff) + ldsw + _i * 8192), 16, 0, 0); } while (0)
; #define PG8_LDA(dst, b, h) do { _Pragma("unroll") for (int m = 0; m < 4; ++m) _Pragma("unroll") for (int k = 0; k < 2; ++k) dst[m][k] = *(const PG8_LAS bf16x8*)(lds + PG8_SA(b, h) + aoff + m * 2048 + k * 1024); } while (0)
; #define PG8_LDB(dst, b, h) do { _Pragma("unroll") for (int n = 0; n < 2; ++n) _Pragma("unroll") for (int k = 0; k < 2; ++k) dst[n][k] = *(const PG8_LAS bf16x8*)(lds + PG8_SB(b, h) + boff + n * 2048 + k * 1024); } while (0)
; #define PG8_MMA(ai, bj, At, Bt) do { __builtin_amdgcn_s_setprio(1); _Pragma("unroll") for (int m = 0; m < 4; ++m) _Pragma("unroll") for (int n = 0; n < 2; ++n) _Pragma("unroll") for (int k = 0; k < 2; ++k) \
;         acc[ai][bj][m][n] = __builtin_amdgcn_mfma_f32_16x16x32_bf16(Bt[n][k], At[m][k], acc[ai][bj][m][n], 0, 0, 0); __builtin_amdgcn_s_setprio(0); } while (0)
; #define PG8_WAIT_V(n) asm volatile("s_waitcnt vmcnt(" #n ")" ::: "memory")
; #define PG8_WAIT_L(n) asm volatile("s_waitcnt lgkmcnt(" #n ")" ::: "memory")
; template <class Epi, class Sched, bool ALIGN_EPI = false, bool SP2 = false>
; __device__ __forceinline__ void gemm_phase(PG8_LAS unsigned char* lds, const Gemm g, const Sched& S, const Epi& E) {
;     ...
;             const bool last = (t == nt - 2);
;             const char* a1 = cA + (size_t)(t + 1) * kstep;
;             const char* a2 = last ? nA : cA + (size_t)(t + 2) * kstep; const char* b2 = last ? nB : cB + (size_t)(t + 2) * kstep;
;             const char* a3 = a2 + kstep; const char* b3 = b2 + kstep;
;             if (last && has_next) S.a_ready(nxt);
;             if constexpr (SP2) {
;             PG8_LDB(B0, 0, 0); PG8_LDB(B1, 0, 1); PG8_SCHED; PG8_LDA(At, 0, 0); PG8_STAGE(PG8_SA(1, 1), a1 + hstep, voffA);
;             PG8_WAIT_V(8); PG8_WAIT_L(0); PG8_BAR; PG8_MMA(0, 0, At, B0); PG8_MMA(0, 1, At, B1); PG8_BAR; PG8_SCHED;
;             PG8_LDA(At, 0, 1); PG8_STAGE(PG8_SB(0, 0), b2, voffB); PG8_STAGE(PG8_SB(0, 1), b2 + hstep, voffB); PG8_STAGE(PG8_SA(0, 0), a2, voffA);
;             PG8_WAIT_V(8); PG8_WAIT_L(0); PG8_BAR; PG8_MMA(1, 0, At, B0); PG8_MMA(1, 1, At, B1); PG8_BAR; PG8_SCHED;
.LBB0_1956:
	ds_read_b128 v[140:143], v149
	ds_read_b128 v[152:155], v149 offset:1024
	ds_read_b128 v[156:159], v149 offset:2048
	ds_read_b128 v[160:163], v149 offset:3072
	ds_read_b128 v[164:167], v150
	ds_read_b128 v[168:171], v150 offset:1024
	ds_read_b128 v[172:175], v150 offset:2048
	ds_read_b128 v[176:179], v150 offset:3072
	s_add_u32 s22, s20, 0x100
	s_addc_u32 s23, s21, 0
	s_cmpk_eq_i32 s47, 0x54
	s_cselect_b32 s27, s5, s23
	s_cselect_b32 s26, s4, s22
	s_cselect_b32 s25, s19, s46
	s_cselect_b32 s24, s18, s45
	v_lshl_add_u64 v[144:145], s[20:21], 0, v[132:133]
	s_add_i32 m0, s31, 0xc000
	ds_read_b128 v[180:183], v151
	ds_read_b128 v[184:187], v151 offset:1024
	ds_read_b128 v[188:191], v151 offset:2048
	ds_read_b128 v[192:195], v151 offset:3072
	ds_read_b128 v[196:199], v151 offset:4096
	ds_read_b128 v[200:203], v151 offset:5120
	ds_read_b128 v[204:207], v151 offset:6144
	ds_read_b128 v[208:211], v151 offset:7168
	global_load_lds_dwordx4 v[144:145], off
	v_lshl_add_u64 v[144:145], s[20:21], 0, v[134:135]
	s_add_i32 m0, s31, 0xe000
	s_nop 0
	global_load_lds_dwordx4 v[144:145], off
	s_waitcnt vmcnt(8)
	s_waitcnt lgkmcnt(0)
	s_barrier
	s_setprio 1
	s_waitcnt lgkmcnt(0)
	v_mfma_f32_16x16x32_bf16 v[124:127], v[140:143], v[180:183], v[124:127]
	v_mfma_f32_16x16x32_bf16 v[120:123], v[156:159], v[180:183], v[120:123]
	v_mfma_f32_16x16x32_bf16 v[108:111], v[140:143], v[188:191], v[108:111]
	v_mfma_f32_16x16x32_bf16 v[104:107], v[156:159], v[188:191], v[104:107]
	v_mfma_f32_16x16x32_bf16 v[92:95], v[140:143], v[196:199], v[92:95]
	v_mfma_f32_16x16x32_bf16 v[88:91], v[156:159], v[196:199], v[88:91]
	v_mfma_f32_16x16x32_bf16 v[76:79], v[140:143], v[204:207], v[76:79]
	v_mfma_f32_16x16x32_bf16 v[72:75], v[156:159], v[204:207], v[72:75]
	v_mfma_f32_16x16x32_bf16 v[124:127], v[152:155], v[184:187], v[124:127]
	v_mfma_f32_16x16x32_bf16 v[120:123], v[160:163], v[184:187], v[120:123]
	v_mfma_f32_16x16x32_bf16 v[108:111], v[152:155], v[192:195], v[108:111]
	v_mfma_f32_16x16x32_bf16 v[104:107], v[160:163], v[192:195], v[104:107]
	v_mfma_f32_16x16x32_bf16 v[92:95], v[152:155], v[200:203], v[92:95]
	v_mfma_f32_16x16x32_bf16 v[88:91], v[160:163], v[200:203], v[88:91]
	v_mfma_f32_16x16x32_bf16 v[76:79], v[152:155], v[208:211], v[76:79]
	v_mfma_f32_16x16x32_bf16 v[72:75], v[160:163], v[208:211], v[72:75]
	s_setprio 0
	s_setprio 1
	v_mfma_f32_16x16x32_bf16 v[116:119], v[164:167], v[180:183], v[116:119]
	v_mfma_f32_16x16x32_bf16 v[112:115], v[172:175], v[180:183], v[112:115]
	v_mfma_f32_16x16x32_bf16 v[100:103], v[164:167], v[188:191], v[100:103]
	v_mfma_f32_16x16x32_bf16 v[96:99], v[172:175], v[188:191], v[96:99]
	v_mfma_f32_16x16x32_bf16 v[84:87], v[164:167], v[196:199], v[84:87]
	v_mfma_f32_16x16x32_bf16 v[80:83], v[172:175], v[196:199], v[80:83]
	v_mfma_f32_16x16x32_bf16 v[68:71], v[164:167], v[204:207], v[68:71]
	v_mfma_f32_16x16x32_bf16 v[64:67], v[172:175], v[204:207], v[64:67]
	v_mfma_f32_16x16x32_bf16 v[116:119], v[168:171], v[184:187], v[116:119]
	v_mfma_f32_16x16x32_bf16 v[112:115], v[176:179], v[184:187], v[112:115]
	v_mfma_f32_16x16x32_bf16 v[100:103], v[168:171], v[192:195], v[100:103]
	v_mfma_f32_16x16x32_bf16 v[96:99], v[176:179], v[192:195], v[96:99]
	v_mfma_f32_16x16x32_bf16 v[84:87], v[168:171], v[200:203], v[84:87]
	v_mfma_f32_16x16x32_bf16 v[80:83], v[176:179], v[200:203], v[80:83]
	v_mfma_f32_16x16x32_bf16 v[68:71], v[168:171], v[208:211], v[68:71]
	v_mfma_f32_16x16x32_bf16 v[64:67], v[176:179], v[208:211], v[64:67]
	s_setprio 0
	s_barrier
	s_add_i32 s20, s39, s30
	v_lshl_add_u64 v[144:145], s[24:25], 0, v[128:129]
	s_mov_b32 m0, s20
	ds_read_b128 v[180:183], v151 offset:16384
	ds_read_b128 v[184:187], v151 offset:17408
	ds_read_b128 v[188:191], v151 offset:18432
	ds_read_b128 v[192:195], v151 offset:19456
	ds_read_b128 v[196:199], v151 offset:20480
	ds_read_b128 v[200:203], v151 offset:21504
	ds_read_b128 v[204:207], v151 offset:22528
	ds_read_b128 v[208:211], v151 offset:23552
	global_load_lds_dwordx4 v[144:145], off
	s_add_i32 m0, s20, 0x2000
	s_add_u32 s20, s24, 0x160000
	v_lshl_add_u64 v[212:213], s[24:25], 0, v[130:131]
	s_addc_u32 s21, s25, 0
	s_add_i32 s48, s40, s30
	global_load_lds_dwordx4 v[212:213], off
	v_lshl_add_u64 v[214:215], s[20:21], 0, v[128:129]
	s_mov_b32 m0, s48
	v_lshl_add_u64 v[216:217], s[26:27], 0, v[130:131]
	global_load_lds_dwordx4 v[214:215], off
	v_lshl_add_u64 v[214:215], s[20:21], 0, v[130:131]
	s_add_i32 m0, s48, 0x2000
	s_nop 0
	global_load_lds_dwordx4 v[214:215], off
	v_lshl_add_u64 v[214:215], s[26:27], 0, v[128:129]
	s_mov_b32 m0, s31
	s_nop 0
	global_load_lds_dwordx4 v[214:215], off
	s_mov_b32 m0, s33
	s_nop 0
	global_load_lds_dwordx4 v[216:217], off
	s_waitcnt vmcnt(8)
	s_waitcnt lgkmcnt(0)
	s_barrier
; #define PG8_STAGE(bufoff, gbase, voff) do { _Pragma("unroll") for (int _i = 0; _i < 2; ++_i) \
;         __builtin_amdgcn_global_load_lds((const unsigned*)((const char*)(gbase) + (voff)[_i]), (PG8_LAS unsigned*)(lds + (bufoff) + ldsw + _i * 8192), 16, 0, 0); } while (0)
; #define PG8_LDA(dst, b, h) do { _Pragma("unroll") for (int m = 0; m < 4; ++m) _Pragma("unroll") for (int k = 0; k < 2; ++k) dst[m][k] = *(const PG8_LAS bf16x8*)(lds + PG8_SA(b, h) + aoff + m * 2048 + k * 1024); } while (0)
; #define PG8_LDB(dst, b, h) do { _Pragma("unroll") for (int n = 0; n < 2; ++n) _Pragma("unroll") for (int k = 0; k < 2; ++k) dst[n][k] = *(const PG8_LAS bf16x8*)(lds + PG8_SB(b, h) + boff + n * 2048 + k * 1024); } while (0)
; #define PG8_MMA(ai, bj, At, Bt) do { __builtin_amdgcn_s_setprio(1); _Pragma("unroll") for (int m = 0; m < 4; ++m) _Pragma("unroll") for (int n = 0; n < 2; ++n) _Pragma("unroll") for (int k = 0; k < 2; ++k) \
;         acc[ai][bj][m][n] = __builtin_amdgcn_mfma_f32_16x16x32_bf16(Bt[n][k], At[m][k], acc[ai][bj][m][n], 0, 0, 0); __builtin_amdgcn_s_setprio(0); } while (0)
; #define PG8_WAIT_V(n) asm volatile("s_waitcnt vmcnt(" #n ")" ::: "memory")
; #define PG8_WAIT_L(n) asm volatile("s_waitcnt lgkmcnt(" #n ")" ::: "memory")
; #define PG8_BAR __builtin_amdgcn_s_barrier()
; #define PG8_SCHED __builtin_amdgcn_sched_barrier(0)
; template <class Epi, class Sched, bool ALIGN_EPI = false, bool SP2 = false>
; __device__ __forceinline__ void gemm_phase(PG8_LAS unsigned char* lds, const Gemm g, const Sched& S, const Epi& E) {
;     ...
;             PG8_WAIT_V(8); PG8_WAIT_L(0); PG8_BAR; PG8_MMA(1, 0, At, B0); PG8_MMA(1, 1, At, B1); PG8_BAR; PG8_SCHED;
;             PG8_LDB(B0, 1, 0); PG8_LDB(B1, 1, 1); PG8_SCHED; PG8_LDA(At, 1, 0); PG8_STAGE(PG8_SA(0, 1), a2 + hstep, voffA);
;             PG8_WAIT_V(8); PG8_WAIT_L(0); PG8_BAR; PG8_MMA(0, 0, At, B0); PG8_MMA(0, 1, At, B1); PG8_BAR; PG8_SCHED;
	s_setprio 1
	s_waitcnt lgkmcnt(0)
	v_mfma_f32_16x16x32_bf16 v[60:63], v[140:143], v[180:183], v[60:63]
	v_mfma_f32_16x16x32_bf16 v[56:59], v[156:159], v[180:183], v[56:59]
	v_mfma_f32_16x16x32_bf16 v[44:47], v[140:143], v[188:191], v[44:47]
	v_mfma_f32_16x16x32_bf16 v[40:43], v[156:159], v[188:191], v[40:43]
	v_mfma_f32_16x16x32_bf16 v[28:31], v[140:143], v[196:199], v[28:31]
	v_mfma_f32_16x16x32_bf16 v[24:27], v[156:159], v[196:199], v[24:27]
	v_mfma_f32_16x16x32_bf16 v[12:15], v[140:143], v[204:207], v[12:15]
	v_mfma_f32_16x16x32_bf16 v[8:11], v[156:159], v[204:207], v[8:11]
	v_mfma_f32_16x16x32_bf16 v[60:63], v[152:155], v[184:187], v[60:63]
	v_mfma_f32_16x16x32_bf16 v[56:59], v[160:163], v[184:187], v[56:59]
	v_mfma_f32_16x16x32_bf16 v[44:47], v[152:155], v[192:195], v[44:47]
	v_mfma_f32_16x16x32_bf16 v[40:43], v[160:163], v[192:195], v[40:43]
	v_mfma_f32_16x16x32_bf16 v[28:31], v[152:155], v[200:203], v[28:31]
	v_mfma_f32_16x16x32_bf16 v[24:27], v[160:163], v[200:203], v[24:27]
	v_mfma_f32_16x16x32_bf16 v[12:15], v[152:155], v[208:211], v[12:15]
	v_mfma_f32_16x16x32_bf16 v[8:11], v[160:163], v[208:211], v[8:11]
	s_setprio 0
	s_setprio 1
	v_mfma_f32_16x16x32_bf16 v[52:55], v[164:167], v[180:183], v[52:55]
	v_mfma_f32_16x16x32_bf16 v[48:51], v[172:175], v[180:183], v[48:51]
	v_mfma_f32_16x16x32_bf16 v[36:39], v[164:167], v[188:191], v[36:39]
	v_mfma_f32_16x16x32_bf16 v[32:35], v[172:175], v[188:191], v[32:35]
	v_mfma_f32_16x16x32_bf16 v[20:23], v[164:167], v[196:199], v[20:23]
	v_mfma_f32_16x16x32_bf16 v[16:19], v[172:175], v[196:199], v[16:19]
	v_mfma_f32_16x16x32_bf16 v[4:7], v[164:167], v[204:207], v[4:7]
	v_mfma_f32_16x16x32_bf16 v[0:3], v[172:175], v[204:207], v[0:3]
	v_mfma_f32_16x16x32_bf16 v[52:55], v[168:171], v[184:187], v[52:55]
	v_mfma_f32_16x16x32_bf16 v[48:51], v[176:179], v[184:187], v[48:51]
	v_mfma_f32_16x16x32_bf16 v[36:39], v[168:171], v[192:195], v[36:39]
	v_mfma_f32_16x16x32_bf16 v[32:35], v[176:179], v[192:195], v[32:35]
	v_mfma_f32_16x16x32_bf16 v[20:23], v[168:171], v[200:203], v[20:23]
	v_mfma_f32_16x16x32_bf16 v[16:19], v[176:179], v[200:203], v[16:19]
	v_mfma_f32_16x16x32_bf16 v[4:7], v[168:171], v[208:211], v[4:7]
	v_mfma_f32_16x16x32_bf16 v[0:3], v[176:179], v[208:211], v[0:3]
	s_setprio 0
	s_barrier
	s_add_i32 s48, 0, 0x18000
	s_add_i32 s49, 0, 0x1c000
	v_add_u32_e32 v160, s48, v147
	v_add_u32_e32 v176, s49, v147
	ds_read_b128 v[140:143], v160
	ds_read_b128 v[152:155], v160 offset:1024
	ds_read_b128 v[156:159], v160 offset:2048
	ds_read_b128 v[160:163], v160 offset:3072
	ds_read_b128 v[164:167], v176
	ds_read_b128 v[168:171], v176 offset:1024
	ds_read_b128 v[172:175], v176 offset:2048
	ds_read_b128 v[176:179], v176 offset:3072
	s_add_u32 s20, s26, 0x160000
	s_addc_u32 s21, s27, 0
	s_mov_b32 m0, s34
	v_lshl_add_u64 v[218:219], s[20:21], 0, v[128:129]
	ds_read_b128 v[180:183], v151 offset:32768
	ds_read_b128 v[184:187], v151 offset:33792
	ds_read_b128 v[188:191], v151 offset:34816
	ds_read_b128 v[192:195], v151 offset:35840
	ds_read_b128 v[196:199], v151 offset:36864
	ds_read_b128 v[200:203], v151 offset:37888
	ds_read_b128 v[204:207], v151 offset:38912
	ds_read_b128 v[208:211], v151 offset:39936
	global_load_lds_dwordx4 v[218:219], off
	v_lshl_add_u64 v[218:219], s[20:21], 0, v[130:131]
	s_mov_b32 m0, s35
	s_nop 0
	global_load_lds_dwordx4 v[218:219], off
	s_waitcnt vmcnt(8)
	s_waitcnt lgkmcnt(0)
	s_barrier
	s_setprio 1
	s_waitcnt lgkmcnt(0)
	v_mfma_f32_16x16x32_bf16 v[124:127], v[140:143], v[180:183], v[124:127]
	v_mfma_f32_16x16x32_bf16 v[120:123], v[156:159], v[180:183], v[120:123]
	v_mfma_f32_16x16x32_bf16 v[108:111], v[140:143], v[188:191], v[108:111]
	v_mfma_f32_16x16x32_bf16 v[104:107], v[156:159], v[188:191], v[104:107]
	v_mfma_f32_16x16x32_bf16 v[92:95], v[140:143], v[196:199], v[92:95]
	v_mfma_f32_16x16x32_bf16 v[88:91], v[156:159], v[196:199], v[88:91]
	v_mfma_f32_16x16x32_bf16 v[76:79], v[140:143], v[204:207], v[76:79]
	v_mfma_f32_16x16x32_bf16 v[72:75], v[156:159], v[204:207], v[72:75]
	v_mfma_f32_16x16x32_bf16 v[124:127], v[152:155], v[184:187], v[124:127]
	v_mfma_f32_16x16x32_bf16 v[120:123], v[160:163], v[184:187], v[120:123]
	v_mfma_f32_16x16x32_bf16 v[108:111], v[152:155], v[192:195], v[108:111]
	v_mfma_f32_16x16x32_bf16 v[104:107], v[160:163], v[192:195], v[104:107]
	v_mfma_f32_16x16x32_bf16 v[92:95], v[152:155], v[200:203], v[92:95]
	v_mfma_f32_16x16x32_bf16 v[88:91], v[160:163], v[200:203], v[88:91]
	v_mfma_f32_16x16x32_bf16 v[76:79], v[152:155], v[208:211], v[76:79]
	v_mfma_f32_16x16x32_bf16 v[72:75], v[160:163], v[208:211], v[72:75]
	s_setprio 0
	s_setprio 1
	v_mfma_f32_16x16x32_bf16 v[116:119], v[164:167], v[180:183], v[116:119]
	v_mfma_f32_16x16x32_bf16 v[112:115], v[172:175], v[180:183], v[112:115]
	v_mfma_f32_16x16x32_bf16 v[100:103], v[164:167], v[188:191], v[100:103]
	v_mfma_f32_16x16x32_bf16 v[96:99], v[172:175], v[188:191], v[96:99]
	v_mfma_f32_16x16x32_bf16 v[84:87], v[164:167], v[196:199], v[84:87]
	v_mfma_f32_16x16x32_bf16 v[80:83], v[172:175], v[196:199], v[80:83]
	v_mfma_f32_16x16x32_bf16 v[68:71], v[164:167], v[204:207], v[68:71]
	v_mfma_f32_16x16x32_bf16 v[64:67], v[172:175], v[204:207], v[64:67]
	v_mfma_f32_16x16x32_bf16 v[116:119], v[168:171], v[184:187], v[116:119]
	v_mfma_f32_16x16x32_bf16 v[112:115], v[176:179], v[184:187], v[112:115]
	v_mfma_f32_16x16x32_bf16 v[100:103], v[168:171], v[192:195], v[100:103]
	v_mfma_f32_16x16x32_bf16 v[96:99], v[176:179], v[192:195], v[96:99]
	v_mfma_f32_16x16x32_bf16 v[84:87], v[168:171], v[200:203], v[84:87]
	v_mfma_f32_16x16x32_bf16 v[80:83], v[176:179], v[200:203], v[80:83]
	v_mfma_f32_16x16x32_bf16 v[68:71], v[168:171], v[208:211], v[68:71]
	v_mfma_f32_16x16x32_bf16 v[64:67], v[176:179], v[208:211], v[64:67]
	s_setprio 0
	s_barrier
; #define PG8_STAGE(bufoff, gbase, voff) do { _Pragma("unroll") for (int _i = 0; _i < 2; ++_i) \
;         __builtin_amdgcn_global_load_lds((const unsigned*)((const char*)(gbase) + (voff)[_i]), (PG8_LAS unsigned*)(lds + (bufoff) + ldsw + _i * 8192), 16, 0, 0); } while (0)
; #define PG8_LDA(dst, b, h) do { _Pragma("unroll") for (int m = 0; m < 4; ++m) _Pragma("unroll") for (int k = 0; k < 2; ++k) dst[m][k] = *(const PG8_LAS bf16x8*)(lds + PG8_SA(b, h) + aoff + m * 2048 + k * 1024); } while (0)
; #define PG8_MMA(ai, bj, At, Bt) do { __builtin_amdgcn_s_setprio(1); _Pragma("unroll") for (int m = 0; m < 4; ++m) _Pragma("unroll") for (int n = 0; n < 2; ++n) _Pragma("unroll") for (int k = 0; k < 2; ++k) \
;         acc[ai][bj][m][n] = __builtin_amdgcn_mfma_f32_16x16x32_bf16(Bt[n][k], At[m][k], acc[ai][bj][m][n], 0, 0, 0); __builtin_amdgcn_s_setprio(0); } while (0)
; #define PG8_WAIT_V(n) asm volatile("s_waitcnt vmcnt(" #n ")" ::: "memory")
; #define PG8_WAIT_L(n) asm volatile("s_waitcnt lgkmcnt(" #n ")" ::: "memory")
; #define PG8_BAR __builtin_amdgcn_s_barrier()
; #define PG8_SCHED __builtin_amdgcn_sched_barrier(0)
; template <class Epi, class Sched, bool ALIGN_EPI = false, bool SP2 = false>
; __device__ __forceinline__ void gemm_phase(PG8_LAS unsigned char* lds, const Gemm g, const Sched& S, const Epi& E) {
;     ...
;         for (int t = 0; t < nt; t += 2) {
;     ...
;             PG8_LDA(At, 1, 1); PG8_STAGE(PG8_SB(1, 0), b3, voffB); PG8_STAGE(PG8_SB(1, 1), b3 + hstep, voffB); PG8_STAGE(PG8_SA(1, 0), a3, voffA);
;             PG8_WAIT_V(8); PG8_WAIT_L(0); PG8_BAR; PG8_MMA(1, 0, At, B0); PG8_MMA(1, 1, At, B1); PG8_BAR; PG8_SCHED;
	s_add_i32 s20, s48, s30
	v_lshl_add_u64 v[144:145], v[144:145], 0, s[6:7]
	s_mov_b32 m0, s20
	ds_read_b128 v[180:183], v151 offset:49152
	ds_read_b128 v[184:187], v151 offset:50176
	ds_read_b128 v[188:191], v151 offset:51200
	ds_read_b128 v[192:195], v151 offset:52224
	ds_read_b128 v[196:199], v151 offset:53248
	ds_read_b128 v[200:203], v151 offset:54272
	ds_read_b128 v[204:207], v151 offset:55296
	ds_read_b128 v[208:211], v151 offset:56320
	global_load_lds_dwordx4 v[144:145], off
	s_add_i32 m0, s20, 0x2000
	s_add_u32 s20, s24, 0x160080
	v_lshl_add_u64 v[144:145], v[212:213], 0, s[6:7]
	s_addc_u32 s21, s25, 0
	s_add_i32 s24, s49, s30
	global_load_lds_dwordx4 v[144:145], off
	v_lshl_add_u64 v[144:145], s[20:21], 0, v[128:129]
	s_mov_b32 m0, s24
	s_nop 0
	global_load_lds_dwordx4 v[144:145], off
	v_lshl_add_u64 v[144:145], s[20:21], 0, v[130:131]
	s_add_i32 m0, s24, 0x2000
	s_nop 0
	global_load_lds_dwordx4 v[144:145], off
	v_lshl_add_u64 v[144:145], v[214:215], 0, s[6:7]
	s_mov_b32 m0, s37
	s_nop 0
	global_load_lds_dwordx4 v[144:145], off
	v_lshl_add_u64 v[144:145], v[216:217], 0, s[6:7]
	s_mov_b32 m0, s38
	s_nop 0
	global_load_lds_dwordx4 v[144:145], off
	s_waitcnt vmcnt(8)
	s_waitcnt lgkmcnt(0)
	s_barrier
	s_setprio 1
	s_waitcnt lgkmcnt(0)
	v_mfma_f32_16x16x32_bf16 v[60:63], v[140:143], v[180:183], v[60:63]
	v_mfma_f32_16x16x32_bf16 v[56:59], v[156:159], v[180:183], v[56:59]
	v_mfma_f32_16x16x32_bf16 v[44:47], v[140:143], v[188:191], v[44:47]
	v_mfma_f32_16x16x32_bf16 v[40:43], v[156:159], v[188:191], v[40:43]
	v_mfma_f32_16x16x32_bf16 v[28:31], v[140:143], v[196:199], v[28:31]
	v_mfma_f32_16x16x32_bf16 v[24:27], v[156:159], v[196:199], v[24:27]
	v_mfma_f32_16x16x32_bf16 v[12:15], v[140:143], v[204:207], v[12:15]
	v_mfma_f32_16x16x32_bf16 v[8:11], v[156:159], v[204:207], v[8:11]
	v_mfma_f32_16x16x32_bf16 v[60:63], v[152:155], v[184:187], v[60:63]
	v_mfma_f32_16x16x32_bf16 v[56:59], v[160:163], v[184:187], v[56:59]
	v_mfma_f32_16x16x32_bf16 v[44:47], v[152:155], v[192:195], v[44:47]
	v_mfma_f32_16x16x32_bf16 v[40:43], v[160:163], v[192:195], v[40:43]
	v_mfma_f32_16x16x32_bf16 v[28:31], v[152:155], v[200:203], v[28:31]
	v_mfma_f32_16x16x32_bf16 v[24:27], v[160:163], v[200:203], v[24:27]
	v_mfma_f32_16x16x32_bf16 v[12:15], v[152:155], v[208:211], v[12:15]
	v_mfma_f32_16x16x32_bf16 v[8:11], v[160:163], v[208:211], v[8:11]
	s_setprio 0
	s_setprio 1
	v_mfma_f32_16x16x32_bf16 v[52:55], v[164:167], v[180:183], v[52:55]
	v_mfma_f32_16x16x32_bf16 v[48:51], v[172:175], v[180:183], v[48:51]
	v_mfma_f32_16x16x32_bf16 v[36:39], v[164:167], v[188:191], v[36:39]
	v_mfma_f32_16x16x32_bf16 v[32:35], v[172:175], v[188:191], v[32:35]
	v_mfma_f32_16x16x32_bf16 v[20:23], v[164:167], v[196:199], v[20:23]
	v_mfma_f32_16x16x32_bf16 v[16:19], v[172:175], v[196:199], v[16:19]
	v_mfma_f32_16x16x32_bf16 v[4:7], v[164:167], v[204:207], v[4:7]
	v_mfma_f32_16x16x32_bf16 v[0:3], v[172:175], v[204:207], v[0:3]
	v_mfma_f32_16x16x32_bf16 v[52:55], v[168:171], v[184:187], v[52:55]
	v_mfma_f32_16x16x32_bf16 v[48:51], v[176:179], v[184:187], v[48:51]
	v_mfma_f32_16x16x32_bf16 v[36:39], v[168:171], v[192:195], v[36:39]
	v_mfma_f32_16x16x32_bf16 v[32:35], v[176:179], v[192:195], v[32:35]
	v_mfma_f32_16x16x32_bf16 v[20:23], v[168:171], v[200:203], v[20:23]
	v_mfma_f32_16x16x32_bf16 v[16:19], v[176:179], v[200:203], v[16:19]
	v_mfma_f32_16x16x32_bf16 v[4:7], v[168:171], v[208:211], v[4:7]
	v_mfma_f32_16x16x32_bf16 v[0:3], v[176:179], v[208:211], v[0:3]
	s_setprio 0
	s_barrier
	s_add_i32 s47, s47, 2
	s_add_u32 s45, s45, 0x100
	s_addc_u32 s46, s46, 0
	s_cmpk_gt_u32 s47, 0x55
	s_mov_b64 s[20:21], s[22:23]
	s_cbranch_scc0 .LBB0_1956
	s_nop 0
	v_readfirstlane_b32 s20, v172
	s_nop 3
	s_lshr_b32 s20, s20, 6
	s_cmp_ge_u32 s20, 4
	s_cbranch_scc0 .Lprio_k7
	s_setprio 1
